# v32 + 8 of 16 LDS-DMA staging loads per K-loop iteration use SGPR base + 32-bit VGPR offset (no 64-bit VALU add)
# speedup vs baseline: 1.0044x; 1.0044x over previous
.LBB0_394:
	s_add_u32 s0, s24, 0xfff80080
	s_addc_u32 s1, s25, -1
	s_add_i32 s33, 0, 0x10000
	s_cmp_eq_u32 s60, 28
	s_cselect_b32 s29, s7, s1
	s_cselect_b32 s28, s19, s0
	s_cselect_b32 s27, s17, s59
	s_cselect_b32 s26, s49, s58
	s_add_i32 s55, 0, 0x14000
	v_add_u32_e32 v158, s33, v151
	v_add_u32_e32 v174, s55, v151
	ds_read_b128 v[142:145], v158
	ds_read_b128 v[146:149], v158 offset:1024
	ds_read_b128 v[154:157], v158 offset:2048
	ds_read_b128 v[158:161], v158 offset:3072
	ds_read_b128 v[162:165], v174
	ds_read_b128 v[166:169], v174 offset:1024
	ds_read_b128 v[170:173], v174 offset:2048
	ds_read_b128 v[174:177], v174 offset:3072
	s_add_i32 m0, s9, 0xc000
	ds_read_b128 v[178:181], v153
	ds_read_b128 v[182:185], v153 offset:1024
	ds_read_b128 v[186:189], v153 offset:2048
	ds_read_b128 v[190:193], v153 offset:3072
	ds_read_b128 v[194:197], v153 offset:4096
	ds_read_b128 v[198:201], v153 offset:5120
	ds_read_b128 v[208:211], v153 offset:6144
	ds_read_b128 v[212:215], v153 offset:7168
	global_load_lds_dwordx4 v138, s[24:25]
	s_add_i32 m0, s9, 0xe000
	s_nop 0
	global_load_lds_dwordx4 v140, s[24:25]
	s_waitcnt vmcnt(8)
	s_waitcnt lgkmcnt(0)
	s_setprio 1
	s_barrier
	v_mfma_f32_16x16x32_bf16 v[126:129], v[142:145], v[178:181], v[126:129]
	v_mfma_f32_16x16x32_bf16 v[122:125], v[154:157], v[178:181], v[122:125]
	v_mfma_f32_16x16x32_bf16 v[110:113], v[142:145], v[186:189], v[110:113]
	v_mfma_f32_16x16x32_bf16 v[106:109], v[154:157], v[186:189], v[106:109]
	v_mfma_f32_16x16x32_bf16 v[94:97], v[142:145], v[194:197], v[94:97]
	v_mfma_f32_16x16x32_bf16 v[90:93], v[154:157], v[194:197], v[90:93]
	v_mfma_f32_16x16x32_bf16 v[78:81], v[142:145], v[208:211], v[78:81]
	v_mfma_f32_16x16x32_bf16 v[74:77], v[154:157], v[208:211], v[74:77]
	v_mfma_f32_16x16x32_bf16 v[126:129], v[146:149], v[182:185], v[126:129]
	v_mfma_f32_16x16x32_bf16 v[122:125], v[158:161], v[182:185], v[122:125]
	v_mfma_f32_16x16x32_bf16 v[110:113], v[146:149], v[190:193], v[110:113]
	v_mfma_f32_16x16x32_bf16 v[106:109], v[158:161], v[190:193], v[106:109]
	v_mfma_f32_16x16x32_bf16 v[94:97], v[146:149], v[198:201], v[94:97]
	v_mfma_f32_16x16x32_bf16 v[90:93], v[158:161], v[198:201], v[90:93]
	v_mfma_f32_16x16x32_bf16 v[78:81], v[146:149], v[212:215], v[78:81]
	v_mfma_f32_16x16x32_bf16 v[74:77], v[158:161], v[212:215], v[74:77]
	s_setprio 0
	s_setprio 1
	v_mfma_f32_16x16x32_bf16 v[118:121], v[162:165], v[178:181], v[118:121]
	v_mfma_f32_16x16x32_bf16 v[114:117], v[170:173], v[178:181], v[114:117]
	v_mfma_f32_16x16x32_bf16 v[102:105], v[162:165], v[186:189], v[102:105]
	v_mfma_f32_16x16x32_bf16 v[98:101], v[170:173], v[186:189], v[98:101]
	v_mfma_f32_16x16x32_bf16 v[86:89], v[162:165], v[194:197], v[86:89]
	v_mfma_f32_16x16x32_bf16 v[82:85], v[170:173], v[194:197], v[82:85]
	v_mfma_f32_16x16x32_bf16 v[70:73], v[162:165], v[208:211], v[70:73]
	v_mfma_f32_16x16x32_bf16 v[66:69], v[170:173], v[208:211], v[66:69]
	v_mfma_f32_16x16x32_bf16 v[118:121], v[166:169], v[182:185], v[118:121]
	v_mfma_f32_16x16x32_bf16 v[114:117], v[174:177], v[182:185], v[114:117]
	v_mfma_f32_16x16x32_bf16 v[102:105], v[166:169], v[190:193], v[102:105]
	v_mfma_f32_16x16x32_bf16 v[98:101], v[174:177], v[190:193], v[98:101]
	v_mfma_f32_16x16x32_bf16 v[86:89], v[166:169], v[198:201], v[86:89]
	v_mfma_f32_16x16x32_bf16 v[82:85], v[174:177], v[198:201], v[82:85]
	v_mfma_f32_16x16x32_bf16 v[70:73], v[166:169], v[212:215], v[70:73]
	v_mfma_f32_16x16x32_bf16 v[66:69], v[174:177], v[212:215], v[66:69]
	s_barrier
	s_setprio 0
	s_add_i32 s0, s33, s34
	v_lshl_add_u64 v[204:205], s[26:27], 0, v[132:133]
	s_mov_b32 m0, s0
	ds_read_b128 v[178:181], v153 offset:16384
	ds_read_b128 v[182:185], v153 offset:17408
	ds_read_b128 v[186:189], v153 offset:18432
	ds_read_b128 v[190:193], v153 offset:19456
	ds_read_b128 v[194:197], v153 offset:20480
	ds_read_b128 v[198:201], v153 offset:21504
	ds_read_b128 v[208:211], v153 offset:22528
	ds_read_b128 v[212:215], v153 offset:23552
	global_load_lds_dwordx4 v[204:205], off
	s_add_i32 m0, s0, 0x2000
	s_add_u32 s0, s26, 0x80000
	v_lshl_add_u64 v[216:217], s[26:27], 0, v[136:137]
	s_addc_u32 s1, s27, 0
	s_add_i32 s33, s55, s34
	global_load_lds_dwordx4 v[216:217], off
	s_mov_b32 m0, s33
	v_lshl_add_u64 v[220:221], s[28:29], 0, v[134:135]
	global_load_lds_dwordx4 v132, s[0:1]
	s_add_i32 m0, s33, 0x2000
	s_nop 0
	global_load_lds_dwordx4 v136, s[0:1]
	v_lshl_add_u64 v[218:219], s[28:29], 0, v[130:131]
	s_mov_b32 m0, s9
	s_nop 0
	global_load_lds_dwordx4 v[218:219], off
	s_mov_b32 m0, s35
	s_nop 0
	global_load_lds_dwordx4 v[220:221], off
	s_waitcnt vmcnt(8)
	s_waitcnt lgkmcnt(0)
	s_setprio 1
	s_barrier
	v_mfma_f32_16x16x32_bf16 v[62:65], v[142:145], v[178:181], v[62:65]
	v_mfma_f32_16x16x32_bf16 v[58:61], v[154:157], v[178:181], v[58:61]
	v_mfma_f32_16x16x32_bf16 v[46:49], v[142:145], v[186:189], v[46:49]
	v_mfma_f32_16x16x32_bf16 v[42:45], v[154:157], v[186:189], v[42:45]
	v_mfma_f32_16x16x32_bf16 v[30:33], v[142:145], v[194:197], v[30:33]
	v_mfma_f32_16x16x32_bf16 v[26:29], v[154:157], v[194:197], v[26:29]
	v_mfma_f32_16x16x32_bf16 v[14:17], v[142:145], v[208:211], v[14:17]
	v_mfma_f32_16x16x32_bf16 v[10:13], v[154:157], v[208:211], v[10:13]
	v_mfma_f32_16x16x32_bf16 v[62:65], v[146:149], v[182:185], v[62:65]
	v_mfma_f32_16x16x32_bf16 v[58:61], v[158:161], v[182:185], v[58:61]
	v_mfma_f32_16x16x32_bf16 v[46:49], v[146:149], v[190:193], v[46:49]
	v_mfma_f32_16x16x32_bf16 v[42:45], v[158:161], v[190:193], v[42:45]
	v_mfma_f32_16x16x32_bf16 v[30:33], v[146:149], v[198:201], v[30:33]
	v_mfma_f32_16x16x32_bf16 v[26:29], v[158:161], v[198:201], v[26:29]
	v_mfma_f32_16x16x32_bf16 v[14:17], v[146:149], v[212:215], v[14:17]
	v_mfma_f32_16x16x32_bf16 v[10:13], v[158:161], v[212:215], v[10:13]
	s_setprio 0
	s_setprio 1
	v_mfma_f32_16x16x32_bf16 v[54:57], v[162:165], v[178:181], v[54:57]
	v_mfma_f32_16x16x32_bf16 v[50:53], v[170:173], v[178:181], v[50:53]
	v_mfma_f32_16x16x32_bf16 v[38:41], v[162:165], v[186:189], v[38:41]
	v_mfma_f32_16x16x32_bf16 v[34:37], v[170:173], v[186:189], v[34:37]
	v_mfma_f32_16x16x32_bf16 v[22:25], v[162:165], v[194:197], v[22:25]
	v_mfma_f32_16x16x32_bf16 v[18:21], v[170:173], v[194:197], v[18:21]
	v_mfma_f32_16x16x32_bf16 v[6:9], v[162:165], v[208:211], v[6:9]
	v_mfma_f32_16x16x32_bf16 v[2:5], v[170:173], v[208:211], v[2:5]
	v_mfma_f32_16x16x32_bf16 v[54:57], v[166:169], v[182:185], v[54:57]
	v_mfma_f32_16x16x32_bf16 v[50:53], v[174:177], v[182:185], v[50:53]
	v_mfma_f32_16x16x32_bf16 v[38:41], v[166:169], v[190:193], v[38:41]
	v_mfma_f32_16x16x32_bf16 v[34:37], v[174:177], v[190:193], v[34:37]
	v_mfma_f32_16x16x32_bf16 v[22:25], v[166:169], v[198:201], v[22:25]
	v_mfma_f32_16x16x32_bf16 v[18:21], v[174:177], v[198:201], v[18:21]
	v_mfma_f32_16x16x32_bf16 v[6:9], v[166:169], v[212:215], v[6:9]
	v_mfma_f32_16x16x32_bf16 v[2:5], v[174:177], v[212:215], v[2:5]
	s_barrier
	s_setprio 0
	s_add_i32 s33, 0, 0x18000
	s_add_i32 s55, 0, 0x1c000
	v_add_u32_e32 v158, s33, v151
	v_add_u32_e32 v174, s55, v151
	ds_read_b128 v[142:145], v158
	ds_read_b128 v[146:149], v158 offset:1024
	ds_read_b128 v[154:157], v158 offset:2048
	ds_read_b128 v[158:161], v158 offset:3072
	ds_read_b128 v[162:165], v174
	ds_read_b128 v[166:169], v174 offset:1024
	ds_read_b128 v[170:173], v174 offset:2048
	ds_read_b128 v[174:177], v174 offset:3072
	s_add_u32 s0, s28, 0x80000
	s_addc_u32 s1, s29, 0
	s_mov_b32 m0, s36
	ds_read_b128 v[178:181], v153 offset:32768
	ds_read_b128 v[182:185], v153 offset:33792
	ds_read_b128 v[186:189], v153 offset:34816
	ds_read_b128 v[190:193], v153 offset:35840
	ds_read_b128 v[194:197], v153 offset:36864
	ds_read_b128 v[198:201], v153 offset:37888
	ds_read_b128 v[208:211], v153 offset:38912
	ds_read_b128 v[212:215], v153 offset:39936
	global_load_lds_dwordx4 v130, s[0:1]
	s_mov_b32 m0, s37
	s_nop 0
	global_load_lds_dwordx4 v134, s[0:1]
	s_waitcnt vmcnt(8)
	s_waitcnt lgkmcnt(0)
	s_setprio 1
	s_barrier
	v_mfma_f32_16x16x32_bf16 v[126:129], v[142:145], v[178:181], v[126:129]
	v_mfma_f32_16x16x32_bf16 v[122:125], v[154:157], v[178:181], v[122:125]
	v_mfma_f32_16x16x32_bf16 v[110:113], v[142:145], v[186:189], v[110:113]
	v_mfma_f32_16x16x32_bf16 v[106:109], v[154:157], v[186:189], v[106:109]
	v_mfma_f32_16x16x32_bf16 v[94:97], v[142:145], v[194:197], v[94:97]
	v_mfma_f32_16x16x32_bf16 v[90:93], v[154:157], v[194:197], v[90:93]
	v_mfma_f32_16x16x32_bf16 v[78:81], v[142:145], v[208:211], v[78:81]
	v_mfma_f32_16x16x32_bf16 v[74:77], v[154:157], v[208:211], v[74:77]
	v_mfma_f32_16x16x32_bf16 v[126:129], v[146:149], v[182:185], v[126:129]
	v_mfma_f32_16x16x32_bf16 v[122:125], v[158:161], v[182:185], v[122:125]
	v_mfma_f32_16x16x32_bf16 v[110:113], v[146:149], v[190:193], v[110:113]
	v_mfma_f32_16x16x32_bf16 v[106:109], v[158:161], v[190:193], v[106:109]
	v_mfma_f32_16x16x32_bf16 v[94:97], v[146:149], v[198:201], v[94:97]
	v_mfma_f32_16x16x32_bf16 v[90:93], v[158:161], v[198:201], v[90:93]
	v_mfma_f32_16x16x32_bf16 v[78:81], v[146:149], v[212:215], v[78:81]
	v_mfma_f32_16x16x32_bf16 v[74:77], v[158:161], v[212:215], v[74:77]
	s_setprio 0
	s_setprio 1
	v_mfma_f32_16x16x32_bf16 v[118:121], v[162:165], v[178:181], v[118:121]
	v_mfma_f32_16x16x32_bf16 v[114:117], v[170:173], v[178:181], v[114:117]
	v_mfma_f32_16x16x32_bf16 v[102:105], v[162:165], v[186:189], v[102:105]
	v_mfma_f32_16x16x32_bf16 v[98:101], v[170:173], v[186:189], v[98:101]
	v_mfma_f32_16x16x32_bf16 v[86:89], v[162:165], v[194:197], v[86:89]
	v_mfma_f32_16x16x32_bf16 v[82:85], v[170:173], v[194:197], v[82:85]
	v_mfma_f32_16x16x32_bf16 v[70:73], v[162:165], v[208:211], v[70:73]
	v_mfma_f32_16x16x32_bf16 v[66:69], v[170:173], v[208:211], v[66:69]
	v_mfma_f32_16x16x32_bf16 v[118:121], v[166:169], v[182:185], v[118:121]
	v_mfma_f32_16x16x32_bf16 v[114:117], v[174:177], v[182:185], v[114:117]
	v_mfma_f32_16x16x32_bf16 v[102:105], v[166:169], v[190:193], v[102:105]
	v_mfma_f32_16x16x32_bf16 v[98:101], v[174:177], v[190:193], v[98:101]
	v_mfma_f32_16x16x32_bf16 v[86:89], v[166:169], v[198:201], v[86:89]
	v_mfma_f32_16x16x32_bf16 v[82:85], v[174:177], v[198:201], v[82:85]
	v_mfma_f32_16x16x32_bf16 v[70:73], v[166:169], v[212:215], v[70:73]
	v_mfma_f32_16x16x32_bf16 v[66:69], v[174:177], v[212:215], v[66:69]
	s_barrier
	s_setprio 0
	s_add_i32 s0, s33, s34
	v_lshl_add_u64 v[204:205], v[204:205], 0, s[80:81]
	s_mov_b32 m0, s0
	ds_read_b128 v[178:181], v153 offset:49152
	ds_read_b128 v[182:185], v153 offset:50176
	ds_read_b128 v[186:189], v153 offset:51200
	ds_read_b128 v[190:193], v153 offset:52224
	ds_read_b128 v[194:197], v153 offset:53248
	ds_read_b128 v[198:201], v153 offset:54272
	ds_read_b128 v[208:211], v153 offset:55296
	ds_read_b128 v[212:215], v153 offset:56320
	global_load_lds_dwordx4 v[204:205], off
	s_add_i32 m0, s0, 0x2000
	s_add_u32 s0, s26, 0x80080
	v_lshl_add_u64 v[204:205], v[216:217], 0, s[80:81]
	s_addc_u32 s1, s27, 0
	s_add_i32 s26, s55, s34
	global_load_lds_dwordx4 v[204:205], off
	s_mov_b32 m0, s26
	s_nop 0
	global_load_lds_dwordx4 v132, s[0:1]
	s_add_i32 m0, s26, 0x2000
	s_nop 0
	global_load_lds_dwordx4 v136, s[0:1]
	v_lshl_add_u64 v[204:205], v[218:219], 0, s[80:81]
	s_mov_b32 m0, s39
	s_nop 0
	global_load_lds_dwordx4 v[204:205], off
	v_lshl_add_u64 v[204:205], v[220:221], 0, s[80:81]
	s_mov_b32 m0, s40
	s_nop 0
	global_load_lds_dwordx4 v[204:205], off
	s_waitcnt vmcnt(8)
	s_waitcnt lgkmcnt(0)
	s_setprio 1
	s_barrier
	v_mfma_f32_16x16x32_bf16 v[62:65], v[142:145], v[178:181], v[62:65]
	v_mfma_f32_16x16x32_bf16 v[58:61], v[154:157], v[178:181], v[58:61]
	v_mfma_f32_16x16x32_bf16 v[46:49], v[142:145], v[186:189], v[46:49]
	v_mfma_f32_16x16x32_bf16 v[42:45], v[154:157], v[186:189], v[42:45]
	v_mfma_f32_16x16x32_bf16 v[30:33], v[142:145], v[194:197], v[30:33]
	v_mfma_f32_16x16x32_bf16 v[26:29], v[154:157], v[194:197], v[26:29]
	v_mfma_f32_16x16x32_bf16 v[14:17], v[142:145], v[208:211], v[14:17]
	v_mfma_f32_16x16x32_bf16 v[10:13], v[154:157], v[208:211], v[10:13]
	v_mfma_f32_16x16x32_bf16 v[62:65], v[146:149], v[182:185], v[62:65]
	v_mfma_f32_16x16x32_bf16 v[58:61], v[158:161], v[182:185], v[58:61]
	v_mfma_f32_16x16x32_bf16 v[46:49], v[146:149], v[190:193], v[46:49]
	v_mfma_f32_16x16x32_bf16 v[42:45], v[158:161], v[190:193], v[42:45]
	v_mfma_f32_16x16x32_bf16 v[30:33], v[146:149], v[198:201], v[30:33]
	v_mfma_f32_16x16x32_bf16 v[26:29], v[158:161], v[198:201], v[26:29]
	v_mfma_f32_16x16x32_bf16 v[14:17], v[146:149], v[212:215], v[14:17]
	v_mfma_f32_16x16x32_bf16 v[10:13], v[158:161], v[212:215], v[10:13]
	s_setprio 0
	s_setprio 1
	v_mfma_f32_16x16x32_bf16 v[54:57], v[162:165], v[178:181], v[54:57]
	v_mfma_f32_16x16x32_bf16 v[50:53], v[170:173], v[178:181], v[50:53]
	v_mfma_f32_16x16x32_bf16 v[38:41], v[162:165], v[186:189], v[38:41]
	v_mfma_f32_16x16x32_bf16 v[34:37], v[170:173], v[186:189], v[34:37]
	v_mfma_f32_16x16x32_bf16 v[22:25], v[162:165], v[194:197], v[22:25]
	v_mfma_f32_16x16x32_bf16 v[18:21], v[170:173], v[194:197], v[18:21]
	v_mfma_f32_16x16x32_bf16 v[6:9], v[162:165], v[208:211], v[6:9]
	v_mfma_f32_16x16x32_bf16 v[2:5], v[170:173], v[208:211], v[2:5]
	v_mfma_f32_16x16x32_bf16 v[54:57], v[166:169], v[182:185], v[54:57]
	v_mfma_f32_16x16x32_bf16 v[50:53], v[174:177], v[182:185], v[50:53]
	v_mfma_f32_16x16x32_bf16 v[38:41], v[166:169], v[190:193], v[38:41]
	v_mfma_f32_16x16x32_bf16 v[34:37], v[174:177], v[190:193], v[34:37]
	v_mfma_f32_16x16x32_bf16 v[22:25], v[166:169], v[198:201], v[22:25]
	v_mfma_f32_16x16x32_bf16 v[18:21], v[174:177], v[198:201], v[18:21]
	v_mfma_f32_16x16x32_bf16 v[6:9], v[166:169], v[212:215], v[6:9]
	v_mfma_f32_16x16x32_bf16 v[2:5], v[174:177], v[212:215], v[2:5]
	s_barrier
	s_setprio 0
	s_add_i32 s60, s60, 2
	s_add_u32 s24, s24, 0x100
	s_addc_u32 s25, s25, 0
	s_add_u32 s58, s58, 0x100
	s_addc_u32 s59, s59, 0
	s_cmp_gt_u32 s60, 29
	s_cbranch_scc0 .LBB0_394
	s_and_b64 vcc, exec, s[14:15]
	s_cbranch_vccz .LBB0_397
	s_barrier

.LBB0_692:
	s_add_u32 s0, s18, 0xfff00080
	s_addc_u32 s1, s19, -1
	s_add_i32 s33, 0, 0x10000
	s_cmp_eq_u32 s61, 60
	s_cselect_b32 s23, s11, s1
	s_cselect_b32 s22, s49, s0
	s_cselect_b32 s21, s9, s60
	s_cselect_b32 s20, s58, s59
	s_add_i32 s55, 0, 0x14000
	v_add_u32_e32 v98, s33, v205
	v_add_u32_e32 v134, s55, v205
	ds_read_b128 v[78:81], v98
	ds_read_b128 v[86:89], v98 offset:1024
	ds_read_b128 v[94:97], v98 offset:2048
	ds_read_b128 v[98:101], v98 offset:3072
	ds_read_b128 v[106:109], v134
	ds_read_b128 v[110:113], v134 offset:1024
	ds_read_b128 v[126:129], v134 offset:2048
	ds_read_b128 v[134:137], v134 offset:3072
	s_add_i32 m0, s27, 0xc000
	ds_read_b128 v[146:149], v239
	ds_read_b128 v[158:161], v239 offset:1024
	ds_read_b128 v[166:169], v239 offset:2048
	ds_read_b128 v[174:177], v239 offset:3072
	ds_read_b128 v[178:181], v239 offset:4096
	ds_read_b128 v[182:185], v239 offset:5120
	ds_read_b128 v[186:189], v239 offset:6144
	ds_read_b128 v[190:193], v239 offset:7168
	global_load_lds_dwordx4 v214, s[18:19]
	s_add_i32 m0, s27, 0xe000
	s_nop 0
	global_load_lds_dwordx4 v216, s[18:19]
	s_waitcnt vmcnt(8)
	s_waitcnt lgkmcnt(0)
	s_setprio 1
	s_barrier
	v_mfma_f32_16x16x32_bf16 v[170:173], v[78:81], v[146:149], v[170:173]
	v_mfma_f32_16x16x32_bf16 v[162:165], v[94:97], v[146:149], v[162:165]
	v_mfma_f32_16x16x32_bf16 v[142:145], v[78:81], v[166:169], v[142:145]
	v_mfma_f32_16x16x32_bf16 v[138:141], v[94:97], v[166:169], v[138:141]
	v_mfma_f32_16x16x32_bf16 v[118:121], v[78:81], v[178:181], v[118:121]
	v_mfma_f32_16x16x32_bf16 v[114:117], v[94:97], v[178:181], v[114:117]
	v_mfma_f32_16x16x32_bf16 v[82:85], v[78:81], v[186:189], v[82:85]
	v_mfma_f32_16x16x32_bf16 v[74:77], v[94:97], v[186:189], v[74:77]
	v_mfma_f32_16x16x32_bf16 v[170:173], v[86:89], v[158:161], v[170:173]
	v_mfma_f32_16x16x32_bf16 v[162:165], v[98:101], v[158:161], v[162:165]
	v_mfma_f32_16x16x32_bf16 v[142:145], v[86:89], v[174:177], v[142:145]
	v_mfma_f32_16x16x32_bf16 v[138:141], v[98:101], v[174:177], v[138:141]
	v_mfma_f32_16x16x32_bf16 v[118:121], v[86:89], v[182:185], v[118:121]
	v_mfma_f32_16x16x32_bf16 v[114:117], v[98:101], v[182:185], v[114:117]
	v_mfma_f32_16x16x32_bf16 v[82:85], v[86:89], v[190:193], v[82:85]
	v_mfma_f32_16x16x32_bf16 v[74:77], v[98:101], v[190:193], v[74:77]
	s_setprio 0
	s_setprio 1
	v_mfma_f32_16x16x32_bf16 v[154:157], v[106:109], v[146:149], v[154:157]
	v_mfma_f32_16x16x32_bf16 v[130:133], v[106:109], v[166:169], v[130:133]
	v_mfma_f32_16x16x32_bf16 v[122:125], v[126:129], v[166:169], v[122:125]
	v_mfma_f32_16x16x32_bf16 v[102:105], v[106:109], v[178:181], v[102:105]
	v_mfma_f32_16x16x32_bf16 v[90:93], v[126:129], v[178:181], v[90:93]
	v_mfma_f32_16x16x32_bf16 v[70:73], v[106:109], v[186:189], v[70:73]
	v_mfma_f32_16x16x32_bf16 v[66:69], v[126:129], v[186:189], v[66:69]
	v_mfma_f32_16x16x32_bf16 v[154:157], v[110:113], v[158:161], v[154:157]
	v_mfma_f32_16x16x32_bf16 v[146:149], v[126:129], v[146:149], v[150:153]
	v_mfma_f32_16x16x32_bf16 v[130:133], v[110:113], v[174:177], v[130:133]
	v_mfma_f32_16x16x32_bf16 v[122:125], v[134:137], v[174:177], v[122:125]
	v_mfma_f32_16x16x32_bf16 v[102:105], v[110:113], v[182:185], v[102:105]
	v_mfma_f32_16x16x32_bf16 v[90:93], v[134:137], v[182:185], v[90:93]
	v_mfma_f32_16x16x32_bf16 v[70:73], v[110:113], v[190:193], v[70:73]
	v_mfma_f32_16x16x32_bf16 v[66:69], v[134:137], v[190:193], v[66:69]
	v_mfma_f32_16x16x32_bf16 v[146:149], v[134:137], v[158:161], v[146:149]
	s_barrier
	s_setprio 0
	s_add_i32 s0, s33, s26
	v_lshl_add_u64 v[194:195], s[20:21], 0, v[202:203]
	s_mov_b32 m0, s0
	ds_read_b128 v[150:153], v239 offset:16384
	ds_read_b128 v[158:161], v239 offset:17408
	ds_read_b128 v[166:169], v239 offset:18432
	ds_read_b128 v[174:177], v239 offset:19456
	ds_read_b128 v[178:181], v239 offset:20480
	ds_read_b128 v[182:185], v239 offset:21504
	ds_read_b128 v[186:189], v239 offset:22528
	ds_read_b128 v[190:193], v239 offset:23552
	global_load_lds_dwordx4 v[194:195], off
	s_add_i32 m0, s0, 0x2000
	s_add_u32 s0, s20, 0x100000
	v_lshl_add_u64 v[196:197], s[20:21], 0, v[208:209]
	s_addc_u32 s1, s21, 0
	s_add_i32 s33, s55, s26
	global_load_lds_dwordx4 v[196:197], off
	s_mov_b32 m0, s33
	v_lshl_add_u64 v[200:201], s[22:23], 0, v[210:211]
	global_load_lds_dwordx4 v202, s[0:1]
	s_add_i32 m0, s33, 0x2000
	s_nop 0
	global_load_lds_dwordx4 v208, s[0:1]
	v_lshl_add_u64 v[198:199], s[22:23], 0, v[212:213]
	s_mov_b32 m0, s27
	s_nop 0
	global_load_lds_dwordx4 v[198:199], off
	s_mov_b32 m0, s28
	s_nop 0
	global_load_lds_dwordx4 v[200:201], off
	s_waitcnt vmcnt(8)
	s_waitcnt lgkmcnt(0)
	s_setprio 1
	s_barrier
	v_mfma_f32_16x16x32_bf16 v[62:65], v[78:81], v[150:153], v[62:65]
	v_mfma_f32_16x16x32_bf16 v[58:61], v[94:97], v[150:153], v[58:61]
	v_mfma_f32_16x16x32_bf16 v[46:49], v[78:81], v[166:169], v[46:49]
	v_mfma_f32_16x16x32_bf16 v[42:45], v[94:97], v[166:169], v[42:45]
	v_mfma_f32_16x16x32_bf16 v[30:33], v[78:81], v[178:181], v[30:33]
	v_mfma_f32_16x16x32_bf16 v[26:29], v[94:97], v[178:181], v[26:29]
	v_mfma_f32_16x16x32_bf16 v[14:17], v[78:81], v[186:189], v[14:17]
	v_mfma_f32_16x16x32_bf16 v[10:13], v[94:97], v[186:189], v[10:13]
	v_mfma_f32_16x16x32_bf16 v[62:65], v[86:89], v[158:161], v[62:65]
	v_mfma_f32_16x16x32_bf16 v[58:61], v[98:101], v[158:161], v[58:61]
	v_mfma_f32_16x16x32_bf16 v[46:49], v[86:89], v[174:177], v[46:49]
	v_mfma_f32_16x16x32_bf16 v[42:45], v[98:101], v[174:177], v[42:45]
	v_mfma_f32_16x16x32_bf16 v[30:33], v[86:89], v[182:185], v[30:33]
	v_mfma_f32_16x16x32_bf16 v[26:29], v[98:101], v[182:185], v[26:29]
	v_mfma_f32_16x16x32_bf16 v[14:17], v[86:89], v[190:193], v[14:17]
	v_mfma_f32_16x16x32_bf16 v[10:13], v[98:101], v[190:193], v[10:13]
	s_setprio 0
	s_setprio 1
	v_mfma_f32_16x16x32_bf16 v[54:57], v[106:109], v[150:153], v[54:57]
	v_mfma_f32_16x16x32_bf16 v[50:53], v[126:129], v[150:153], v[50:53]
	v_mfma_f32_16x16x32_bf16 v[38:41], v[106:109], v[166:169], v[38:41]
	v_mfma_f32_16x16x32_bf16 v[34:37], v[126:129], v[166:169], v[34:37]
	v_mfma_f32_16x16x32_bf16 v[22:25], v[106:109], v[178:181], v[22:25]
	v_mfma_f32_16x16x32_bf16 v[18:21], v[126:129], v[178:181], v[18:21]
	v_mfma_f32_16x16x32_bf16 v[6:9], v[106:109], v[186:189], v[6:9]
	v_mfma_f32_16x16x32_bf16 v[2:5], v[126:129], v[186:189], v[2:5]
	v_mfma_f32_16x16x32_bf16 v[54:57], v[110:113], v[158:161], v[54:57]
	v_mfma_f32_16x16x32_bf16 v[50:53], v[134:137], v[158:161], v[50:53]
	v_mfma_f32_16x16x32_bf16 v[38:41], v[110:113], v[174:177], v[38:41]
	v_mfma_f32_16x16x32_bf16 v[34:37], v[134:137], v[174:177], v[34:37]
	v_mfma_f32_16x16x32_bf16 v[22:25], v[110:113], v[182:185], v[22:25]
	v_mfma_f32_16x16x32_bf16 v[18:21], v[134:137], v[182:185], v[18:21]
	v_mfma_f32_16x16x32_bf16 v[6:9], v[110:113], v[190:193], v[6:9]
	v_mfma_f32_16x16x32_bf16 v[2:5], v[134:137], v[190:193], v[2:5]
	s_barrier
	s_setprio 0
	s_add_i32 s33, 0, 0x18000
	s_add_i32 s55, 0, 0x1c000
	v_add_u32_e32 v98, s33, v205
	v_add_u32_e32 v134, s55, v205
	ds_read_b128 v[78:81], v98
	ds_read_b128 v[86:89], v98 offset:1024
	ds_read_b128 v[94:97], v98 offset:2048
	ds_read_b128 v[98:101], v98 offset:3072
	ds_read_b128 v[106:109], v134
	ds_read_b128 v[110:113], v134 offset:1024
	ds_read_b128 v[126:129], v134 offset:2048
	ds_read_b128 v[134:137], v134 offset:3072
	s_add_u32 s0, s22, 0x100000
	s_addc_u32 s1, s23, 0
	s_mov_b32 m0, s29
	ds_read_b128 v[150:153], v239 offset:32768
	ds_read_b128 v[158:161], v239 offset:33792
	ds_read_b128 v[166:169], v239 offset:34816
	ds_read_b128 v[174:177], v239 offset:35840
	ds_read_b128 v[178:181], v239 offset:36864
	ds_read_b128 v[182:185], v239 offset:37888
	ds_read_b128 v[186:189], v239 offset:38912
	ds_read_b128 v[190:193], v239 offset:39936
	global_load_lds_dwordx4 v212, s[0:1]
	s_mov_b32 m0, s30
	s_nop 0
	global_load_lds_dwordx4 v210, s[0:1]
	s_waitcnt vmcnt(8)
	s_waitcnt lgkmcnt(0)
	s_setprio 1
	s_barrier
	v_mfma_f32_16x16x32_bf16 v[170:173], v[78:81], v[150:153], v[170:173]
	v_mfma_f32_16x16x32_bf16 v[162:165], v[94:97], v[150:153], v[162:165]
	v_mfma_f32_16x16x32_bf16 v[142:145], v[78:81], v[166:169], v[142:145]
	v_mfma_f32_16x16x32_bf16 v[138:141], v[94:97], v[166:169], v[138:141]
	v_mfma_f32_16x16x32_bf16 v[118:121], v[78:81], v[178:181], v[118:121]
	v_mfma_f32_16x16x32_bf16 v[114:117], v[94:97], v[178:181], v[114:117]
	v_mfma_f32_16x16x32_bf16 v[82:85], v[78:81], v[186:189], v[82:85]
	v_mfma_f32_16x16x32_bf16 v[74:77], v[94:97], v[186:189], v[74:77]
	v_mfma_f32_16x16x32_bf16 v[170:173], v[86:89], v[158:161], v[170:173]
	v_mfma_f32_16x16x32_bf16 v[162:165], v[98:101], v[158:161], v[162:165]
	v_mfma_f32_16x16x32_bf16 v[142:145], v[86:89], v[174:177], v[142:145]
	v_mfma_f32_16x16x32_bf16 v[138:141], v[98:101], v[174:177], v[138:141]
	v_mfma_f32_16x16x32_bf16 v[118:121], v[86:89], v[182:185], v[118:121]
	v_mfma_f32_16x16x32_bf16 v[114:117], v[98:101], v[182:185], v[114:117]
	v_mfma_f32_16x16x32_bf16 v[82:85], v[86:89], v[190:193], v[82:85]
	v_mfma_f32_16x16x32_bf16 v[74:77], v[98:101], v[190:193], v[74:77]
	s_setprio 0
	s_setprio 1
	v_mfma_f32_16x16x32_bf16 v[154:157], v[106:109], v[150:153], v[154:157]
	v_mfma_f32_16x16x32_bf16 v[146:149], v[126:129], v[150:153], v[146:149]
	v_mfma_f32_16x16x32_bf16 v[130:133], v[106:109], v[166:169], v[130:133]
	v_mfma_f32_16x16x32_bf16 v[122:125], v[126:129], v[166:169], v[122:125]
	v_mfma_f32_16x16x32_bf16 v[102:105], v[106:109], v[178:181], v[102:105]
	v_mfma_f32_16x16x32_bf16 v[90:93], v[126:129], v[178:181], v[90:93]
	v_mfma_f32_16x16x32_bf16 v[70:73], v[106:109], v[186:189], v[70:73]
	v_mfma_f32_16x16x32_bf16 v[66:69], v[126:129], v[186:189], v[66:69]
	v_mfma_f32_16x16x32_bf16 v[154:157], v[110:113], v[158:161], v[154:157]
	v_mfma_f32_16x16x32_bf16 v[150:153], v[134:137], v[158:161], v[146:149]
	v_mfma_f32_16x16x32_bf16 v[130:133], v[110:113], v[174:177], v[130:133]
	v_mfma_f32_16x16x32_bf16 v[122:125], v[134:137], v[174:177], v[122:125]
	v_mfma_f32_16x16x32_bf16 v[102:105], v[110:113], v[182:185], v[102:105]
	v_mfma_f32_16x16x32_bf16 v[90:93], v[134:137], v[182:185], v[90:93]
	v_mfma_f32_16x16x32_bf16 v[70:73], v[110:113], v[190:193], v[70:73]
	v_mfma_f32_16x16x32_bf16 v[66:69], v[134:137], v[190:193], v[66:69]
	s_barrier
	s_setprio 0
	s_add_i32 s0, s33, s26
	v_lshl_add_u64 v[194:195], v[194:195], 0, s[80:81]
	s_mov_b32 m0, s0
	ds_read_b128 v[146:149], v239 offset:49152
	ds_read_b128 v[158:161], v239 offset:50176
	ds_read_b128 v[166:169], v239 offset:51200
	ds_read_b128 v[174:177], v239 offset:52224
	ds_read_b128 v[178:181], v239 offset:53248
	ds_read_b128 v[182:185], v239 offset:54272
	ds_read_b128 v[186:189], v239 offset:55296
	ds_read_b128 v[190:193], v239 offset:56320
	global_load_lds_dwordx4 v[194:195], off
	s_add_i32 m0, s0, 0x2000
	s_add_u32 s0, s20, 0x100080
	v_lshl_add_u64 v[194:195], v[196:197], 0, s[80:81]
	s_addc_u32 s1, s21, 0
	s_add_i32 s20, s55, s26
	global_load_lds_dwordx4 v[194:195], off
	s_mov_b32 m0, s20
	s_nop 0
	global_load_lds_dwordx4 v202, s[0:1]
	s_add_i32 m0, s20, 0x2000
	s_nop 0
	global_load_lds_dwordx4 v208, s[0:1]
	v_lshl_add_u64 v[194:195], v[198:199], 0, s[80:81]
	s_mov_b32 m0, s35
	s_nop 0
	global_load_lds_dwordx4 v[194:195], off
	v_lshl_add_u64 v[194:195], v[200:201], 0, s[80:81]
	s_mov_b32 m0, s36
	s_nop 0
	global_load_lds_dwordx4 v[194:195], off
	s_waitcnt vmcnt(8)
	s_waitcnt lgkmcnt(0)
	s_setprio 1
	s_barrier
	v_mfma_f32_16x16x32_bf16 v[62:65], v[78:81], v[146:149], v[62:65]
	v_mfma_f32_16x16x32_bf16 v[58:61], v[94:97], v[146:149], v[58:61]
	v_mfma_f32_16x16x32_bf16 v[46:49], v[78:81], v[166:169], v[46:49]
	v_mfma_f32_16x16x32_bf16 v[42:45], v[94:97], v[166:169], v[42:45]
	v_mfma_f32_16x16x32_bf16 v[30:33], v[78:81], v[178:181], v[30:33]
	v_mfma_f32_16x16x32_bf16 v[26:29], v[94:97], v[178:181], v[26:29]
	v_mfma_f32_16x16x32_bf16 v[14:17], v[78:81], v[186:189], v[14:17]
	v_mfma_f32_16x16x32_bf16 v[10:13], v[94:97], v[186:189], v[10:13]
	v_mfma_f32_16x16x32_bf16 v[62:65], v[86:89], v[158:161], v[62:65]
	v_mfma_f32_16x16x32_bf16 v[58:61], v[98:101], v[158:161], v[58:61]
	v_mfma_f32_16x16x32_bf16 v[46:49], v[86:89], v[174:177], v[46:49]
	v_mfma_f32_16x16x32_bf16 v[42:45], v[98:101], v[174:177], v[42:45]
	v_mfma_f32_16x16x32_bf16 v[30:33], v[86:89], v[182:185], v[30:33]
	v_mfma_f32_16x16x32_bf16 v[26:29], v[98:101], v[182:185], v[26:29]
	v_mfma_f32_16x16x32_bf16 v[14:17], v[86:89], v[190:193], v[14:17]
	v_mfma_f32_16x16x32_bf16 v[10:13], v[98:101], v[190:193], v[10:13]
	s_setprio 0
	s_setprio 1
	v_mfma_f32_16x16x32_bf16 v[54:57], v[106:109], v[146:149], v[54:57]
	v_mfma_f32_16x16x32_bf16 v[50:53], v[126:129], v[146:149], v[50:53]
	v_mfma_f32_16x16x32_bf16 v[38:41], v[106:109], v[166:169], v[38:41]
	v_mfma_f32_16x16x32_bf16 v[34:37], v[126:129], v[166:169], v[34:37]
	v_mfma_f32_16x16x32_bf16 v[22:25], v[106:109], v[178:181], v[22:25]
	v_mfma_f32_16x16x32_bf16 v[18:21], v[126:129], v[178:181], v[18:21]
	v_mfma_f32_16x16x32_bf16 v[6:9], v[106:109], v[186:189], v[6:9]
	v_mfma_f32_16x16x32_bf16 v[2:5], v[126:129], v[186:189], v[2:5]
	v_mfma_f32_16x16x32_bf16 v[54:57], v[110:113], v[158:161], v[54:57]
	v_mfma_f32_16x16x32_bf16 v[50:53], v[134:137], v[158:161], v[50:53]
	v_mfma_f32_16x16x32_bf16 v[38:41], v[110:113], v[174:177], v[38:41]
	v_mfma_f32_16x16x32_bf16 v[34:37], v[134:137], v[174:177], v[34:37]
	v_mfma_f32_16x16x32_bf16 v[22:25], v[110:113], v[182:185], v[22:25]
	v_mfma_f32_16x16x32_bf16 v[18:21], v[134:137], v[182:185], v[18:21]
	v_mfma_f32_16x16x32_bf16 v[6:9], v[110:113], v[190:193], v[6:9]
	v_mfma_f32_16x16x32_bf16 v[2:5], v[134:137], v[190:193], v[2:5]
	s_barrier
	s_setprio 0
	s_add_i32 s61, s61, 2
	s_add_u32 s18, s18, 0x100
	s_addc_u32 s19, s19, 0
	s_add_u32 s59, s59, 0x100
	s_addc_u32 s60, s60, 0
	s_cmp_gt_u32 s61, 61
	s_cbranch_scc0 .LBB0_692
	s_and_b64 vcc, exec, s[6:7]
	s_cbranch_vccz .LBB0_695
	s_barrier

.LBB0_712:
	s_add_u32 s0, s18, 0xfff00080
	s_addc_u32 s1, s19, -1
	s_add_i32 s33, 0, 0x10000
	s_cmp_eq_u32 s49, 4
	s_cselect_b32 s23, s15, s1
	s_cselect_b32 s22, s14, s0
	s_cselect_b32 s21, s17, s11
	s_cselect_b32 s20, s16, s9
	s_add_i32 s55, 0, 0x14000
	v_add_u32_e32 v152, s33, v136
	v_add_u32_e32 v168, s55, v136
	ds_read_b128 v[140:143], v152
	ds_read_b128 v[144:147], v152 offset:1024
	ds_read_b128 v[148:151], v152 offset:2048
	ds_read_b128 v[152:155], v152 offset:3072
	ds_read_b128 v[156:159], v168
	ds_read_b128 v[160:163], v168 offset:1024
	ds_read_b128 v[164:167], v168 offset:2048
	ds_read_b128 v[168:171], v168 offset:3072
	s_add_i32 m0, s27, 0xc000
	ds_read_b128 v[172:175], v139
	ds_read_b128 v[176:179], v139 offset:1024
	ds_read_b128 v[180:183], v139 offset:2048
	ds_read_b128 v[184:187], v139 offset:3072
	ds_read_b128 v[188:191], v139 offset:4096
	ds_read_b128 v[192:195], v139 offset:5120
	ds_read_b128 v[196:199], v139 offset:6144
	ds_read_b128 v[208:211], v139 offset:7168
	global_load_lds_dwordx4 v132, s[18:19]
	s_add_i32 m0, s27, 0xe000
	s_nop 0
	global_load_lds_dwordx4 v134, s[18:19]
	s_waitcnt vmcnt(8)
	s_waitcnt lgkmcnt(0)
	s_setprio 1
	s_barrier
	v_mfma_f32_16x16x32_bf16 v[126:129], v[140:143], v[172:175], v[126:129]
	v_mfma_f32_16x16x32_bf16 v[122:125], v[148:151], v[172:175], v[122:125]
	v_mfma_f32_16x16x32_bf16 v[118:121], v[140:143], v[180:183], v[118:121]
	v_mfma_f32_16x16x32_bf16 v[114:117], v[148:151], v[180:183], v[114:117]
	v_mfma_f32_16x16x32_bf16 v[106:109], v[140:143], v[188:191], v[106:109]
	v_mfma_f32_16x16x32_bf16 v[98:101], v[148:151], v[188:191], v[98:101]
	v_mfma_f32_16x16x32_bf16 v[90:93], v[140:143], v[196:199], v[90:93]
	v_mfma_f32_16x16x32_bf16 v[82:85], v[148:151], v[196:199], v[82:85]
	v_mfma_f32_16x16x32_bf16 v[126:129], v[144:147], v[176:179], v[126:129]
	v_mfma_f32_16x16x32_bf16 v[122:125], v[152:155], v[176:179], v[122:125]
	v_mfma_f32_16x16x32_bf16 v[118:121], v[144:147], v[184:187], v[118:121]
	v_mfma_f32_16x16x32_bf16 v[114:117], v[152:155], v[184:187], v[114:117]
	v_mfma_f32_16x16x32_bf16 v[106:109], v[144:147], v[192:195], v[106:109]
	v_mfma_f32_16x16x32_bf16 v[98:101], v[152:155], v[192:195], v[98:101]
	v_mfma_f32_16x16x32_bf16 v[90:93], v[144:147], v[208:211], v[90:93]
	v_mfma_f32_16x16x32_bf16 v[82:85], v[152:155], v[208:211], v[82:85]
	s_setprio 0
	s_setprio 1
	v_mfma_f32_16x16x32_bf16 v[110:113], v[156:159], v[172:175], v[110:113]
	v_mfma_f32_16x16x32_bf16 v[102:105], v[164:167], v[172:175], v[102:105]
	v_mfma_f32_16x16x32_bf16 v[94:97], v[156:159], v[180:183], v[94:97]
	v_mfma_f32_16x16x32_bf16 v[86:89], v[164:167], v[180:183], v[86:89]
	v_mfma_f32_16x16x32_bf16 v[78:81], v[156:159], v[188:191], v[78:81]
	v_mfma_f32_16x16x32_bf16 v[74:77], v[164:167], v[188:191], v[74:77]
	v_mfma_f32_16x16x32_bf16 v[70:73], v[156:159], v[196:199], v[70:73]
	v_mfma_f32_16x16x32_bf16 v[66:69], v[164:167], v[196:199], v[66:69]
	v_mfma_f32_16x16x32_bf16 v[110:113], v[160:163], v[176:179], v[110:113]
	v_mfma_f32_16x16x32_bf16 v[102:105], v[168:171], v[176:179], v[102:105]
	v_mfma_f32_16x16x32_bf16 v[94:97], v[160:163], v[184:187], v[94:97]
	v_mfma_f32_16x16x32_bf16 v[86:89], v[168:171], v[184:187], v[86:89]
	v_mfma_f32_16x16x32_bf16 v[78:81], v[160:163], v[192:195], v[78:81]
	v_mfma_f32_16x16x32_bf16 v[74:77], v[168:171], v[192:195], v[74:77]
	v_mfma_f32_16x16x32_bf16 v[70:73], v[160:163], v[208:211], v[70:73]
	v_mfma_f32_16x16x32_bf16 v[66:69], v[168:171], v[208:211], v[66:69]
	s_barrier
	s_setprio 0
	s_add_i32 s0, s33, s26
	v_lshl_add_u64 v[200:201], s[20:21], 0, v[202:203]
	s_mov_b32 m0, s0
	ds_read_b128 v[172:175], v139 offset:16384
	ds_read_b128 v[176:179], v139 offset:17408
	ds_read_b128 v[180:183], v139 offset:18432
	ds_read_b128 v[184:187], v139 offset:19456
	ds_read_b128 v[188:191], v139 offset:20480
	ds_read_b128 v[192:195], v139 offset:21504
	ds_read_b128 v[196:199], v139 offset:22528
	ds_read_b128 v[208:211], v139 offset:23552
	global_load_lds_dwordx4 v[200:201], off
	s_add_i32 m0, s0, 0x2000
	s_add_u32 s0, s20, 0x100000
	v_lshl_add_u64 v[204:205], s[20:21], 0, v[130:131]
	s_addc_u32 s1, s21, 0
	s_add_i32 s33, s55, s26
	global_load_lds_dwordx4 v[204:205], off
	s_mov_b32 m0, s33
	v_lshl_add_u64 v[212:213], s[22:23], 0, v[130:131]
	global_load_lds_dwordx4 v202, s[0:1]
	s_add_i32 m0, s33, 0x2000
	s_nop 0
	global_load_lds_dwordx4 v130, s[0:1]
	v_lshl_add_u64 v[206:207], s[22:23], 0, v[202:203]
	s_mov_b32 m0, s27
	s_nop 0
	global_load_lds_dwordx4 v[206:207], off
	s_mov_b32 m0, s28
	s_nop 0
	global_load_lds_dwordx4 v[212:213], off
	s_waitcnt vmcnt(8)
	s_waitcnt lgkmcnt(0)
	s_setprio 1
	s_barrier
	v_mfma_f32_16x16x32_bf16 v[62:65], v[140:143], v[172:175], v[62:65]
	v_mfma_f32_16x16x32_bf16 v[58:61], v[148:151], v[172:175], v[58:61]
	v_mfma_f32_16x16x32_bf16 v[54:57], v[140:143], v[180:183], v[54:57]
	v_mfma_f32_16x16x32_bf16 v[50:53], v[148:151], v[180:183], v[50:53]
	v_mfma_f32_16x16x32_bf16 v[38:41], v[140:143], v[188:191], v[38:41]
	v_mfma_f32_16x16x32_bf16 v[34:37], v[148:151], v[188:191], v[34:37]
	v_mfma_f32_16x16x32_bf16 v[22:25], v[140:143], v[196:199], v[22:25]
	v_mfma_f32_16x16x32_bf16 v[18:21], v[148:151], v[196:199], v[18:21]
	v_mfma_f32_16x16x32_bf16 v[62:65], v[144:147], v[176:179], v[62:65]
	v_mfma_f32_16x16x32_bf16 v[58:61], v[152:155], v[176:179], v[58:61]
	v_mfma_f32_16x16x32_bf16 v[54:57], v[144:147], v[184:187], v[54:57]
	v_mfma_f32_16x16x32_bf16 v[50:53], v[152:155], v[184:187], v[50:53]
	v_mfma_f32_16x16x32_bf16 v[38:41], v[144:147], v[192:195], v[38:41]
	v_mfma_f32_16x16x32_bf16 v[34:37], v[152:155], v[192:195], v[34:37]
	v_mfma_f32_16x16x32_bf16 v[22:25], v[144:147], v[208:211], v[22:25]
	v_mfma_f32_16x16x32_bf16 v[18:21], v[152:155], v[208:211], v[18:21]
	s_setprio 0
	s_setprio 1
	v_mfma_f32_16x16x32_bf16 v[46:49], v[156:159], v[172:175], v[46:49]
	v_mfma_f32_16x16x32_bf16 v[42:45], v[164:167], v[172:175], v[42:45]
	v_mfma_f32_16x16x32_bf16 v[30:33], v[156:159], v[180:183], v[30:33]
	v_mfma_f32_16x16x32_bf16 v[26:29], v[164:167], v[180:183], v[26:29]
	v_mfma_f32_16x16x32_bf16 v[14:17], v[156:159], v[188:191], v[14:17]
	v_mfma_f32_16x16x32_bf16 v[10:13], v[164:167], v[188:191], v[10:13]
	v_mfma_f32_16x16x32_bf16 v[6:9], v[156:159], v[196:199], v[6:9]
	v_mfma_f32_16x16x32_bf16 v[2:5], v[164:167], v[196:199], v[2:5]
	v_mfma_f32_16x16x32_bf16 v[46:49], v[160:163], v[176:179], v[46:49]
	v_mfma_f32_16x16x32_bf16 v[42:45], v[168:171], v[176:179], v[42:45]
	v_mfma_f32_16x16x32_bf16 v[30:33], v[160:163], v[184:187], v[30:33]
	v_mfma_f32_16x16x32_bf16 v[26:29], v[168:171], v[184:187], v[26:29]
	v_mfma_f32_16x16x32_bf16 v[14:17], v[160:163], v[192:195], v[14:17]
	v_mfma_f32_16x16x32_bf16 v[10:13], v[168:171], v[192:195], v[10:13]
	v_mfma_f32_16x16x32_bf16 v[6:9], v[160:163], v[208:211], v[6:9]
	v_mfma_f32_16x16x32_bf16 v[2:5], v[168:171], v[208:211], v[2:5]
	s_barrier
	s_setprio 0
	s_add_i32 s33, 0, 0x18000
	s_add_i32 s55, 0, 0x1c000
	v_add_u32_e32 v152, s33, v136
	v_add_u32_e32 v168, s55, v136
	ds_read_b128 v[140:143], v152
	ds_read_b128 v[144:147], v152 offset:1024
	ds_read_b128 v[148:151], v152 offset:2048
	ds_read_b128 v[152:155], v152 offset:3072
	ds_read_b128 v[156:159], v168
	ds_read_b128 v[160:163], v168 offset:1024
	ds_read_b128 v[164:167], v168 offset:2048
	ds_read_b128 v[168:171], v168 offset:3072
	s_add_u32 s0, s22, 0x100000
	s_addc_u32 s1, s23, 0
	s_mov_b32 m0, s29
	ds_read_b128 v[172:175], v139 offset:32768
	ds_read_b128 v[176:179], v139 offset:33792
	ds_read_b128 v[180:183], v139 offset:34816
	ds_read_b128 v[184:187], v139 offset:35840
	ds_read_b128 v[188:191], v139 offset:36864
	ds_read_b128 v[192:195], v139 offset:37888
	ds_read_b128 v[196:199], v139 offset:38912
	ds_read_b128 v[208:211], v139 offset:39936
	global_load_lds_dwordx4 v202, s[0:1]
	s_mov_b32 m0, s30
	s_nop 0
	global_load_lds_dwordx4 v130, s[0:1]
	s_waitcnt vmcnt(8)
	s_waitcnt lgkmcnt(0)
	s_setprio 1
	s_barrier
	v_mfma_f32_16x16x32_bf16 v[126:129], v[140:143], v[172:175], v[126:129]
	v_mfma_f32_16x16x32_bf16 v[122:125], v[148:151], v[172:175], v[122:125]
	v_mfma_f32_16x16x32_bf16 v[118:121], v[140:143], v[180:183], v[118:121]
	v_mfma_f32_16x16x32_bf16 v[114:117], v[148:151], v[180:183], v[114:117]
	v_mfma_f32_16x16x32_bf16 v[106:109], v[140:143], v[188:191], v[106:109]
	v_mfma_f32_16x16x32_bf16 v[98:101], v[148:151], v[188:191], v[98:101]
	v_mfma_f32_16x16x32_bf16 v[90:93], v[140:143], v[196:199], v[90:93]
	v_mfma_f32_16x16x32_bf16 v[82:85], v[148:151], v[196:199], v[82:85]
	v_mfma_f32_16x16x32_bf16 v[126:129], v[144:147], v[176:179], v[126:129]
	v_mfma_f32_16x16x32_bf16 v[122:125], v[152:155], v[176:179], v[122:125]
	v_mfma_f32_16x16x32_bf16 v[118:121], v[144:147], v[184:187], v[118:121]
	v_mfma_f32_16x16x32_bf16 v[114:117], v[152:155], v[184:187], v[114:117]
	v_mfma_f32_16x16x32_bf16 v[106:109], v[144:147], v[192:195], v[106:109]
	v_mfma_f32_16x16x32_bf16 v[98:101], v[152:155], v[192:195], v[98:101]
	v_mfma_f32_16x16x32_bf16 v[90:93], v[144:147], v[208:211], v[90:93]
	v_mfma_f32_16x16x32_bf16 v[82:85], v[152:155], v[208:211], v[82:85]
	s_setprio 0
	s_setprio 1
	v_mfma_f32_16x16x32_bf16 v[110:113], v[156:159], v[172:175], v[110:113]
	v_mfma_f32_16x16x32_bf16 v[102:105], v[164:167], v[172:175], v[102:105]
	v_mfma_f32_16x16x32_bf16 v[94:97], v[156:159], v[180:183], v[94:97]
	v_mfma_f32_16x16x32_bf16 v[86:89], v[164:167], v[180:183], v[86:89]
	v_mfma_f32_16x16x32_bf16 v[78:81], v[156:159], v[188:191], v[78:81]
	v_mfma_f32_16x16x32_bf16 v[74:77], v[164:167], v[188:191], v[74:77]
	v_mfma_f32_16x16x32_bf16 v[70:73], v[156:159], v[196:199], v[70:73]
	v_mfma_f32_16x16x32_bf16 v[66:69], v[164:167], v[196:199], v[66:69]
	v_mfma_f32_16x16x32_bf16 v[110:113], v[160:163], v[176:179], v[110:113]
	v_mfma_f32_16x16x32_bf16 v[102:105], v[168:171], v[176:179], v[102:105]
	v_mfma_f32_16x16x32_bf16 v[94:97], v[160:163], v[184:187], v[94:97]
	v_mfma_f32_16x16x32_bf16 v[86:89], v[168:171], v[184:187], v[86:89]
	v_mfma_f32_16x16x32_bf16 v[78:81], v[160:163], v[192:195], v[78:81]
	v_mfma_f32_16x16x32_bf16 v[74:77], v[168:171], v[192:195], v[74:77]
	v_mfma_f32_16x16x32_bf16 v[70:73], v[160:163], v[208:211], v[70:73]
	v_mfma_f32_16x16x32_bf16 v[66:69], v[168:171], v[208:211], v[66:69]
	s_barrier
	s_setprio 0
	s_add_i32 s0, s33, s26
	v_lshl_add_u64 v[200:201], v[200:201], 0, s[80:81]
	s_mov_b32 m0, s0
	ds_read_b128 v[172:175], v139 offset:49152
	ds_read_b128 v[176:179], v139 offset:50176
	ds_read_b128 v[180:183], v139 offset:51200
	ds_read_b128 v[184:187], v139 offset:52224
	ds_read_b128 v[188:191], v139 offset:53248
	ds_read_b128 v[192:195], v139 offset:54272
	ds_read_b128 v[196:199], v139 offset:55296
	ds_read_b128 v[208:211], v139 offset:56320
	global_load_lds_dwordx4 v[200:201], off
	s_add_i32 m0, s0, 0x2000
	s_add_u32 s0, s20, 0x100080
	v_lshl_add_u64 v[200:201], v[204:205], 0, s[80:81]
	s_addc_u32 s1, s21, 0
	s_add_i32 s20, s55, s26
	global_load_lds_dwordx4 v[200:201], off
	s_mov_b32 m0, s20
	s_nop 0
	global_load_lds_dwordx4 v202, s[0:1]
	s_add_i32 m0, s20, 0x2000
	s_nop 0
	global_load_lds_dwordx4 v130, s[0:1]
	v_lshl_add_u64 v[200:201], v[206:207], 0, s[80:81]
	s_mov_b32 m0, s31
	s_nop 0
	global_load_lds_dwordx4 v[200:201], off
	v_lshl_add_u64 v[200:201], v[212:213], 0, s[80:81]
	s_mov_b32 m0, s34
	s_nop 0
	global_load_lds_dwordx4 v[200:201], off
	s_waitcnt vmcnt(8)
	s_waitcnt lgkmcnt(0)
	s_setprio 1
	s_barrier
	v_mfma_f32_16x16x32_bf16 v[62:65], v[140:143], v[172:175], v[62:65]
	v_mfma_f32_16x16x32_bf16 v[58:61], v[148:151], v[172:175], v[58:61]
	v_mfma_f32_16x16x32_bf16 v[54:57], v[140:143], v[180:183], v[54:57]
	v_mfma_f32_16x16x32_bf16 v[50:53], v[148:151], v[180:183], v[50:53]
	v_mfma_f32_16x16x32_bf16 v[38:41], v[140:143], v[188:191], v[38:41]
	v_mfma_f32_16x16x32_bf16 v[34:37], v[148:151], v[188:191], v[34:37]
	v_mfma_f32_16x16x32_bf16 v[22:25], v[140:143], v[196:199], v[22:25]
	v_mfma_f32_16x16x32_bf16 v[18:21], v[148:151], v[196:199], v[18:21]
	v_mfma_f32_16x16x32_bf16 v[62:65], v[144:147], v[176:179], v[62:65]
	v_mfma_f32_16x16x32_bf16 v[58:61], v[152:155], v[176:179], v[58:61]
	v_mfma_f32_16x16x32_bf16 v[54:57], v[144:147], v[184:187], v[54:57]
	v_mfma_f32_16x16x32_bf16 v[50:53], v[152:155], v[184:187], v[50:53]
	v_mfma_f32_16x16x32_bf16 v[38:41], v[144:147], v[192:195], v[38:41]
	v_mfma_f32_16x16x32_bf16 v[34:37], v[152:155], v[192:195], v[34:37]
	v_mfma_f32_16x16x32_bf16 v[22:25], v[144:147], v[208:211], v[22:25]
	v_mfma_f32_16x16x32_bf16 v[18:21], v[152:155], v[208:211], v[18:21]
	s_setprio 0
	s_setprio 1
	v_mfma_f32_16x16x32_bf16 v[46:49], v[156:159], v[172:175], v[46:49]
	v_mfma_f32_16x16x32_bf16 v[42:45], v[164:167], v[172:175], v[42:45]
	v_mfma_f32_16x16x32_bf16 v[30:33], v[156:159], v[180:183], v[30:33]
	v_mfma_f32_16x16x32_bf16 v[26:29], v[164:167], v[180:183], v[26:29]
	v_mfma_f32_16x16x32_bf16 v[14:17], v[156:159], v[188:191], v[14:17]
	v_mfma_f32_16x16x32_bf16 v[10:13], v[164:167], v[188:191], v[10:13]
	v_mfma_f32_16x16x32_bf16 v[6:9], v[156:159], v[196:199], v[6:9]
	v_mfma_f32_16x16x32_bf16 v[2:5], v[164:167], v[196:199], v[2:5]
	v_mfma_f32_16x16x32_bf16 v[46:49], v[160:163], v[176:179], v[46:49]
	v_mfma_f32_16x16x32_bf16 v[42:45], v[168:171], v[176:179], v[42:45]
	v_mfma_f32_16x16x32_bf16 v[30:33], v[160:163], v[184:187], v[30:33]
	v_mfma_f32_16x16x32_bf16 v[26:29], v[168:171], v[184:187], v[26:29]
	v_mfma_f32_16x16x32_bf16 v[14:17], v[160:163], v[192:195], v[14:17]
	v_mfma_f32_16x16x32_bf16 v[10:13], v[168:171], v[192:195], v[10:13]
	v_mfma_f32_16x16x32_bf16 v[6:9], v[160:163], v[208:211], v[6:9]
	v_mfma_f32_16x16x32_bf16 v[2:5], v[168:171], v[208:211], v[2:5]
	s_barrier
	s_setprio 0
	s_add_i32 s49, s49, 2
	s_add_u32 s18, s18, 0x100
	s_addc_u32 s19, s19, 0
	s_add_u32 s9, s9, 0x100
	s_addc_u32 s11, s11, 0
	s_cmp_gt_u32 s49, 5
	s_cbranch_scc0 .LBB0_712
	s_and_b64 vcc, exec, s[6:7]
	s_cbranch_vccz .LBB0_715
	s_barrier

.LBB0_837:
	s_add_u32 s0, s18, 0xfff80080
	s_addc_u32 s1, s19, -1
	s_add_i32 s33, 0, 0x10000
	s_cmp_eq_u32 s59, 28
	s_cselect_b32 s23, s11, s1
	s_cselect_b32 s22, s38, s0
	v_add_u32_e32 v140, s33, v143
	s_cselect_b32 s21, s9, s58
	s_cselect_b32 s20, s39, s49
	s_add_i32 s55, 0, 0x14000
	ds_read_b128 v[146:149], v140
	ds_read_b128 v[150:153], v140 offset:1024
	ds_read_b128 v[154:157], v140 offset:2048
	ds_read_b128 v[158:161], v140 offset:3072
	v_add_u32_e32 v140, s55, v143
	ds_read_b128 v[162:165], v140
	ds_read_b128 v[166:169], v140 offset:1024
	ds_read_b128 v[170:173], v140 offset:2048
	ds_read_b128 v[174:177], v140 offset:3072
	s_add_i32 m0, s27, 0xc000
	ds_read_b128 v[178:181], v145
	ds_read_b128 v[182:185], v145 offset:1024
	ds_read_b128 v[186:189], v145 offset:2048
	ds_read_b128 v[190:193], v145 offset:3072
	ds_read_b128 v[194:197], v145 offset:4096
	ds_read_b128 v[198:201], v145 offset:5120
	ds_read_b128 v[208:211], v145 offset:6144
	ds_read_b128 v[212:215], v145 offset:7168
	global_load_lds_dwordx4 v136, s[18:19]
	s_add_i32 m0, s27, 0xe000
	s_nop 0
	global_load_lds_dwordx4 v138, s[18:19]
	s_waitcnt vmcnt(8)
	s_waitcnt lgkmcnt(0)
	s_setprio 1
	s_barrier
	v_mfma_f32_16x16x32_bf16 v[126:129], v[146:149], v[178:181], v[126:129]
	v_mfma_f32_16x16x32_bf16 v[118:121], v[154:157], v[178:181], v[118:121]
	v_mfma_f32_16x16x32_bf16 v[110:113], v[146:149], v[186:189], v[110:113]
	v_mfma_f32_16x16x32_bf16 v[102:105], v[154:157], v[186:189], v[102:105]
	v_mfma_f32_16x16x32_bf16 v[94:97], v[146:149], v[194:197], v[94:97]
	v_mfma_f32_16x16x32_bf16 v[86:89], v[154:157], v[194:197], v[86:89]
	v_mfma_f32_16x16x32_bf16 v[78:81], v[146:149], v[208:211], v[78:81]
	v_mfma_f32_16x16x32_bf16 v[70:73], v[154:157], v[208:211], v[70:73]
	v_mfma_f32_16x16x32_bf16 v[126:129], v[150:153], v[182:185], v[126:129]
	v_mfma_f32_16x16x32_bf16 v[118:121], v[158:161], v[182:185], v[118:121]
	v_mfma_f32_16x16x32_bf16 v[110:113], v[150:153], v[190:193], v[110:113]
	v_mfma_f32_16x16x32_bf16 v[102:105], v[158:161], v[190:193], v[102:105]
	v_mfma_f32_16x16x32_bf16 v[94:97], v[150:153], v[198:201], v[94:97]
	v_mfma_f32_16x16x32_bf16 v[86:89], v[158:161], v[198:201], v[86:89]
	v_mfma_f32_16x16x32_bf16 v[78:81], v[150:153], v[212:215], v[78:81]
	v_mfma_f32_16x16x32_bf16 v[70:73], v[158:161], v[212:215], v[70:73]
	s_setprio 0
	s_setprio 1
	v_mfma_f32_16x16x32_bf16 v[122:125], v[162:165], v[178:181], v[122:125]
	v_mfma_f32_16x16x32_bf16 v[114:117], v[170:173], v[178:181], v[114:117]
	v_mfma_f32_16x16x32_bf16 v[106:109], v[162:165], v[186:189], v[106:109]
	v_mfma_f32_16x16x32_bf16 v[98:101], v[170:173], v[186:189], v[98:101]
	v_mfma_f32_16x16x32_bf16 v[90:93], v[162:165], v[194:197], v[90:93]
	v_mfma_f32_16x16x32_bf16 v[82:85], v[170:173], v[194:197], v[82:85]
	v_mfma_f32_16x16x32_bf16 v[74:77], v[162:165], v[208:211], v[74:77]
	v_mfma_f32_16x16x32_bf16 v[66:69], v[170:173], v[208:211], v[66:69]
	v_mfma_f32_16x16x32_bf16 v[122:125], v[166:169], v[182:185], v[122:125]
	v_mfma_f32_16x16x32_bf16 v[114:117], v[174:177], v[182:185], v[114:117]
	v_mfma_f32_16x16x32_bf16 v[106:109], v[166:169], v[190:193], v[106:109]
	v_mfma_f32_16x16x32_bf16 v[98:101], v[174:177], v[190:193], v[98:101]
	v_mfma_f32_16x16x32_bf16 v[90:93], v[166:169], v[198:201], v[90:93]
	v_mfma_f32_16x16x32_bf16 v[82:85], v[174:177], v[198:201], v[82:85]
	v_mfma_f32_16x16x32_bf16 v[74:77], v[166:169], v[212:215], v[74:77]
	v_mfma_f32_16x16x32_bf16 v[66:69], v[174:177], v[212:215], v[66:69]
	s_barrier
	s_setprio 0
	s_add_i32 s0, s33, s26
	v_lshl_add_u64 v[140:141], s[20:21], 0, v[202:203]
	s_mov_b32 m0, s0
	ds_read_b128 v[178:181], v145 offset:16384
	ds_read_b128 v[182:185], v145 offset:17408
	ds_read_b128 v[186:189], v145 offset:18432
	ds_read_b128 v[190:193], v145 offset:19456
	ds_read_b128 v[194:197], v145 offset:20480
	ds_read_b128 v[198:201], v145 offset:21504
	ds_read_b128 v[208:211], v145 offset:22528
	ds_read_b128 v[212:215], v145 offset:23552
	global_load_lds_dwordx4 v[140:141], off
	s_add_i32 m0, s0, 0x2000
	s_add_u32 s0, s20, 0x80000
	v_lshl_add_u64 v[204:205], s[20:21], 0, v[130:131]
	s_addc_u32 s1, s21, 0
	s_add_i32 s33, s55, s26
	global_load_lds_dwordx4 v[204:205], off
	s_mov_b32 m0, s33
	v_lshl_add_u64 v[216:217], s[22:23], 0, v[132:133]
	global_load_lds_dwordx4 v202, s[0:1]
	s_add_i32 m0, s33, 0x2000
	s_nop 0
	global_load_lds_dwordx4 v130, s[0:1]
	v_lshl_add_u64 v[206:207], s[22:23], 0, v[134:135]
	s_mov_b32 m0, s27
	s_nop 0
	global_load_lds_dwordx4 v[206:207], off
	s_mov_b32 m0, s28
	s_nop 0
	global_load_lds_dwordx4 v[216:217], off
	s_waitcnt vmcnt(8)
	s_waitcnt lgkmcnt(0)
	s_setprio 1
	s_barrier
	v_mfma_f32_16x16x32_bf16 v[62:65], v[146:149], v[178:181], v[62:65]
	v_mfma_f32_16x16x32_bf16 v[54:57], v[154:157], v[178:181], v[54:57]
	v_mfma_f32_16x16x32_bf16 v[46:49], v[146:149], v[186:189], v[46:49]
	v_mfma_f32_16x16x32_bf16 v[38:41], v[154:157], v[186:189], v[38:41]
	v_mfma_f32_16x16x32_bf16 v[30:33], v[146:149], v[194:197], v[30:33]
	v_mfma_f32_16x16x32_bf16 v[22:25], v[154:157], v[194:197], v[22:25]
	v_mfma_f32_16x16x32_bf16 v[14:17], v[146:149], v[208:211], v[14:17]
	v_mfma_f32_16x16x32_bf16 v[6:9], v[154:157], v[208:211], v[6:9]
	v_mfma_f32_16x16x32_bf16 v[62:65], v[150:153], v[182:185], v[62:65]
	v_mfma_f32_16x16x32_bf16 v[54:57], v[158:161], v[182:185], v[54:57]
	v_mfma_f32_16x16x32_bf16 v[46:49], v[150:153], v[190:193], v[46:49]
	v_mfma_f32_16x16x32_bf16 v[38:41], v[158:161], v[190:193], v[38:41]
	v_mfma_f32_16x16x32_bf16 v[30:33], v[150:153], v[198:201], v[30:33]
	v_mfma_f32_16x16x32_bf16 v[22:25], v[158:161], v[198:201], v[22:25]
	v_mfma_f32_16x16x32_bf16 v[14:17], v[150:153], v[212:215], v[14:17]
	v_mfma_f32_16x16x32_bf16 v[6:9], v[158:161], v[212:215], v[6:9]
	s_setprio 0
	s_setprio 1
	v_mfma_f32_16x16x32_bf16 v[58:61], v[162:165], v[178:181], v[58:61]
	v_mfma_f32_16x16x32_bf16 v[50:53], v[170:173], v[178:181], v[50:53]
	v_mfma_f32_16x16x32_bf16 v[42:45], v[162:165], v[186:189], v[42:45]
	v_mfma_f32_16x16x32_bf16 v[34:37], v[170:173], v[186:189], v[34:37]
	v_mfma_f32_16x16x32_bf16 v[26:29], v[162:165], v[194:197], v[26:29]
	v_mfma_f32_16x16x32_bf16 v[18:21], v[170:173], v[194:197], v[18:21]
	v_mfma_f32_16x16x32_bf16 v[10:13], v[162:165], v[208:211], v[10:13]
	v_mfma_f32_16x16x32_bf16 v[2:5], v[170:173], v[208:211], v[2:5]
	v_mfma_f32_16x16x32_bf16 v[58:61], v[166:169], v[182:185], v[58:61]
	v_mfma_f32_16x16x32_bf16 v[50:53], v[174:177], v[182:185], v[50:53]
	v_mfma_f32_16x16x32_bf16 v[42:45], v[166:169], v[190:193], v[42:45]
	v_mfma_f32_16x16x32_bf16 v[34:37], v[174:177], v[190:193], v[34:37]
	v_mfma_f32_16x16x32_bf16 v[26:29], v[166:169], v[198:201], v[26:29]
	v_mfma_f32_16x16x32_bf16 v[18:21], v[174:177], v[198:201], v[18:21]
	v_mfma_f32_16x16x32_bf16 v[10:13], v[166:169], v[212:215], v[10:13]
	v_mfma_f32_16x16x32_bf16 v[2:5], v[174:177], v[212:215], v[2:5]
	s_barrier
	s_setprio 0
	s_add_i32 s33, 0, 0x18000
	s_add_i32 s55, 0, 0x1c000
	v_add_u32_e32 v158, s33, v143
	v_add_u32_e32 v174, s55, v143
	ds_read_b128 v[146:149], v158
	ds_read_b128 v[150:153], v158 offset:1024
	ds_read_b128 v[154:157], v158 offset:2048
	ds_read_b128 v[158:161], v158 offset:3072
	ds_read_b128 v[162:165], v174
	ds_read_b128 v[166:169], v174 offset:1024
	ds_read_b128 v[170:173], v174 offset:2048
	ds_read_b128 v[174:177], v174 offset:3072
	s_add_u32 s0, s22, 0x80000
	s_addc_u32 s1, s23, 0
	s_mov_b32 m0, s29
	ds_read_b128 v[178:181], v145 offset:32768
	ds_read_b128 v[182:185], v145 offset:33792
	ds_read_b128 v[186:189], v145 offset:34816
	ds_read_b128 v[190:193], v145 offset:35840
	ds_read_b128 v[194:197], v145 offset:36864
	ds_read_b128 v[198:201], v145 offset:37888
	ds_read_b128 v[208:211], v145 offset:38912
	ds_read_b128 v[212:215], v145 offset:39936
	global_load_lds_dwordx4 v134, s[0:1]
	s_mov_b32 m0, s30
	s_nop 0
	global_load_lds_dwordx4 v132, s[0:1]
	s_waitcnt vmcnt(8)
	s_waitcnt lgkmcnt(0)
	s_setprio 1
	s_barrier
	v_mfma_f32_16x16x32_bf16 v[126:129], v[146:149], v[178:181], v[126:129]
	v_mfma_f32_16x16x32_bf16 v[118:121], v[154:157], v[178:181], v[118:121]
	v_mfma_f32_16x16x32_bf16 v[110:113], v[146:149], v[186:189], v[110:113]
	v_mfma_f32_16x16x32_bf16 v[102:105], v[154:157], v[186:189], v[102:105]
	v_mfma_f32_16x16x32_bf16 v[94:97], v[146:149], v[194:197], v[94:97]
	v_mfma_f32_16x16x32_bf16 v[86:89], v[154:157], v[194:197], v[86:89]
	v_mfma_f32_16x16x32_bf16 v[78:81], v[146:149], v[208:211], v[78:81]
	v_mfma_f32_16x16x32_bf16 v[70:73], v[154:157], v[208:211], v[70:73]
	v_mfma_f32_16x16x32_bf16 v[126:129], v[150:153], v[182:185], v[126:129]
	v_mfma_f32_16x16x32_bf16 v[118:121], v[158:161], v[182:185], v[118:121]
	v_mfma_f32_16x16x32_bf16 v[110:113], v[150:153], v[190:193], v[110:113]
	v_mfma_f32_16x16x32_bf16 v[102:105], v[158:161], v[190:193], v[102:105]
	v_mfma_f32_16x16x32_bf16 v[94:97], v[150:153], v[198:201], v[94:97]
	v_mfma_f32_16x16x32_bf16 v[86:89], v[158:161], v[198:201], v[86:89]
	v_mfma_f32_16x16x32_bf16 v[78:81], v[150:153], v[212:215], v[78:81]
	v_mfma_f32_16x16x32_bf16 v[70:73], v[158:161], v[212:215], v[70:73]
	s_setprio 0
	s_setprio 1
	v_mfma_f32_16x16x32_bf16 v[122:125], v[162:165], v[178:181], v[122:125]
	v_mfma_f32_16x16x32_bf16 v[114:117], v[170:173], v[178:181], v[114:117]
	v_mfma_f32_16x16x32_bf16 v[106:109], v[162:165], v[186:189], v[106:109]
	v_mfma_f32_16x16x32_bf16 v[98:101], v[170:173], v[186:189], v[98:101]
	v_mfma_f32_16x16x32_bf16 v[90:93], v[162:165], v[194:197], v[90:93]
	v_mfma_f32_16x16x32_bf16 v[82:85], v[170:173], v[194:197], v[82:85]
	v_mfma_f32_16x16x32_bf16 v[74:77], v[162:165], v[208:211], v[74:77]
	v_mfma_f32_16x16x32_bf16 v[66:69], v[170:173], v[208:211], v[66:69]
	v_mfma_f32_16x16x32_bf16 v[122:125], v[166:169], v[182:185], v[122:125]
	v_mfma_f32_16x16x32_bf16 v[114:117], v[174:177], v[182:185], v[114:117]
	v_mfma_f32_16x16x32_bf16 v[106:109], v[166:169], v[190:193], v[106:109]
	v_mfma_f32_16x16x32_bf16 v[98:101], v[174:177], v[190:193], v[98:101]
	v_mfma_f32_16x16x32_bf16 v[90:93], v[166:169], v[198:201], v[90:93]
	v_mfma_f32_16x16x32_bf16 v[82:85], v[174:177], v[198:201], v[82:85]
	v_mfma_f32_16x16x32_bf16 v[74:77], v[166:169], v[212:215], v[74:77]
	v_mfma_f32_16x16x32_bf16 v[66:69], v[174:177], v[212:215], v[66:69]
	s_barrier
	s_setprio 0
	s_add_i32 s0, s33, s26
	v_lshl_add_u64 v[140:141], v[140:141], 0, s[80:81]
	s_mov_b32 m0, s0
	ds_read_b128 v[178:181], v145 offset:49152
	ds_read_b128 v[182:185], v145 offset:50176
	ds_read_b128 v[186:189], v145 offset:51200
	ds_read_b128 v[190:193], v145 offset:52224
	ds_read_b128 v[194:197], v145 offset:53248
	ds_read_b128 v[198:201], v145 offset:54272
	ds_read_b128 v[208:211], v145 offset:55296
	ds_read_b128 v[212:215], v145 offset:56320
	global_load_lds_dwordx4 v[140:141], off
	s_add_i32 m0, s0, 0x2000
	s_add_u32 s0, s20, 0x80080
	v_lshl_add_u64 v[140:141], v[204:205], 0, s[80:81]
	s_addc_u32 s1, s21, 0
	s_add_i32 s20, s55, s26
	global_load_lds_dwordx4 v[140:141], off
	s_mov_b32 m0, s20
	s_nop 0
	global_load_lds_dwordx4 v202, s[0:1]
	s_add_i32 m0, s20, 0x2000
	s_nop 0
	global_load_lds_dwordx4 v130, s[0:1]
	v_lshl_add_u64 v[140:141], v[206:207], 0, s[80:81]
	s_mov_b32 m0, s31
	s_nop 0
	global_load_lds_dwordx4 v[140:141], off
	v_lshl_add_u64 v[140:141], v[216:217], 0, s[80:81]
	s_mov_b32 m0, s34
	s_nop 0
	global_load_lds_dwordx4 v[140:141], off
	s_waitcnt vmcnt(8)
	s_waitcnt lgkmcnt(0)
	s_setprio 1
	s_barrier
	v_mfma_f32_16x16x32_bf16 v[62:65], v[146:149], v[178:181], v[62:65]
	v_mfma_f32_16x16x32_bf16 v[54:57], v[154:157], v[178:181], v[54:57]
	v_mfma_f32_16x16x32_bf16 v[46:49], v[146:149], v[186:189], v[46:49]
	v_mfma_f32_16x16x32_bf16 v[38:41], v[154:157], v[186:189], v[38:41]
	v_mfma_f32_16x16x32_bf16 v[30:33], v[146:149], v[194:197], v[30:33]
	v_mfma_f32_16x16x32_bf16 v[22:25], v[154:157], v[194:197], v[22:25]
	v_mfma_f32_16x16x32_bf16 v[14:17], v[146:149], v[208:211], v[14:17]
	v_mfma_f32_16x16x32_bf16 v[6:9], v[154:157], v[208:211], v[6:9]
	v_mfma_f32_16x16x32_bf16 v[62:65], v[150:153], v[182:185], v[62:65]
	v_mfma_f32_16x16x32_bf16 v[54:57], v[158:161], v[182:185], v[54:57]
	v_mfma_f32_16x16x32_bf16 v[46:49], v[150:153], v[190:193], v[46:49]
	v_mfma_f32_16x16x32_bf16 v[38:41], v[158:161], v[190:193], v[38:41]
	v_mfma_f32_16x16x32_bf16 v[30:33], v[150:153], v[198:201], v[30:33]
	v_mfma_f32_16x16x32_bf16 v[22:25], v[158:161], v[198:201], v[22:25]
	v_mfma_f32_16x16x32_bf16 v[14:17], v[150:153], v[212:215], v[14:17]
	v_mfma_f32_16x16x32_bf16 v[6:9], v[158:161], v[212:215], v[6:9]
	s_setprio 0
	s_setprio 1
	v_mfma_f32_16x16x32_bf16 v[58:61], v[162:165], v[178:181], v[58:61]
	v_mfma_f32_16x16x32_bf16 v[50:53], v[170:173], v[178:181], v[50:53]
	v_mfma_f32_16x16x32_bf16 v[42:45], v[162:165], v[186:189], v[42:45]
	v_mfma_f32_16x16x32_bf16 v[34:37], v[170:173], v[186:189], v[34:37]
	v_mfma_f32_16x16x32_bf16 v[26:29], v[162:165], v[194:197], v[26:29]
	v_mfma_f32_16x16x32_bf16 v[18:21], v[170:173], v[194:197], v[18:21]
	v_mfma_f32_16x16x32_bf16 v[10:13], v[162:165], v[208:211], v[10:13]
	v_mfma_f32_16x16x32_bf16 v[2:5], v[170:173], v[208:211], v[2:5]
	v_mfma_f32_16x16x32_bf16 v[58:61], v[166:169], v[182:185], v[58:61]
	v_mfma_f32_16x16x32_bf16 v[50:53], v[174:177], v[182:185], v[50:53]
	v_mfma_f32_16x16x32_bf16 v[42:45], v[166:169], v[190:193], v[42:45]
	v_mfma_f32_16x16x32_bf16 v[34:37], v[174:177], v[190:193], v[34:37]
	v_mfma_f32_16x16x32_bf16 v[26:29], v[166:169], v[198:201], v[26:29]
	v_mfma_f32_16x16x32_bf16 v[18:21], v[174:177], v[198:201], v[18:21]
	v_mfma_f32_16x16x32_bf16 v[10:13], v[166:169], v[212:215], v[10:13]
	v_mfma_f32_16x16x32_bf16 v[2:5], v[174:177], v[212:215], v[2:5]
	s_barrier
	s_setprio 0
	s_add_i32 s59, s59, 2
	s_add_u32 s18, s18, 0x100
	s_addc_u32 s19, s19, 0
	s_add_u32 s49, s49, 0x100
	s_addc_u32 s58, s58, 0
	s_cmp_gt_u32 s59, 29
	s_cbranch_scc0 .LBB0_837
	s_and_b64 vcc, exec, s[6:7]
	s_cbranch_vccz .LBB0_840
	s_barrier

.LBB0_970:
	s_add_u32 s16, s2, 0x100
	s_addc_u32 s17, s3, 0
	s_add_i32 s0, 0, 0x10000
	s_cmpk_eq_i32 s59, 0x54
	s_cselect_b32 s21, s7, s17
	s_cselect_b32 s20, s6, s16
	s_cselect_b32 s19, s15, s58
	s_cselect_b32 s18, s14, s49
	s_add_i32 s33, 0, 0x14000
	v_add_u32_e32 v98, s0, v205
	v_add_u32_e32 v134, s33, v205
	ds_read_b128 v[78:81], v98
	ds_read_b128 v[82:85], v98 offset:1024
	ds_read_b128 v[94:97], v98 offset:2048
	ds_read_b128 v[98:101], v98 offset:3072
	ds_read_b128 v[106:109], v134
	ds_read_b128 v[110:113], v134 offset:1024
	ds_read_b128 v[126:129], v134 offset:2048
	ds_read_b128 v[134:137], v134 offset:3072
	s_add_i32 m0, s25, 0xc000
	ds_read_b128 v[146:149], v239
	ds_read_b128 v[158:161], v239 offset:1024
	ds_read_b128 v[166:169], v239 offset:2048
	ds_read_b128 v[174:177], v239 offset:3072
	ds_read_b128 v[178:181], v239 offset:4096
	ds_read_b128 v[182:185], v239 offset:5120
	ds_read_b128 v[186:189], v239 offset:6144
	ds_read_b128 v[190:193], v239 offset:7168
	global_load_lds_dwordx4 v214, s[2:3]
	s_add_i32 m0, s25, 0xe000
	s_nop 0
	global_load_lds_dwordx4 v216, s[2:3]
	s_waitcnt vmcnt(8)
	s_waitcnt lgkmcnt(0)
	s_setprio 1
	s_barrier
	v_mfma_f32_16x16x32_bf16 v[170:173], v[78:81], v[146:149], v[170:173]
	v_mfma_f32_16x16x32_bf16 v[162:165], v[94:97], v[146:149], v[162:165]
	v_mfma_f32_16x16x32_bf16 v[142:145], v[78:81], v[166:169], v[142:145]
	v_mfma_f32_16x16x32_bf16 v[138:141], v[94:97], v[166:169], v[138:141]
	v_mfma_f32_16x16x32_bf16 v[118:121], v[78:81], v[178:181], v[118:121]
	v_mfma_f32_16x16x32_bf16 v[114:117], v[94:97], v[178:181], v[114:117]
	v_mfma_f32_16x16x32_bf16 v[86:89], v[78:81], v[186:189], v[86:89]
	v_mfma_f32_16x16x32_bf16 v[74:77], v[94:97], v[186:189], v[74:77]
	v_mfma_f32_16x16x32_bf16 v[170:173], v[82:85], v[158:161], v[170:173]
	v_mfma_f32_16x16x32_bf16 v[162:165], v[98:101], v[158:161], v[162:165]
	v_mfma_f32_16x16x32_bf16 v[142:145], v[82:85], v[174:177], v[142:145]
	v_mfma_f32_16x16x32_bf16 v[138:141], v[98:101], v[174:177], v[138:141]
	v_mfma_f32_16x16x32_bf16 v[118:121], v[82:85], v[182:185], v[118:121]
	v_mfma_f32_16x16x32_bf16 v[114:117], v[98:101], v[182:185], v[114:117]
	v_mfma_f32_16x16x32_bf16 v[86:89], v[82:85], v[190:193], v[86:89]
	v_mfma_f32_16x16x32_bf16 v[74:77], v[98:101], v[190:193], v[74:77]
	s_setprio 0
	s_setprio 1
	v_mfma_f32_16x16x32_bf16 v[154:157], v[106:109], v[146:149], v[154:157]
	v_mfma_f32_16x16x32_bf16 v[130:133], v[106:109], v[166:169], v[130:133]
	v_mfma_f32_16x16x32_bf16 v[122:125], v[126:129], v[166:169], v[122:125]
	v_mfma_f32_16x16x32_bf16 v[102:105], v[106:109], v[178:181], v[102:105]
	v_mfma_f32_16x16x32_bf16 v[90:93], v[126:129], v[178:181], v[90:93]
	v_mfma_f32_16x16x32_bf16 v[70:73], v[106:109], v[186:189], v[70:73]
	v_mfma_f32_16x16x32_bf16 v[66:69], v[126:129], v[186:189], v[66:69]
	v_mfma_f32_16x16x32_bf16 v[154:157], v[110:113], v[158:161], v[154:157]
	v_mfma_f32_16x16x32_bf16 v[146:149], v[126:129], v[146:149], v[150:153]
	v_mfma_f32_16x16x32_bf16 v[130:133], v[110:113], v[174:177], v[130:133]
	v_mfma_f32_16x16x32_bf16 v[122:125], v[134:137], v[174:177], v[122:125]
	v_mfma_f32_16x16x32_bf16 v[102:105], v[110:113], v[182:185], v[102:105]
	v_mfma_f32_16x16x32_bf16 v[90:93], v[134:137], v[182:185], v[90:93]
	v_mfma_f32_16x16x32_bf16 v[70:73], v[110:113], v[190:193], v[70:73]
	v_mfma_f32_16x16x32_bf16 v[66:69], v[134:137], v[190:193], v[66:69]
	v_mfma_f32_16x16x32_bf16 v[146:149], v[134:137], v[158:161], v[146:149]
	s_barrier
	s_setprio 0
	s_add_i32 s0, s0, s24
	v_lshl_add_u64 v[194:195], s[18:19], 0, v[202:203]
	s_mov_b32 m0, s0
	ds_read_b128 v[150:153], v239 offset:16384
	ds_read_b128 v[158:161], v239 offset:17408
	ds_read_b128 v[166:169], v239 offset:18432
	ds_read_b128 v[174:177], v239 offset:19456
	ds_read_b128 v[178:181], v239 offset:20480
	ds_read_b128 v[182:185], v239 offset:21504
	ds_read_b128 v[186:189], v239 offset:22528
	ds_read_b128 v[190:193], v239 offset:23552
	global_load_lds_dwordx4 v[194:195], off
	s_add_i32 m0, s0, 0x2000
	s_add_u32 s0, s18, 0x160000
	v_lshl_add_u64 v[196:197], s[18:19], 0, v[208:209]
	s_addc_u32 s1, s19, 0
	s_add_i32 s2, s33, s24
	global_load_lds_dwordx4 v[196:197], off
	s_mov_b32 m0, s2
	v_lshl_add_u64 v[200:201], s[20:21], 0, v[210:211]
	global_load_lds_dwordx4 v202, s[0:1]
	s_add_i32 m0, s2, 0x2000
	s_nop 0
	global_load_lds_dwordx4 v208, s[0:1]
	v_lshl_add_u64 v[198:199], s[20:21], 0, v[212:213]
	s_mov_b32 m0, s25
	s_nop 0
	global_load_lds_dwordx4 v[198:199], off
	s_mov_b32 m0, s26
	s_nop 0
	global_load_lds_dwordx4 v[200:201], off
	s_waitcnt vmcnt(8)
	s_waitcnt lgkmcnt(0)
	s_setprio 1
	s_barrier
	v_mfma_f32_16x16x32_bf16 v[62:65], v[78:81], v[150:153], v[62:65]
	v_mfma_f32_16x16x32_bf16 v[58:61], v[94:97], v[150:153], v[58:61]
	v_mfma_f32_16x16x32_bf16 v[46:49], v[78:81], v[166:169], v[46:49]
	v_mfma_f32_16x16x32_bf16 v[42:45], v[94:97], v[166:169], v[42:45]
	v_mfma_f32_16x16x32_bf16 v[30:33], v[78:81], v[178:181], v[30:33]
	v_mfma_f32_16x16x32_bf16 v[26:29], v[94:97], v[178:181], v[26:29]
	v_mfma_f32_16x16x32_bf16 v[14:17], v[78:81], v[186:189], v[14:17]
	v_mfma_f32_16x16x32_bf16 v[10:13], v[94:97], v[186:189], v[10:13]
	v_mfma_f32_16x16x32_bf16 v[62:65], v[82:85], v[158:161], v[62:65]
	v_mfma_f32_16x16x32_bf16 v[58:61], v[98:101], v[158:161], v[58:61]
	v_mfma_f32_16x16x32_bf16 v[46:49], v[82:85], v[174:177], v[46:49]
	v_mfma_f32_16x16x32_bf16 v[42:45], v[98:101], v[174:177], v[42:45]
	v_mfma_f32_16x16x32_bf16 v[30:33], v[82:85], v[182:185], v[30:33]
	v_mfma_f32_16x16x32_bf16 v[26:29], v[98:101], v[182:185], v[26:29]
	v_mfma_f32_16x16x32_bf16 v[14:17], v[82:85], v[190:193], v[14:17]
	v_mfma_f32_16x16x32_bf16 v[10:13], v[98:101], v[190:193], v[10:13]
	s_setprio 0
	s_setprio 1
	v_mfma_f32_16x16x32_bf16 v[54:57], v[106:109], v[150:153], v[54:57]
	v_mfma_f32_16x16x32_bf16 v[50:53], v[126:129], v[150:153], v[50:53]
	v_mfma_f32_16x16x32_bf16 v[38:41], v[106:109], v[166:169], v[38:41]
	v_mfma_f32_16x16x32_bf16 v[34:37], v[126:129], v[166:169], v[34:37]
	v_mfma_f32_16x16x32_bf16 v[22:25], v[106:109], v[178:181], v[22:25]
	v_mfma_f32_16x16x32_bf16 v[18:21], v[126:129], v[178:181], v[18:21]
	v_mfma_f32_16x16x32_bf16 v[6:9], v[106:109], v[186:189], v[6:9]
	v_mfma_f32_16x16x32_bf16 v[2:5], v[126:129], v[186:189], v[2:5]
	v_mfma_f32_16x16x32_bf16 v[54:57], v[110:113], v[158:161], v[54:57]
	v_mfma_f32_16x16x32_bf16 v[50:53], v[134:137], v[158:161], v[50:53]
	v_mfma_f32_16x16x32_bf16 v[38:41], v[110:113], v[174:177], v[38:41]
	v_mfma_f32_16x16x32_bf16 v[34:37], v[134:137], v[174:177], v[34:37]
	v_mfma_f32_16x16x32_bf16 v[22:25], v[110:113], v[182:185], v[22:25]
	v_mfma_f32_16x16x32_bf16 v[18:21], v[134:137], v[182:185], v[18:21]
	v_mfma_f32_16x16x32_bf16 v[6:9], v[110:113], v[190:193], v[6:9]
	v_mfma_f32_16x16x32_bf16 v[2:5], v[134:137], v[190:193], v[2:5]
	s_barrier
	s_setprio 0
	s_add_i32 s2, 0, 0x18000
	s_add_i32 s3, 0, 0x1c000
	v_add_u32_e32 v98, s2, v205
	v_add_u32_e32 v134, s3, v205
	ds_read_b128 v[78:81], v98
	ds_read_b128 v[82:85], v98 offset:1024
	ds_read_b128 v[94:97], v98 offset:2048
	ds_read_b128 v[98:101], v98 offset:3072
	ds_read_b128 v[106:109], v134
	ds_read_b128 v[110:113], v134 offset:1024
	ds_read_b128 v[126:129], v134 offset:2048
	ds_read_b128 v[134:137], v134 offset:3072
	s_add_u32 s0, s20, 0x160000
	s_addc_u32 s1, s21, 0
	s_mov_b32 m0, s27
	ds_read_b128 v[150:153], v239 offset:32768
	ds_read_b128 v[158:161], v239 offset:33792
	ds_read_b128 v[166:169], v239 offset:34816
	ds_read_b128 v[174:177], v239 offset:35840
	ds_read_b128 v[178:181], v239 offset:36864
	ds_read_b128 v[182:185], v239 offset:37888
	ds_read_b128 v[186:189], v239 offset:38912
	ds_read_b128 v[190:193], v239 offset:39936
	global_load_lds_dwordx4 v212, s[0:1]
	s_mov_b32 m0, s28
	s_nop 0
	global_load_lds_dwordx4 v210, s[0:1]
	s_waitcnt vmcnt(8)
	s_waitcnt lgkmcnt(0)
	s_setprio 1
	s_barrier
	v_mfma_f32_16x16x32_bf16 v[170:173], v[78:81], v[150:153], v[170:173]
	v_mfma_f32_16x16x32_bf16 v[162:165], v[94:97], v[150:153], v[162:165]
	v_mfma_f32_16x16x32_bf16 v[142:145], v[78:81], v[166:169], v[142:145]
	v_mfma_f32_16x16x32_bf16 v[138:141], v[94:97], v[166:169], v[138:141]
	v_mfma_f32_16x16x32_bf16 v[118:121], v[78:81], v[178:181], v[118:121]
	v_mfma_f32_16x16x32_bf16 v[114:117], v[94:97], v[178:181], v[114:117]
	v_mfma_f32_16x16x32_bf16 v[86:89], v[78:81], v[186:189], v[86:89]
	v_mfma_f32_16x16x32_bf16 v[74:77], v[94:97], v[186:189], v[74:77]
	v_mfma_f32_16x16x32_bf16 v[170:173], v[82:85], v[158:161], v[170:173]
	v_mfma_f32_16x16x32_bf16 v[162:165], v[98:101], v[158:161], v[162:165]
	v_mfma_f32_16x16x32_bf16 v[142:145], v[82:85], v[174:177], v[142:145]
	v_mfma_f32_16x16x32_bf16 v[138:141], v[98:101], v[174:177], v[138:141]
	v_mfma_f32_16x16x32_bf16 v[118:121], v[82:85], v[182:185], v[118:121]
	v_mfma_f32_16x16x32_bf16 v[114:117], v[98:101], v[182:185], v[114:117]
	v_mfma_f32_16x16x32_bf16 v[86:89], v[82:85], v[190:193], v[86:89]
	v_mfma_f32_16x16x32_bf16 v[74:77], v[98:101], v[190:193], v[74:77]
	s_setprio 0
	s_setprio 1
	v_mfma_f32_16x16x32_bf16 v[154:157], v[106:109], v[150:153], v[154:157]
	v_mfma_f32_16x16x32_bf16 v[146:149], v[126:129], v[150:153], v[146:149]
	v_mfma_f32_16x16x32_bf16 v[130:133], v[106:109], v[166:169], v[130:133]
	v_mfma_f32_16x16x32_bf16 v[122:125], v[126:129], v[166:169], v[122:125]
	v_mfma_f32_16x16x32_bf16 v[102:105], v[106:109], v[178:181], v[102:105]
	v_mfma_f32_16x16x32_bf16 v[90:93], v[126:129], v[178:181], v[90:93]
	v_mfma_f32_16x16x32_bf16 v[70:73], v[106:109], v[186:189], v[70:73]
	v_mfma_f32_16x16x32_bf16 v[66:69], v[126:129], v[186:189], v[66:69]
	v_mfma_f32_16x16x32_bf16 v[154:157], v[110:113], v[158:161], v[154:157]
	v_mfma_f32_16x16x32_bf16 v[150:153], v[134:137], v[158:161], v[146:149]
	v_mfma_f32_16x16x32_bf16 v[130:133], v[110:113], v[174:177], v[130:133]
	v_mfma_f32_16x16x32_bf16 v[122:125], v[134:137], v[174:177], v[122:125]
	v_mfma_f32_16x16x32_bf16 v[102:105], v[110:113], v[182:185], v[102:105]
	v_mfma_f32_16x16x32_bf16 v[90:93], v[134:137], v[182:185], v[90:93]
	v_mfma_f32_16x16x32_bf16 v[70:73], v[110:113], v[190:193], v[70:73]
	v_mfma_f32_16x16x32_bf16 v[66:69], v[134:137], v[190:193], v[66:69]
	s_barrier
	s_setprio 0
	s_add_i32 s0, s2, s24
	v_lshl_add_u64 v[194:195], v[194:195], 0, s[80:81]
	s_mov_b32 m0, s0
	ds_read_b128 v[146:149], v239 offset:49152
	ds_read_b128 v[158:161], v239 offset:50176
	ds_read_b128 v[166:169], v239 offset:51200
	ds_read_b128 v[174:177], v239 offset:52224
	ds_read_b128 v[178:181], v239 offset:53248
	ds_read_b128 v[182:185], v239 offset:54272
	ds_read_b128 v[186:189], v239 offset:55296
	ds_read_b128 v[190:193], v239 offset:56320
	global_load_lds_dwordx4 v[194:195], off
	s_add_i32 m0, s0, 0x2000
	s_add_u32 s0, s18, 0x160080
	v_lshl_add_u64 v[194:195], v[196:197], 0, s[80:81]
	s_addc_u32 s1, s19, 0
	s_add_i32 s2, s3, s24
	global_load_lds_dwordx4 v[194:195], off
	s_mov_b32 m0, s2
	s_nop 0
	global_load_lds_dwordx4 v202, s[0:1]
	s_add_i32 m0, s2, 0x2000
	s_nop 0
	global_load_lds_dwordx4 v208, s[0:1]
	v_lshl_add_u64 v[194:195], v[198:199], 0, s[80:81]
	s_mov_b32 m0, s31
	s_nop 0
	global_load_lds_dwordx4 v[194:195], off
	v_lshl_add_u64 v[194:195], v[200:201], 0, s[80:81]
	s_mov_b32 m0, s34
	s_nop 0
	global_load_lds_dwordx4 v[194:195], off
	s_waitcnt vmcnt(8)
	s_waitcnt lgkmcnt(0)
	s_setprio 1
	s_barrier
	v_mfma_f32_16x16x32_bf16 v[62:65], v[78:81], v[146:149], v[62:65]
	v_mfma_f32_16x16x32_bf16 v[58:61], v[94:97], v[146:149], v[58:61]
	v_mfma_f32_16x16x32_bf16 v[46:49], v[78:81], v[166:169], v[46:49]
	v_mfma_f32_16x16x32_bf16 v[42:45], v[94:97], v[166:169], v[42:45]
	v_mfma_f32_16x16x32_bf16 v[30:33], v[78:81], v[178:181], v[30:33]
	v_mfma_f32_16x16x32_bf16 v[26:29], v[94:97], v[178:181], v[26:29]
	v_mfma_f32_16x16x32_bf16 v[14:17], v[78:81], v[186:189], v[14:17]
	v_mfma_f32_16x16x32_bf16 v[10:13], v[94:97], v[186:189], v[10:13]
	v_mfma_f32_16x16x32_bf16 v[62:65], v[82:85], v[158:161], v[62:65]
	v_mfma_f32_16x16x32_bf16 v[58:61], v[98:101], v[158:161], v[58:61]
	v_mfma_f32_16x16x32_bf16 v[46:49], v[82:85], v[174:177], v[46:49]
	v_mfma_f32_16x16x32_bf16 v[42:45], v[98:101], v[174:177], v[42:45]
	v_mfma_f32_16x16x32_bf16 v[30:33], v[82:85], v[182:185], v[30:33]
	v_mfma_f32_16x16x32_bf16 v[26:29], v[98:101], v[182:185], v[26:29]
	v_mfma_f32_16x16x32_bf16 v[14:17], v[82:85], v[190:193], v[14:17]
	v_mfma_f32_16x16x32_bf16 v[10:13], v[98:101], v[190:193], v[10:13]
	s_setprio 0
	s_setprio 1
	v_mfma_f32_16x16x32_bf16 v[54:57], v[106:109], v[146:149], v[54:57]
	v_mfma_f32_16x16x32_bf16 v[50:53], v[126:129], v[146:149], v[50:53]
	v_mfma_f32_16x16x32_bf16 v[38:41], v[106:109], v[166:169], v[38:41]
	v_mfma_f32_16x16x32_bf16 v[34:37], v[126:129], v[166:169], v[34:37]
	v_mfma_f32_16x16x32_bf16 v[22:25], v[106:109], v[178:181], v[22:25]
	v_mfma_f32_16x16x32_bf16 v[18:21], v[126:129], v[178:181], v[18:21]
	v_mfma_f32_16x16x32_bf16 v[6:9], v[106:109], v[186:189], v[6:9]
	v_mfma_f32_16x16x32_bf16 v[2:5], v[126:129], v[186:189], v[2:5]
	v_mfma_f32_16x16x32_bf16 v[54:57], v[110:113], v[158:161], v[54:57]
	v_mfma_f32_16x16x32_bf16 v[50:53], v[134:137], v[158:161], v[50:53]
	v_mfma_f32_16x16x32_bf16 v[38:41], v[110:113], v[174:177], v[38:41]
	v_mfma_f32_16x16x32_bf16 v[34:37], v[134:137], v[174:177], v[34:37]
	v_mfma_f32_16x16x32_bf16 v[22:25], v[110:113], v[182:185], v[22:25]
	v_mfma_f32_16x16x32_bf16 v[18:21], v[134:137], v[182:185], v[18:21]
	v_mfma_f32_16x16x32_bf16 v[6:9], v[110:113], v[190:193], v[6:9]
	v_mfma_f32_16x16x32_bf16 v[2:5], v[134:137], v[190:193], v[2:5]
	s_barrier
	s_setprio 0
	s_add_i32 s59, s59, 2
	s_add_u32 s49, s49, 0x100
	s_addc_u32 s58, s58, 0
	s_cmpk_gt_u32 s59, 0x55
	s_mov_b64 s[2:3], s[16:17]
	s_cbranch_scc0 .LBB0_970
	s_and_b64 vcc, exec, s[10:11]
	s_cbranch_vccz .LBB0_973
	s_barrier

.LBB0_990:
	s_add_u32 s4, s2, 0x100
	s_addc_u32 s5, s3, 0
	s_add_i32 s0, 0, 0x10000
	s_cmp_eq_u32 s59, 4
	s_cselect_b32 s21, s15, s5
	s_cselect_b32 s20, s14, s4
	s_cselect_b32 s19, s17, s58
	s_cselect_b32 s18, s16, s49
	s_add_i32 s33, 0, 0x14000
	v_add_u32_e32 v152, s0, v136
	v_add_u32_e32 v168, s33, v136
	ds_read_b128 v[140:143], v152
	ds_read_b128 v[144:147], v152 offset:1024
	ds_read_b128 v[148:151], v152 offset:2048
	ds_read_b128 v[152:155], v152 offset:3072
	ds_read_b128 v[156:159], v168
	ds_read_b128 v[160:163], v168 offset:1024
	ds_read_b128 v[164:167], v168 offset:2048
	ds_read_b128 v[168:171], v168 offset:3072
	s_add_i32 m0, s25, 0xc000
	ds_read_b128 v[172:175], v139
	ds_read_b128 v[176:179], v139 offset:1024
	ds_read_b128 v[180:183], v139 offset:2048
	ds_read_b128 v[184:187], v139 offset:3072
	ds_read_b128 v[188:191], v139 offset:4096
	ds_read_b128 v[192:195], v139 offset:5120
	ds_read_b128 v[196:199], v139 offset:6144
	ds_read_b128 v[208:211], v139 offset:7168
	global_load_lds_dwordx4 v132, s[2:3]
	s_add_i32 m0, s25, 0xe000
	s_nop 0
	global_load_lds_dwordx4 v134, s[2:3]
	s_waitcnt vmcnt(8)
	s_waitcnt lgkmcnt(0)
	s_setprio 1
	s_barrier
	v_mfma_f32_16x16x32_bf16 v[126:129], v[140:143], v[172:175], v[126:129]
	v_mfma_f32_16x16x32_bf16 v[122:125], v[148:151], v[172:175], v[122:125]
	v_mfma_f32_16x16x32_bf16 v[118:121], v[140:143], v[180:183], v[118:121]
	v_mfma_f32_16x16x32_bf16 v[114:117], v[148:151], v[180:183], v[114:117]
	v_mfma_f32_16x16x32_bf16 v[106:109], v[140:143], v[188:191], v[106:109]
	v_mfma_f32_16x16x32_bf16 v[98:101], v[148:151], v[188:191], v[98:101]
	v_mfma_f32_16x16x32_bf16 v[90:93], v[140:143], v[196:199], v[90:93]
	v_mfma_f32_16x16x32_bf16 v[82:85], v[148:151], v[196:199], v[82:85]
	v_mfma_f32_16x16x32_bf16 v[126:129], v[144:147], v[176:179], v[126:129]
	v_mfma_f32_16x16x32_bf16 v[122:125], v[152:155], v[176:179], v[122:125]
	v_mfma_f32_16x16x32_bf16 v[118:121], v[144:147], v[184:187], v[118:121]
	v_mfma_f32_16x16x32_bf16 v[114:117], v[152:155], v[184:187], v[114:117]
	v_mfma_f32_16x16x32_bf16 v[106:109], v[144:147], v[192:195], v[106:109]
	v_mfma_f32_16x16x32_bf16 v[98:101], v[152:155], v[192:195], v[98:101]
	v_mfma_f32_16x16x32_bf16 v[90:93], v[144:147], v[208:211], v[90:93]
	v_mfma_f32_16x16x32_bf16 v[82:85], v[152:155], v[208:211], v[82:85]
	s_setprio 0
	s_setprio 1
	v_mfma_f32_16x16x32_bf16 v[110:113], v[156:159], v[172:175], v[110:113]
	v_mfma_f32_16x16x32_bf16 v[102:105], v[164:167], v[172:175], v[102:105]
	v_mfma_f32_16x16x32_bf16 v[94:97], v[156:159], v[180:183], v[94:97]
	v_mfma_f32_16x16x32_bf16 v[86:89], v[164:167], v[180:183], v[86:89]
	v_mfma_f32_16x16x32_bf16 v[78:81], v[156:159], v[188:191], v[78:81]
	v_mfma_f32_16x16x32_bf16 v[74:77], v[164:167], v[188:191], v[74:77]
	v_mfma_f32_16x16x32_bf16 v[70:73], v[156:159], v[196:199], v[70:73]
	v_mfma_f32_16x16x32_bf16 v[66:69], v[164:167], v[196:199], v[66:69]
	v_mfma_f32_16x16x32_bf16 v[110:113], v[160:163], v[176:179], v[110:113]
	v_mfma_f32_16x16x32_bf16 v[102:105], v[168:171], v[176:179], v[102:105]
	v_mfma_f32_16x16x32_bf16 v[94:97], v[160:163], v[184:187], v[94:97]
	v_mfma_f32_16x16x32_bf16 v[86:89], v[168:171], v[184:187], v[86:89]
	v_mfma_f32_16x16x32_bf16 v[78:81], v[160:163], v[192:195], v[78:81]
	v_mfma_f32_16x16x32_bf16 v[74:77], v[168:171], v[192:195], v[74:77]
	v_mfma_f32_16x16x32_bf16 v[70:73], v[160:163], v[208:211], v[70:73]
	v_mfma_f32_16x16x32_bf16 v[66:69], v[168:171], v[208:211], v[66:69]
	s_barrier
	s_setprio 0
	s_add_i32 s0, s0, s24
	v_lshl_add_u64 v[200:201], s[18:19], 0, v[202:203]
	s_mov_b32 m0, s0
	ds_read_b128 v[172:175], v139 offset:16384
	ds_read_b128 v[176:179], v139 offset:17408
	ds_read_b128 v[180:183], v139 offset:18432
	ds_read_b128 v[184:187], v139 offset:19456
	ds_read_b128 v[188:191], v139 offset:20480
	ds_read_b128 v[192:195], v139 offset:21504
	ds_read_b128 v[196:199], v139 offset:22528
	ds_read_b128 v[208:211], v139 offset:23552
	global_load_lds_dwordx4 v[200:201], off
	s_add_i32 m0, s0, 0x2000
	s_add_u32 s0, s18, 0x160000
	v_lshl_add_u64 v[204:205], s[18:19], 0, v[130:131]
	s_addc_u32 s1, s19, 0
	s_add_i32 s2, s33, s24
	global_load_lds_dwordx4 v[204:205], off
	s_mov_b32 m0, s2
	v_lshl_add_u64 v[212:213], s[20:21], 0, v[130:131]
	global_load_lds_dwordx4 v202, s[0:1]
	s_add_i32 m0, s2, 0x2000
	s_nop 0
	global_load_lds_dwordx4 v130, s[0:1]
	v_lshl_add_u64 v[206:207], s[20:21], 0, v[202:203]
	s_mov_b32 m0, s25
	s_nop 0
	global_load_lds_dwordx4 v[206:207], off
	s_mov_b32 m0, s26
	s_nop 0
	global_load_lds_dwordx4 v[212:213], off
	s_waitcnt vmcnt(8)
	s_waitcnt lgkmcnt(0)
	s_setprio 1
	s_barrier
	v_mfma_f32_16x16x32_bf16 v[62:65], v[140:143], v[172:175], v[62:65]
	v_mfma_f32_16x16x32_bf16 v[58:61], v[148:151], v[172:175], v[58:61]
	v_mfma_f32_16x16x32_bf16 v[54:57], v[140:143], v[180:183], v[54:57]
	v_mfma_f32_16x16x32_bf16 v[50:53], v[148:151], v[180:183], v[50:53]
	v_mfma_f32_16x16x32_bf16 v[38:41], v[140:143], v[188:191], v[38:41]
	v_mfma_f32_16x16x32_bf16 v[34:37], v[148:151], v[188:191], v[34:37]
	v_mfma_f32_16x16x32_bf16 v[22:25], v[140:143], v[196:199], v[22:25]
	v_mfma_f32_16x16x32_bf16 v[18:21], v[148:151], v[196:199], v[18:21]
	v_mfma_f32_16x16x32_bf16 v[62:65], v[144:147], v[176:179], v[62:65]
	v_mfma_f32_16x16x32_bf16 v[58:61], v[152:155], v[176:179], v[58:61]
	v_mfma_f32_16x16x32_bf16 v[54:57], v[144:147], v[184:187], v[54:57]
	v_mfma_f32_16x16x32_bf16 v[50:53], v[152:155], v[184:187], v[50:53]
	v_mfma_f32_16x16x32_bf16 v[38:41], v[144:147], v[192:195], v[38:41]
	v_mfma_f32_16x16x32_bf16 v[34:37], v[152:155], v[192:195], v[34:37]
	v_mfma_f32_16x16x32_bf16 v[22:25], v[144:147], v[208:211], v[22:25]
	v_mfma_f32_16x16x32_bf16 v[18:21], v[152:155], v[208:211], v[18:21]
	s_setprio 0
	s_setprio 1
	v_mfma_f32_16x16x32_bf16 v[46:49], v[156:159], v[172:175], v[46:49]
	v_mfma_f32_16x16x32_bf16 v[42:45], v[164:167], v[172:175], v[42:45]
	v_mfma_f32_16x16x32_bf16 v[30:33], v[156:159], v[180:183], v[30:33]
	v_mfma_f32_16x16x32_bf16 v[26:29], v[164:167], v[180:183], v[26:29]
	v_mfma_f32_16x16x32_bf16 v[14:17], v[156:159], v[188:191], v[14:17]
	v_mfma_f32_16x16x32_bf16 v[10:13], v[164:167], v[188:191], v[10:13]
	v_mfma_f32_16x16x32_bf16 v[6:9], v[156:159], v[196:199], v[6:9]
	v_mfma_f32_16x16x32_bf16 v[2:5], v[164:167], v[196:199], v[2:5]
	v_mfma_f32_16x16x32_bf16 v[46:49], v[160:163], v[176:179], v[46:49]
	v_mfma_f32_16x16x32_bf16 v[42:45], v[168:171], v[176:179], v[42:45]
	v_mfma_f32_16x16x32_bf16 v[30:33], v[160:163], v[184:187], v[30:33]
	v_mfma_f32_16x16x32_bf16 v[26:29], v[168:171], v[184:187], v[26:29]
	v_mfma_f32_16x16x32_bf16 v[14:17], v[160:163], v[192:195], v[14:17]
	v_mfma_f32_16x16x32_bf16 v[10:13], v[168:171], v[192:195], v[10:13]
	v_mfma_f32_16x16x32_bf16 v[6:9], v[160:163], v[208:211], v[6:9]
	v_mfma_f32_16x16x32_bf16 v[2:5], v[168:171], v[208:211], v[2:5]
	s_barrier
	s_setprio 0
	s_add_i32 s2, 0, 0x18000
	s_add_i32 s3, 0, 0x1c000
	v_add_u32_e32 v152, s2, v136
	v_add_u32_e32 v168, s3, v136
	ds_read_b128 v[140:143], v152
	ds_read_b128 v[144:147], v152 offset:1024
	ds_read_b128 v[148:151], v152 offset:2048
	ds_read_b128 v[152:155], v152 offset:3072
	ds_read_b128 v[156:159], v168
	ds_read_b128 v[160:163], v168 offset:1024
	ds_read_b128 v[164:167], v168 offset:2048
	ds_read_b128 v[168:171], v168 offset:3072
	s_add_u32 s0, s20, 0x160000
	s_addc_u32 s1, s21, 0
	s_mov_b32 m0, s27
	ds_read_b128 v[172:175], v139 offset:32768
	ds_read_b128 v[176:179], v139 offset:33792
	ds_read_b128 v[180:183], v139 offset:34816
	ds_read_b128 v[184:187], v139 offset:35840
	ds_read_b128 v[188:191], v139 offset:36864
	ds_read_b128 v[192:195], v139 offset:37888
	ds_read_b128 v[196:199], v139 offset:38912
	ds_read_b128 v[208:211], v139 offset:39936
	global_load_lds_dwordx4 v202, s[0:1]
	s_mov_b32 m0, s28
	s_nop 0
	global_load_lds_dwordx4 v130, s[0:1]
	s_waitcnt vmcnt(8)
	s_waitcnt lgkmcnt(0)
	s_setprio 1
	s_barrier
	v_mfma_f32_16x16x32_bf16 v[126:129], v[140:143], v[172:175], v[126:129]
	v_mfma_f32_16x16x32_bf16 v[122:125], v[148:151], v[172:175], v[122:125]
	v_mfma_f32_16x16x32_bf16 v[118:121], v[140:143], v[180:183], v[118:121]
	v_mfma_f32_16x16x32_bf16 v[114:117], v[148:151], v[180:183], v[114:117]
	v_mfma_f32_16x16x32_bf16 v[106:109], v[140:143], v[188:191], v[106:109]
	v_mfma_f32_16x16x32_bf16 v[98:101], v[148:151], v[188:191], v[98:101]
	v_mfma_f32_16x16x32_bf16 v[90:93], v[140:143], v[196:199], v[90:93]
	v_mfma_f32_16x16x32_bf16 v[82:85], v[148:151], v[196:199], v[82:85]
	v_mfma_f32_16x16x32_bf16 v[126:129], v[144:147], v[176:179], v[126:129]
	v_mfma_f32_16x16x32_bf16 v[122:125], v[152:155], v[176:179], v[122:125]
	v_mfma_f32_16x16x32_bf16 v[118:121], v[144:147], v[184:187], v[118:121]
	v_mfma_f32_16x16x32_bf16 v[114:117], v[152:155], v[184:187], v[114:117]
	v_mfma_f32_16x16x32_bf16 v[106:109], v[144:147], v[192:195], v[106:109]
	v_mfma_f32_16x16x32_bf16 v[98:101], v[152:155], v[192:195], v[98:101]
	v_mfma_f32_16x16x32_bf16 v[90:93], v[144:147], v[208:211], v[90:93]
	v_mfma_f32_16x16x32_bf16 v[82:85], v[152:155], v[208:211], v[82:85]
	s_setprio 0
	s_setprio 1
	v_mfma_f32_16x16x32_bf16 v[110:113], v[156:159], v[172:175], v[110:113]
	v_mfma_f32_16x16x32_bf16 v[102:105], v[164:167], v[172:175], v[102:105]
	v_mfma_f32_16x16x32_bf16 v[94:97], v[156:159], v[180:183], v[94:97]
	v_mfma_f32_16x16x32_bf16 v[86:89], v[164:167], v[180:183], v[86:89]
	v_mfma_f32_16x16x32_bf16 v[78:81], v[156:159], v[188:191], v[78:81]
	v_mfma_f32_16x16x32_bf16 v[74:77], v[164:167], v[188:191], v[74:77]
	v_mfma_f32_16x16x32_bf16 v[70:73], v[156:159], v[196:199], v[70:73]
	v_mfma_f32_16x16x32_bf16 v[66:69], v[164:167], v[196:199], v[66:69]
	v_mfma_f32_16x16x32_bf16 v[110:113], v[160:163], v[176:179], v[110:113]
	v_mfma_f32_16x16x32_bf16 v[102:105], v[168:171], v[176:179], v[102:105]
	v_mfma_f32_16x16x32_bf16 v[94:97], v[160:163], v[184:187], v[94:97]
	v_mfma_f32_16x16x32_bf16 v[86:89], v[168:171], v[184:187], v[86:89]
	v_mfma_f32_16x16x32_bf16 v[78:81], v[160:163], v[192:195], v[78:81]
	v_mfma_f32_16x16x32_bf16 v[74:77], v[168:171], v[192:195], v[74:77]
	v_mfma_f32_16x16x32_bf16 v[70:73], v[160:163], v[208:211], v[70:73]
	v_mfma_f32_16x16x32_bf16 v[66:69], v[168:171], v[208:211], v[66:69]
	s_barrier
	s_setprio 0
	s_add_i32 s0, s2, s24
	v_lshl_add_u64 v[200:201], v[200:201], 0, s[80:81]
	s_mov_b32 m0, s0
	ds_read_b128 v[172:175], v139 offset:49152
	ds_read_b128 v[176:179], v139 offset:50176
	ds_read_b128 v[180:183], v139 offset:51200
	ds_read_b128 v[184:187], v139 offset:52224
	ds_read_b128 v[188:191], v139 offset:53248
	ds_read_b128 v[192:195], v139 offset:54272
	ds_read_b128 v[196:199], v139 offset:55296
	ds_read_b128 v[208:211], v139 offset:56320
	global_load_lds_dwordx4 v[200:201], off
	s_add_i32 m0, s0, 0x2000
	s_add_u32 s0, s18, 0x160080
	v_lshl_add_u64 v[200:201], v[204:205], 0, s[80:81]
	s_addc_u32 s1, s19, 0
	s_add_i32 s2, s3, s24
	global_load_lds_dwordx4 v[200:201], off
	s_mov_b32 m0, s2
	s_nop 0
	global_load_lds_dwordx4 v202, s[0:1]
	s_add_i32 m0, s2, 0x2000
	s_nop 0
	global_load_lds_dwordx4 v130, s[0:1]
	v_lshl_add_u64 v[200:201], v[206:207], 0, s[80:81]
	s_mov_b32 m0, s29
	s_nop 0
	global_load_lds_dwordx4 v[200:201], off
	v_lshl_add_u64 v[200:201], v[212:213], 0, s[80:81]
	s_mov_b32 m0, s30
	s_nop 0
	global_load_lds_dwordx4 v[200:201], off
	s_waitcnt vmcnt(8)
	s_waitcnt lgkmcnt(0)
	s_setprio 1
	s_barrier
	v_mfma_f32_16x16x32_bf16 v[62:65], v[140:143], v[172:175], v[62:65]
	v_mfma_f32_16x16x32_bf16 v[58:61], v[148:151], v[172:175], v[58:61]
	v_mfma_f32_16x16x32_bf16 v[54:57], v[140:143], v[180:183], v[54:57]
	v_mfma_f32_16x16x32_bf16 v[50:53], v[148:151], v[180:183], v[50:53]
	v_mfma_f32_16x16x32_bf16 v[38:41], v[140:143], v[188:191], v[38:41]
	v_mfma_f32_16x16x32_bf16 v[34:37], v[148:151], v[188:191], v[34:37]
	v_mfma_f32_16x16x32_bf16 v[22:25], v[140:143], v[196:199], v[22:25]
	v_mfma_f32_16x16x32_bf16 v[18:21], v[148:151], v[196:199], v[18:21]
	v_mfma_f32_16x16x32_bf16 v[62:65], v[144:147], v[176:179], v[62:65]
	v_mfma_f32_16x16x32_bf16 v[58:61], v[152:155], v[176:179], v[58:61]
	v_mfma_f32_16x16x32_bf16 v[54:57], v[144:147], v[184:187], v[54:57]
	v_mfma_f32_16x16x32_bf16 v[50:53], v[152:155], v[184:187], v[50:53]
	v_mfma_f32_16x16x32_bf16 v[38:41], v[144:147], v[192:195], v[38:41]
	v_mfma_f32_16x16x32_bf16 v[34:37], v[152:155], v[192:195], v[34:37]
	v_mfma_f32_16x16x32_bf16 v[22:25], v[144:147], v[208:211], v[22:25]
	v_mfma_f32_16x16x32_bf16 v[18:21], v[152:155], v[208:211], v[18:21]
	s_setprio 0
	s_setprio 1
	v_mfma_f32_16x16x32_bf16 v[46:49], v[156:159], v[172:175], v[46:49]
	v_mfma_f32_16x16x32_bf16 v[42:45], v[164:167], v[172:175], v[42:45]
	v_mfma_f32_16x16x32_bf16 v[30:33], v[156:159], v[180:183], v[30:33]
	v_mfma_f32_16x16x32_bf16 v[26:29], v[164:167], v[180:183], v[26:29]
	v_mfma_f32_16x16x32_bf16 v[14:17], v[156:159], v[188:191], v[14:17]
	v_mfma_f32_16x16x32_bf16 v[10:13], v[164:167], v[188:191], v[10:13]
	v_mfma_f32_16x16x32_bf16 v[6:9], v[156:159], v[196:199], v[6:9]
	v_mfma_f32_16x16x32_bf16 v[2:5], v[164:167], v[196:199], v[2:5]
	v_mfma_f32_16x16x32_bf16 v[46:49], v[160:163], v[176:179], v[46:49]
	v_mfma_f32_16x16x32_bf16 v[42:45], v[168:171], v[176:179], v[42:45]
	v_mfma_f32_16x16x32_bf16 v[30:33], v[160:163], v[184:187], v[30:33]
	v_mfma_f32_16x16x32_bf16 v[26:29], v[168:171], v[184:187], v[26:29]
	v_mfma_f32_16x16x32_bf16 v[14:17], v[160:163], v[192:195], v[14:17]
	v_mfma_f32_16x16x32_bf16 v[10:13], v[168:171], v[192:195], v[10:13]
	v_mfma_f32_16x16x32_bf16 v[6:9], v[160:163], v[208:211], v[6:9]
	v_mfma_f32_16x16x32_bf16 v[2:5], v[168:171], v[208:211], v[2:5]
	s_barrier
	s_setprio 0
	s_add_i32 s59, s59, 2
	s_add_u32 s49, s49, 0x100
	s_addc_u32 s58, s58, 0
	s_cmp_gt_u32 s59, 5
	s_mov_b64 s[2:3], s[4:5]
	s_cbranch_scc0 .LBB0_990
	s_and_b64 vcc, exec, s[10:11]
	s_cbranch_vccz .LBB0_993
	s_barrier

.LBB0_1115:
	s_add_u32 s0, s22, 0xfff80080
	s_addc_u32 s1, s23, -1
	s_add_i32 s33, 0, 0x10000
	s_cmp_eq_u32 s58, 28
	s_cselect_b32 s5, s17, s1
	s_cselect_b32 s4, s39, s0
	v_add_u32_e32 v143, s33, v145
	s_cselect_b32 s3, s15, s49
	s_cselect_b32 s2, s40, s41
	s_add_i32 s55, 0, 0x14000
	ds_read_b128 v[148:151], v143
	ds_read_b128 v[152:155], v143 offset:1024
	ds_read_b128 v[156:159], v143 offset:2048
	ds_read_b128 v[160:163], v143 offset:3072
	v_add_u32_e32 v143, s55, v145
	ds_read_b128 v[164:167], v143
	ds_read_b128 v[168:171], v143 offset:1024
	ds_read_b128 v[172:175], v143 offset:2048
	ds_read_b128 v[176:179], v143 offset:3072
	s_add_i32 m0, s27, 0xc000
	ds_read_b128 v[180:183], v147
	ds_read_b128 v[184:187], v147 offset:1024
	ds_read_b128 v[188:191], v147 offset:2048
	ds_read_b128 v[192:195], v147 offset:3072
	ds_read_b128 v[196:199], v147 offset:4096
	ds_read_b128 v[208:211], v147 offset:5120
	ds_read_b128 v[212:215], v147 offset:6144
	ds_read_b128 v[216:219], v147 offset:7168
	global_load_lds_dwordx4 v138, s[22:23]
	s_add_i32 m0, s27, 0xe000
	s_nop 0
	global_load_lds_dwordx4 v140, s[22:23]
	s_waitcnt vmcnt(8)
	s_waitcnt lgkmcnt(0)
	s_setprio 1
	s_barrier
	v_mfma_f32_16x16x32_bf16 v[126:129], v[148:151], v[180:183], v[126:129]
	v_mfma_f32_16x16x32_bf16 v[122:125], v[156:159], v[180:183], v[122:125]
	v_mfma_f32_16x16x32_bf16 v[110:113], v[148:151], v[188:191], v[110:113]
	v_mfma_f32_16x16x32_bf16 v[106:109], v[156:159], v[188:191], v[106:109]
	v_mfma_f32_16x16x32_bf16 v[94:97], v[148:151], v[196:199], v[94:97]
	v_mfma_f32_16x16x32_bf16 v[90:93], v[156:159], v[196:199], v[90:93]
	v_mfma_f32_16x16x32_bf16 v[78:81], v[148:151], v[212:215], v[78:81]
	v_mfma_f32_16x16x32_bf16 v[74:77], v[156:159], v[212:215], v[74:77]
	v_mfma_f32_16x16x32_bf16 v[126:129], v[152:155], v[184:187], v[126:129]
	v_mfma_f32_16x16x32_bf16 v[122:125], v[160:163], v[184:187], v[122:125]
	v_mfma_f32_16x16x32_bf16 v[110:113], v[152:155], v[192:195], v[110:113]
	v_mfma_f32_16x16x32_bf16 v[106:109], v[160:163], v[192:195], v[106:109]
	v_mfma_f32_16x16x32_bf16 v[94:97], v[152:155], v[208:211], v[94:97]
	v_mfma_f32_16x16x32_bf16 v[90:93], v[160:163], v[208:211], v[90:93]
	v_mfma_f32_16x16x32_bf16 v[78:81], v[152:155], v[216:219], v[78:81]
	v_mfma_f32_16x16x32_bf16 v[74:77], v[160:163], v[216:219], v[74:77]
	s_setprio 0
	s_setprio 1
	v_mfma_f32_16x16x32_bf16 v[118:121], v[164:167], v[180:183], v[118:121]
	v_mfma_f32_16x16x32_bf16 v[114:117], v[172:175], v[180:183], v[114:117]
	v_mfma_f32_16x16x32_bf16 v[102:105], v[164:167], v[188:191], v[102:105]
	v_mfma_f32_16x16x32_bf16 v[98:101], v[172:175], v[188:191], v[98:101]
	v_mfma_f32_16x16x32_bf16 v[86:89], v[164:167], v[196:199], v[86:89]
	v_mfma_f32_16x16x32_bf16 v[82:85], v[172:175], v[196:199], v[82:85]
	v_mfma_f32_16x16x32_bf16 v[70:73], v[164:167], v[212:215], v[70:73]
	v_mfma_f32_16x16x32_bf16 v[66:69], v[172:175], v[212:215], v[66:69]
	v_mfma_f32_16x16x32_bf16 v[118:121], v[168:171], v[184:187], v[118:121]
	v_mfma_f32_16x16x32_bf16 v[114:117], v[176:179], v[184:187], v[114:117]
	v_mfma_f32_16x16x32_bf16 v[102:105], v[168:171], v[192:195], v[102:105]
	v_mfma_f32_16x16x32_bf16 v[98:101], v[176:179], v[192:195], v[98:101]
	v_mfma_f32_16x16x32_bf16 v[86:89], v[168:171], v[208:211], v[86:89]
	v_mfma_f32_16x16x32_bf16 v[82:85], v[176:179], v[208:211], v[82:85]
	v_mfma_f32_16x16x32_bf16 v[70:73], v[168:171], v[216:219], v[70:73]
	v_mfma_f32_16x16x32_bf16 v[66:69], v[176:179], v[216:219], v[66:69]
	s_barrier
	s_setprio 0
	s_add_i32 s0, s33, s26
	v_lshl_add_u64 v[200:201], s[2:3], 0, v[134:135]
	s_mov_b32 m0, s0
	ds_read_b128 v[180:183], v147 offset:16384
	ds_read_b128 v[184:187], v147 offset:17408
	ds_read_b128 v[188:191], v147 offset:18432
	ds_read_b128 v[192:195], v147 offset:19456
	ds_read_b128 v[196:199], v147 offset:20480
	ds_read_b128 v[208:211], v147 offset:21504
	ds_read_b128 v[212:215], v147 offset:22528
	ds_read_b128 v[216:219], v147 offset:23552
	global_load_lds_dwordx4 v[200:201], off
	s_add_i32 m0, s0, 0x2000
	s_add_u32 s0, s2, 0x80000
	v_lshl_add_u64 v[204:205], s[2:3], 0, v[130:131]
	s_addc_u32 s1, s3, 0
	s_add_i32 s33, s55, s26
	global_load_lds_dwordx4 v[204:205], off
	s_mov_b32 m0, s33
	v_lshl_add_u64 v[220:221], s[4:5], 0, v[132:133]
	global_load_lds_dwordx4 v134, s[0:1]
	s_add_i32 m0, s33, 0x2000
	s_nop 0
	global_load_lds_dwordx4 v130, s[0:1]
	v_lshl_add_u64 v[206:207], s[4:5], 0, v[136:137]
	s_mov_b32 m0, s27
	s_nop 0
	global_load_lds_dwordx4 v[206:207], off
	s_mov_b32 m0, s28
	s_nop 0
	global_load_lds_dwordx4 v[220:221], off
	s_waitcnt vmcnt(8)
	s_waitcnt lgkmcnt(0)
	s_setprio 1
	s_barrier
	v_mfma_f32_16x16x32_bf16 v[62:65], v[148:151], v[180:183], v[62:65]
	v_mfma_f32_16x16x32_bf16 v[58:61], v[156:159], v[180:183], v[58:61]
	v_mfma_f32_16x16x32_bf16 v[46:49], v[148:151], v[188:191], v[46:49]
	v_mfma_f32_16x16x32_bf16 v[42:45], v[156:159], v[188:191], v[42:45]
	v_mfma_f32_16x16x32_bf16 v[30:33], v[148:151], v[196:199], v[30:33]
	v_mfma_f32_16x16x32_bf16 v[26:29], v[156:159], v[196:199], v[26:29]
	v_mfma_f32_16x16x32_bf16 v[14:17], v[148:151], v[212:215], v[14:17]
	v_mfma_f32_16x16x32_bf16 v[10:13], v[156:159], v[212:215], v[10:13]
	v_mfma_f32_16x16x32_bf16 v[62:65], v[152:155], v[184:187], v[62:65]
	v_mfma_f32_16x16x32_bf16 v[58:61], v[160:163], v[184:187], v[58:61]
	v_mfma_f32_16x16x32_bf16 v[46:49], v[152:155], v[192:195], v[46:49]
	v_mfma_f32_16x16x32_bf16 v[42:45], v[160:163], v[192:195], v[42:45]
	v_mfma_f32_16x16x32_bf16 v[30:33], v[152:155], v[208:211], v[30:33]
	v_mfma_f32_16x16x32_bf16 v[26:29], v[160:163], v[208:211], v[26:29]
	v_mfma_f32_16x16x32_bf16 v[14:17], v[152:155], v[216:219], v[14:17]
	v_mfma_f32_16x16x32_bf16 v[10:13], v[160:163], v[216:219], v[10:13]
	s_setprio 0
	s_setprio 1
	v_mfma_f32_16x16x32_bf16 v[54:57], v[164:167], v[180:183], v[54:57]
	v_mfma_f32_16x16x32_bf16 v[50:53], v[172:175], v[180:183], v[50:53]
	v_mfma_f32_16x16x32_bf16 v[38:41], v[164:167], v[188:191], v[38:41]
	v_mfma_f32_16x16x32_bf16 v[34:37], v[172:175], v[188:191], v[34:37]
	v_mfma_f32_16x16x32_bf16 v[22:25], v[164:167], v[196:199], v[22:25]
	v_mfma_f32_16x16x32_bf16 v[18:21], v[172:175], v[196:199], v[18:21]
	v_mfma_f32_16x16x32_bf16 v[6:9], v[164:167], v[212:215], v[6:9]
	v_mfma_f32_16x16x32_bf16 v[2:5], v[172:175], v[212:215], v[2:5]
	v_mfma_f32_16x16x32_bf16 v[54:57], v[168:171], v[184:187], v[54:57]
	v_mfma_f32_16x16x32_bf16 v[50:53], v[176:179], v[184:187], v[50:53]
	v_mfma_f32_16x16x32_bf16 v[38:41], v[168:171], v[192:195], v[38:41]
	v_mfma_f32_16x16x32_bf16 v[34:37], v[176:179], v[192:195], v[34:37]
	v_mfma_f32_16x16x32_bf16 v[22:25], v[168:171], v[208:211], v[22:25]
	v_mfma_f32_16x16x32_bf16 v[18:21], v[176:179], v[208:211], v[18:21]
	v_mfma_f32_16x16x32_bf16 v[6:9], v[168:171], v[216:219], v[6:9]
	v_mfma_f32_16x16x32_bf16 v[2:5], v[176:179], v[216:219], v[2:5]
	s_barrier
	s_setprio 0
	s_add_i32 s33, 0, 0x18000
	v_add_u32_e32 v143, s33, v145
	s_add_i32 s55, 0, 0x1c000
	ds_read_b128 v[148:151], v143
	ds_read_b128 v[152:155], v143 offset:1024
	ds_read_b128 v[156:159], v143 offset:2048
	ds_read_b128 v[160:163], v143 offset:3072
	v_add_u32_e32 v143, s55, v145
	ds_read_b128 v[164:167], v143
	ds_read_b128 v[168:171], v143 offset:1024
	ds_read_b128 v[172:175], v143 offset:2048
	ds_read_b128 v[176:179], v143 offset:3072
	s_add_u32 s0, s4, 0x80000
	s_addc_u32 s1, s5, 0
	s_mov_b32 m0, s29
	ds_read_b128 v[180:183], v147 offset:32768
	ds_read_b128 v[184:187], v147 offset:33792
	ds_read_b128 v[188:191], v147 offset:34816
	ds_read_b128 v[192:195], v147 offset:35840
	ds_read_b128 v[196:199], v147 offset:36864
	ds_read_b128 v[208:211], v147 offset:37888
	ds_read_b128 v[212:215], v147 offset:38912
	ds_read_b128 v[216:219], v147 offset:39936
	global_load_lds_dwordx4 v136, s[0:1]
	s_mov_b32 m0, s30
	s_nop 0
	global_load_lds_dwordx4 v132, s[0:1]
	s_waitcnt vmcnt(8)
	s_waitcnt lgkmcnt(0)
	s_setprio 1
	s_barrier
	v_mfma_f32_16x16x32_bf16 v[126:129], v[148:151], v[180:183], v[126:129]
	v_mfma_f32_16x16x32_bf16 v[122:125], v[156:159], v[180:183], v[122:125]
	v_mfma_f32_16x16x32_bf16 v[110:113], v[148:151], v[188:191], v[110:113]
	v_mfma_f32_16x16x32_bf16 v[106:109], v[156:159], v[188:191], v[106:109]
	v_mfma_f32_16x16x32_bf16 v[94:97], v[148:151], v[196:199], v[94:97]
	v_mfma_f32_16x16x32_bf16 v[90:93], v[156:159], v[196:199], v[90:93]
	v_mfma_f32_16x16x32_bf16 v[78:81], v[148:151], v[212:215], v[78:81]
	v_mfma_f32_16x16x32_bf16 v[74:77], v[156:159], v[212:215], v[74:77]
	v_mfma_f32_16x16x32_bf16 v[126:129], v[152:155], v[184:187], v[126:129]
	v_mfma_f32_16x16x32_bf16 v[122:125], v[160:163], v[184:187], v[122:125]
	v_mfma_f32_16x16x32_bf16 v[110:113], v[152:155], v[192:195], v[110:113]
	v_mfma_f32_16x16x32_bf16 v[106:109], v[160:163], v[192:195], v[106:109]
	v_mfma_f32_16x16x32_bf16 v[94:97], v[152:155], v[208:211], v[94:97]
	v_mfma_f32_16x16x32_bf16 v[90:93], v[160:163], v[208:211], v[90:93]
	v_mfma_f32_16x16x32_bf16 v[78:81], v[152:155], v[216:219], v[78:81]
	v_mfma_f32_16x16x32_bf16 v[74:77], v[160:163], v[216:219], v[74:77]
	s_setprio 0
	s_setprio 1
	v_mfma_f32_16x16x32_bf16 v[118:121], v[164:167], v[180:183], v[118:121]
	v_mfma_f32_16x16x32_bf16 v[114:117], v[172:175], v[180:183], v[114:117]
	v_mfma_f32_16x16x32_bf16 v[102:105], v[164:167], v[188:191], v[102:105]
	v_mfma_f32_16x16x32_bf16 v[98:101], v[172:175], v[188:191], v[98:101]
	v_mfma_f32_16x16x32_bf16 v[86:89], v[164:167], v[196:199], v[86:89]
	v_mfma_f32_16x16x32_bf16 v[82:85], v[172:175], v[196:199], v[82:85]
	v_mfma_f32_16x16x32_bf16 v[70:73], v[164:167], v[212:215], v[70:73]
	v_mfma_f32_16x16x32_bf16 v[66:69], v[172:175], v[212:215], v[66:69]
	v_mfma_f32_16x16x32_bf16 v[118:121], v[168:171], v[184:187], v[118:121]
	v_mfma_f32_16x16x32_bf16 v[114:117], v[176:179], v[184:187], v[114:117]
	v_mfma_f32_16x16x32_bf16 v[102:105], v[168:171], v[192:195], v[102:105]
	v_mfma_f32_16x16x32_bf16 v[98:101], v[176:179], v[192:195], v[98:101]
	v_mfma_f32_16x16x32_bf16 v[86:89], v[168:171], v[208:211], v[86:89]
	v_mfma_f32_16x16x32_bf16 v[82:85], v[176:179], v[208:211], v[82:85]
	v_mfma_f32_16x16x32_bf16 v[70:73], v[168:171], v[216:219], v[70:73]
	v_mfma_f32_16x16x32_bf16 v[66:69], v[176:179], v[216:219], v[66:69]
	s_barrier
	s_setprio 0
	s_add_i32 s0, s33, s26
	v_lshl_add_u64 v[200:201], v[200:201], 0, s[80:81]
	s_mov_b32 m0, s0
	ds_read_b128 v[180:183], v147 offset:49152
	ds_read_b128 v[184:187], v147 offset:50176
	ds_read_b128 v[188:191], v147 offset:51200
	ds_read_b128 v[192:195], v147 offset:52224
	ds_read_b128 v[196:199], v147 offset:53248
	ds_read_b128 v[208:211], v147 offset:54272
	ds_read_b128 v[212:215], v147 offset:55296
	ds_read_b128 v[216:219], v147 offset:56320
	global_load_lds_dwordx4 v[200:201], off
	s_add_i32 m0, s0, 0x2000
	s_add_u32 s0, s2, 0x80080
	v_lshl_add_u64 v[200:201], v[204:205], 0, s[80:81]
	s_addc_u32 s1, s3, 0
	s_add_i32 s2, s55, s26
	global_load_lds_dwordx4 v[200:201], off
	s_mov_b32 m0, s2
	s_nop 0
	global_load_lds_dwordx4 v134, s[0:1]
	s_add_i32 m0, s2, 0x2000
	s_nop 0
	global_load_lds_dwordx4 v130, s[0:1]
	v_lshl_add_u64 v[200:201], v[206:207], 0, s[80:81]
	s_mov_b32 m0, s34
	s_nop 0
	global_load_lds_dwordx4 v[200:201], off
	v_lshl_add_u64 v[200:201], v[220:221], 0, s[80:81]
	s_mov_b32 m0, s35
	s_nop 0
	global_load_lds_dwordx4 v[200:201], off
	s_waitcnt vmcnt(8)
	s_waitcnt lgkmcnt(0)
	s_setprio 1
	s_barrier
	v_mfma_f32_16x16x32_bf16 v[62:65], v[148:151], v[180:183], v[62:65]
	v_mfma_f32_16x16x32_bf16 v[58:61], v[156:159], v[180:183], v[58:61]
	v_mfma_f32_16x16x32_bf16 v[46:49], v[148:151], v[188:191], v[46:49]
	v_mfma_f32_16x16x32_bf16 v[42:45], v[156:159], v[188:191], v[42:45]
	v_mfma_f32_16x16x32_bf16 v[30:33], v[148:151], v[196:199], v[30:33]
	v_mfma_f32_16x16x32_bf16 v[26:29], v[156:159], v[196:199], v[26:29]
	v_mfma_f32_16x16x32_bf16 v[14:17], v[148:151], v[212:215], v[14:17]
	v_mfma_f32_16x16x32_bf16 v[10:13], v[156:159], v[212:215], v[10:13]
	v_mfma_f32_16x16x32_bf16 v[62:65], v[152:155], v[184:187], v[62:65]
	v_mfma_f32_16x16x32_bf16 v[58:61], v[160:163], v[184:187], v[58:61]
	v_mfma_f32_16x16x32_bf16 v[46:49], v[152:155], v[192:195], v[46:49]
	v_mfma_f32_16x16x32_bf16 v[42:45], v[160:163], v[192:195], v[42:45]
	v_mfma_f32_16x16x32_bf16 v[30:33], v[152:155], v[208:211], v[30:33]
	v_mfma_f32_16x16x32_bf16 v[26:29], v[160:163], v[208:211], v[26:29]
	v_mfma_f32_16x16x32_bf16 v[14:17], v[152:155], v[216:219], v[14:17]
	v_mfma_f32_16x16x32_bf16 v[10:13], v[160:163], v[216:219], v[10:13]
	s_setprio 0
	s_setprio 1
	v_mfma_f32_16x16x32_bf16 v[54:57], v[164:167], v[180:183], v[54:57]
	v_mfma_f32_16x16x32_bf16 v[50:53], v[172:175], v[180:183], v[50:53]
	v_mfma_f32_16x16x32_bf16 v[38:41], v[164:167], v[188:191], v[38:41]
	v_mfma_f32_16x16x32_bf16 v[34:37], v[172:175], v[188:191], v[34:37]
	v_mfma_f32_16x16x32_bf16 v[22:25], v[164:167], v[196:199], v[22:25]
	v_mfma_f32_16x16x32_bf16 v[18:21], v[172:175], v[196:199], v[18:21]
	v_mfma_f32_16x16x32_bf16 v[6:9], v[164:167], v[212:215], v[6:9]
	v_mfma_f32_16x16x32_bf16 v[2:5], v[172:175], v[212:215], v[2:5]
	v_mfma_f32_16x16x32_bf16 v[54:57], v[168:171], v[184:187], v[54:57]
	v_mfma_f32_16x16x32_bf16 v[50:53], v[176:179], v[184:187], v[50:53]
	v_mfma_f32_16x16x32_bf16 v[38:41], v[168:171], v[192:195], v[38:41]
	v_mfma_f32_16x16x32_bf16 v[34:37], v[176:179], v[192:195], v[34:37]
	v_mfma_f32_16x16x32_bf16 v[22:25], v[168:171], v[208:211], v[22:25]
	v_mfma_f32_16x16x32_bf16 v[18:21], v[176:179], v[208:211], v[18:21]
	v_mfma_f32_16x16x32_bf16 v[6:9], v[168:171], v[216:219], v[6:9]
	v_mfma_f32_16x16x32_bf16 v[2:5], v[176:179], v[216:219], v[2:5]
	s_barrier
	s_setprio 0
	s_add_i32 s58, s58, 2
	s_add_u32 s22, s22, 0x100
	s_addc_u32 s23, s23, 0
	s_add_u32 s41, s41, 0x100
	s_addc_u32 s49, s49, 0
	s_cmp_gt_u32 s58, 29
	s_cbranch_scc0 .LBB0_1115
	s_and_b64 vcc, exec, s[10:11]
	s_cbranch_vccz .LBB0_1118
	s_barrier

.LBB0_1242:
	s_add_u32 s28, s18, s4
	s_addc_u32 s29, s19, s5
	s_add_u32 s24, s28, 0x100
	s_addc_u32 s25, s29, 0
	s_and_b64 s[0:1], s[2:3], exec
	s_cselect_b32 s25, s49, s25
	s_cselect_b32 s24, s58, s24
	s_add_u32 s0, s20, s4
	s_addc_u32 s1, s21, s5
	s_add_u32 s4, s0, 0x100
	s_addc_u32 s5, s1, 0
	s_add_i32 s55, 0, 0x10000
	s_and_b64 s[0:1], s[2:3], exec
	s_cselect_b32 s27, s59, s5
	s_cselect_b32 s26, s60, s4
	s_add_i32 s0, 0, 0x14000
	s_add_u32 s30, s28, 0x20080
	s_addc_u32 s31, s29, 0
	s_add_i32 s57, s55, s36
	s_add_i32 m0, s37, 0xc000
	s_add_i32 s1, s37, 0xe000
	s_add_i32 s63, s57, 0x2000
	v_add_u32_e32 v138, s55, v141
	s_add_u32 s28, s26, 0x10000
	ds_read_b128 v[144:147], v138
	ds_read_b128 v[148:151], v138 offset:1024
	ds_read_b128 v[152:155], v138 offset:2048
	ds_read_b128 v[156:159], v138 offset:3072
	v_add_u32_e32 v138, s0, v141
	s_addc_u32 s29, s27, 0
	s_add_i32 s33, s0, s36
	ds_read_b128 v[160:163], v138
	ds_read_b128 v[164:167], v138 offset:1024
	ds_read_b128 v[168:171], v138 offset:2048
	ds_read_b128 v[172:175], v138 offset:3072
	s_add_i32 s56, s33, 0x2000
	s_add_i32 vcc_lo, 0, 0x18000
	s_add_i32 vcc_hi, 0, 0x1c000
	s_add_u32 s4, s24, 0x20000
	s_addc_u32 s5, s25, 0
	s_add_i32 s61, vcc_lo, s36
	s_add_i32 s62, s61, 0x2000
	s_add_u32 s2, s26, 0x10080
	s_addc_u32 s3, s27, 0
	s_add_i32 s55, vcc_hi, s36
	s_add_i32 s0, s55, 0x2000
	ds_read_b128 v[176:179], v142
	ds_read_b128 v[180:183], v142 offset:1024
	ds_read_b128 v[184:187], v142 offset:2048
	ds_read_b128 v[188:191], v142 offset:3072
	ds_read_b128 v[192:195], v142 offset:4096
	ds_read_b128 v[196:199], v142 offset:5120
	ds_read_b128 v[208:211], v142 offset:6144
	ds_read_b128 v[212:215], v142 offset:7168
	global_load_lds_dwordx4 v134, s[30:31]
	s_mov_b32 m0, s1
	s_nop 0
	global_load_lds_dwordx4 v132, s[30:31]
	s_waitcnt vmcnt(8)
	s_waitcnt lgkmcnt(0)
	s_setprio 1
	s_barrier
	v_mfma_f32_16x16x32_bf16 v[126:129], v[144:147], v[176:179], v[126:129]
	v_mfma_f32_16x16x32_bf16 v[122:125], v[152:155], v[176:179], v[122:125]
	v_mfma_f32_16x16x32_bf16 v[118:121], v[144:147], v[184:187], v[118:121]
	v_mfma_f32_16x16x32_bf16 v[110:113], v[152:155], v[184:187], v[110:113]
	v_mfma_f32_16x16x32_bf16 v[102:105], v[144:147], v[192:195], v[102:105]
	v_mfma_f32_16x16x32_bf16 v[94:97], v[152:155], v[192:195], v[94:97]
	v_mfma_f32_16x16x32_bf16 v[86:89], v[144:147], v[208:211], v[86:89]
	v_mfma_f32_16x16x32_bf16 v[78:81], v[152:155], v[208:211], v[78:81]
	v_mfma_f32_16x16x32_bf16 v[126:129], v[148:151], v[180:183], v[126:129]
	v_mfma_f32_16x16x32_bf16 v[122:125], v[156:159], v[180:183], v[122:125]
	v_mfma_f32_16x16x32_bf16 v[118:121], v[148:151], v[188:191], v[118:121]
	v_mfma_f32_16x16x32_bf16 v[110:113], v[156:159], v[188:191], v[110:113]
	v_mfma_f32_16x16x32_bf16 v[102:105], v[148:151], v[196:199], v[102:105]
	v_mfma_f32_16x16x32_bf16 v[94:97], v[156:159], v[196:199], v[94:97]
	v_mfma_f32_16x16x32_bf16 v[86:89], v[148:151], v[212:215], v[86:89]
	v_mfma_f32_16x16x32_bf16 v[78:81], v[156:159], v[212:215], v[78:81]
	s_setprio 0
	s_setprio 1
	v_mfma_f32_16x16x32_bf16 v[114:117], v[160:163], v[176:179], v[114:117]
	v_mfma_f32_16x16x32_bf16 v[106:109], v[168:171], v[176:179], v[106:109]
	v_mfma_f32_16x16x32_bf16 v[98:101], v[160:163], v[184:187], v[98:101]
	v_mfma_f32_16x16x32_bf16 v[90:93], v[168:171], v[184:187], v[90:93]
	v_mfma_f32_16x16x32_bf16 v[82:85], v[160:163], v[192:195], v[82:85]
	v_mfma_f32_16x16x32_bf16 v[74:77], v[168:171], v[192:195], v[74:77]
	v_mfma_f32_16x16x32_bf16 v[70:73], v[160:163], v[208:211], v[70:73]
	v_mfma_f32_16x16x32_bf16 v[66:69], v[168:171], v[208:211], v[66:69]
	v_mfma_f32_16x16x32_bf16 v[114:117], v[164:167], v[180:183], v[114:117]
	v_mfma_f32_16x16x32_bf16 v[106:109], v[172:175], v[180:183], v[106:109]
	v_mfma_f32_16x16x32_bf16 v[98:101], v[164:167], v[188:191], v[98:101]
	v_mfma_f32_16x16x32_bf16 v[90:93], v[172:175], v[188:191], v[90:93]
	v_mfma_f32_16x16x32_bf16 v[82:85], v[164:167], v[196:199], v[82:85]
	v_mfma_f32_16x16x32_bf16 v[74:77], v[172:175], v[196:199], v[74:77]
	v_mfma_f32_16x16x32_bf16 v[70:73], v[164:167], v[212:215], v[70:73]
	v_mfma_f32_16x16x32_bf16 v[66:69], v[172:175], v[212:215], v[66:69]
	s_barrier
	s_setprio 0
	s_mov_b32 m0, s57
	v_lshl_add_u64 v[138:139], s[26:27], 0, v[202:203]
	ds_read_b128 v[176:179], v142 offset:16384
	ds_read_b128 v[180:183], v142 offset:17408
	ds_read_b128 v[184:187], v142 offset:18432
	ds_read_b128 v[188:191], v142 offset:19456
	ds_read_b128 v[192:195], v142 offset:20480
	ds_read_b128 v[196:199], v142 offset:21504
	ds_read_b128 v[208:211], v142 offset:22528
	ds_read_b128 v[212:215], v142 offset:23552
	global_load_lds_dwordx4 v[138:139], off
	v_lshl_add_u64 v[200:201], s[26:27], 0, v[130:131]
	s_mov_b32 m0, s63
	global_load_lds_dwordx4 v[200:201], off
	s_mov_b32 m0, s33
	v_lshl_add_u64 v[206:207], s[24:25], 0, v[132:133]
	global_load_lds_dwordx4 v202, s[28:29]
	s_mov_b32 m0, s56
	s_nop 0
	global_load_lds_dwordx4 v130, s[28:29]
	v_lshl_add_u64 v[204:205], s[24:25], 0, v[134:135]
	s_mov_b32 m0, s37
	s_nop 0
	global_load_lds_dwordx4 v[204:205], off
	s_mov_b32 m0, s38
	s_nop 0
	global_load_lds_dwordx4 v[206:207], off
	s_waitcnt vmcnt(8)
	s_waitcnt lgkmcnt(0)
	s_setprio 1
	s_barrier
	v_mfma_f32_16x16x32_bf16 v[62:65], v[144:147], v[176:179], v[62:65]
	v_mfma_f32_16x16x32_bf16 v[58:61], v[152:155], v[176:179], v[58:61]
	v_mfma_f32_16x16x32_bf16 v[54:57], v[144:147], v[184:187], v[54:57]
	v_mfma_f32_16x16x32_bf16 v[46:49], v[152:155], v[184:187], v[46:49]
	v_mfma_f32_16x16x32_bf16 v[38:41], v[144:147], v[192:195], v[38:41]
	v_mfma_f32_16x16x32_bf16 v[30:33], v[152:155], v[192:195], v[30:33]
	v_mfma_f32_16x16x32_bf16 v[22:25], v[144:147], v[208:211], v[22:25]
	v_mfma_f32_16x16x32_bf16 v[14:17], v[152:155], v[208:211], v[14:17]
	v_mfma_f32_16x16x32_bf16 v[62:65], v[148:151], v[180:183], v[62:65]
	v_mfma_f32_16x16x32_bf16 v[58:61], v[156:159], v[180:183], v[58:61]
	v_mfma_f32_16x16x32_bf16 v[54:57], v[148:151], v[188:191], v[54:57]
	v_mfma_f32_16x16x32_bf16 v[46:49], v[156:159], v[188:191], v[46:49]
	v_mfma_f32_16x16x32_bf16 v[38:41], v[148:151], v[196:199], v[38:41]
	v_mfma_f32_16x16x32_bf16 v[30:33], v[156:159], v[196:199], v[30:33]
	v_mfma_f32_16x16x32_bf16 v[22:25], v[148:151], v[212:215], v[22:25]
	v_mfma_f32_16x16x32_bf16 v[14:17], v[156:159], v[212:215], v[14:17]
	s_setprio 0
	s_setprio 1
	v_mfma_f32_16x16x32_bf16 v[50:53], v[160:163], v[176:179], v[50:53]
	v_mfma_f32_16x16x32_bf16 v[42:45], v[168:171], v[176:179], v[42:45]
	v_mfma_f32_16x16x32_bf16 v[34:37], v[160:163], v[184:187], v[34:37]
	v_mfma_f32_16x16x32_bf16 v[26:29], v[168:171], v[184:187], v[26:29]
	v_mfma_f32_16x16x32_bf16 v[18:21], v[160:163], v[192:195], v[18:21]
	v_mfma_f32_16x16x32_bf16 v[10:13], v[168:171], v[192:195], v[10:13]
	v_mfma_f32_16x16x32_bf16 v[6:9], v[160:163], v[208:211], v[6:9]
	v_mfma_f32_16x16x32_bf16 v[2:5], v[168:171], v[208:211], v[2:5]
	v_mfma_f32_16x16x32_bf16 v[50:53], v[164:167], v[180:183], v[50:53]
	v_mfma_f32_16x16x32_bf16 v[42:45], v[172:175], v[180:183], v[42:45]
	v_mfma_f32_16x16x32_bf16 v[34:37], v[164:167], v[188:191], v[34:37]
	v_mfma_f32_16x16x32_bf16 v[26:29], v[172:175], v[188:191], v[26:29]
	v_mfma_f32_16x16x32_bf16 v[18:21], v[164:167], v[196:199], v[18:21]
	v_mfma_f32_16x16x32_bf16 v[10:13], v[172:175], v[196:199], v[10:13]
	v_mfma_f32_16x16x32_bf16 v[6:9], v[164:167], v[212:215], v[6:9]
	v_mfma_f32_16x16x32_bf16 v[2:5], v[172:175], v[212:215], v[2:5]
	s_barrier
	s_setprio 0
	v_add_u32_e32 v143, vcc_lo, v141
	ds_read_b128 v[144:147], v143
	ds_read_b128 v[148:151], v143 offset:1024
	ds_read_b128 v[152:155], v143 offset:2048
	ds_read_b128 v[156:159], v143 offset:3072
	v_add_u32_e32 v143, vcc_hi, v141
	ds_read_b128 v[160:163], v143
	ds_read_b128 v[164:167], v143 offset:1024
	ds_read_b128 v[168:171], v143 offset:2048
	ds_read_b128 v[172:175], v143 offset:3072
	s_mov_b32 m0, s39
	ds_read_b128 v[176:179], v142 offset:32768
	ds_read_b128 v[180:183], v142 offset:33792
	ds_read_b128 v[184:187], v142 offset:34816
	ds_read_b128 v[188:191], v142 offset:35840
	ds_read_b128 v[192:195], v142 offset:36864
	ds_read_b128 v[196:199], v142 offset:37888
	ds_read_b128 v[208:211], v142 offset:38912
	ds_read_b128 v[212:215], v142 offset:39936
	global_load_lds_dwordx4 v134, s[4:5]
	s_mov_b32 m0, s40
	s_nop 0
	global_load_lds_dwordx4 v132, s[4:5]
	s_waitcnt vmcnt(8)
	s_waitcnt lgkmcnt(0)
	s_setprio 1
	s_barrier
	v_mfma_f32_16x16x32_bf16 v[126:129], v[144:147], v[176:179], v[126:129]
	v_mfma_f32_16x16x32_bf16 v[122:125], v[152:155], v[176:179], v[122:125]
	v_mfma_f32_16x16x32_bf16 v[118:121], v[144:147], v[184:187], v[118:121]
	v_mfma_f32_16x16x32_bf16 v[110:113], v[152:155], v[184:187], v[110:113]
	v_mfma_f32_16x16x32_bf16 v[102:105], v[144:147], v[192:195], v[102:105]
	v_mfma_f32_16x16x32_bf16 v[94:97], v[152:155], v[192:195], v[94:97]
	v_mfma_f32_16x16x32_bf16 v[86:89], v[144:147], v[208:211], v[86:89]
	v_mfma_f32_16x16x32_bf16 v[78:81], v[152:155], v[208:211], v[78:81]
	v_mfma_f32_16x16x32_bf16 v[126:129], v[148:151], v[180:183], v[126:129]
	v_mfma_f32_16x16x32_bf16 v[122:125], v[156:159], v[180:183], v[122:125]
	v_mfma_f32_16x16x32_bf16 v[118:121], v[148:151], v[188:191], v[118:121]
	v_mfma_f32_16x16x32_bf16 v[110:113], v[156:159], v[188:191], v[110:113]
	v_mfma_f32_16x16x32_bf16 v[102:105], v[148:151], v[196:199], v[102:105]
	v_mfma_f32_16x16x32_bf16 v[94:97], v[156:159], v[196:199], v[94:97]
	v_mfma_f32_16x16x32_bf16 v[86:89], v[148:151], v[212:215], v[86:89]
	v_mfma_f32_16x16x32_bf16 v[78:81], v[156:159], v[212:215], v[78:81]
	s_setprio 0
	s_setprio 1
	v_mfma_f32_16x16x32_bf16 v[114:117], v[160:163], v[176:179], v[114:117]
	v_mfma_f32_16x16x32_bf16 v[106:109], v[168:171], v[176:179], v[106:109]
	v_mfma_f32_16x16x32_bf16 v[98:101], v[160:163], v[184:187], v[98:101]
	v_mfma_f32_16x16x32_bf16 v[90:93], v[168:171], v[184:187], v[90:93]
	v_mfma_f32_16x16x32_bf16 v[82:85], v[160:163], v[192:195], v[82:85]
	v_mfma_f32_16x16x32_bf16 v[74:77], v[168:171], v[192:195], v[74:77]
	v_mfma_f32_16x16x32_bf16 v[70:73], v[160:163], v[208:211], v[70:73]
	v_mfma_f32_16x16x32_bf16 v[66:69], v[168:171], v[208:211], v[66:69]
	v_mfma_f32_16x16x32_bf16 v[114:117], v[164:167], v[180:183], v[114:117]
	v_mfma_f32_16x16x32_bf16 v[106:109], v[172:175], v[180:183], v[106:109]
	v_mfma_f32_16x16x32_bf16 v[98:101], v[164:167], v[188:191], v[98:101]
	v_mfma_f32_16x16x32_bf16 v[90:93], v[172:175], v[188:191], v[90:93]
	v_mfma_f32_16x16x32_bf16 v[82:85], v[164:167], v[196:199], v[82:85]
	v_mfma_f32_16x16x32_bf16 v[74:77], v[172:175], v[196:199], v[74:77]
	v_mfma_f32_16x16x32_bf16 v[70:73], v[164:167], v[212:215], v[70:73]
	v_mfma_f32_16x16x32_bf16 v[66:69], v[172:175], v[212:215], v[66:69]
	s_barrier
	s_setprio 0
	s_mov_b32 m0, s61
	v_lshl_add_u64 v[138:139], v[138:139], 0, s[80:81]
	ds_read_b128 v[176:179], v142 offset:49152
	ds_read_b128 v[180:183], v142 offset:50176
	ds_read_b128 v[184:187], v142 offset:51200
	ds_read_b128 v[188:191], v142 offset:52224
	ds_read_b128 v[192:195], v142 offset:53248
	ds_read_b128 v[196:199], v142 offset:54272
	ds_read_b128 v[208:211], v142 offset:55296
	ds_read_b128 v[212:215], v142 offset:56320
	global_load_lds_dwordx4 v[138:139], off
	v_lshl_add_u64 v[138:139], v[200:201], 0, s[80:81]
	s_mov_b32 m0, s62
	s_nop 0
	global_load_lds_dwordx4 v[138:139], off
	s_mov_b32 m0, s55
	s_nop 0
	global_load_lds_dwordx4 v202, s[2:3]
	s_mov_b32 m0, s0
	s_nop 0
	global_load_lds_dwordx4 v130, s[2:3]
	v_lshl_add_u64 v[138:139], v[204:205], 0, s[80:81]
	s_mov_b32 m0, s41
	s_nop 0
	global_load_lds_dwordx4 v[138:139], off
	v_lshl_add_u64 v[138:139], v[206:207], 0, s[80:81]
	s_mov_b32 m0, s86
	s_nop 0
	global_load_lds_dwordx4 v[138:139], off
	s_waitcnt vmcnt(8)
	s_waitcnt lgkmcnt(0)
	s_setprio 1
	s_barrier
	v_mfma_f32_16x16x32_bf16 v[62:65], v[144:147], v[176:179], v[62:65]
	v_mfma_f32_16x16x32_bf16 v[58:61], v[152:155], v[176:179], v[58:61]
	v_mfma_f32_16x16x32_bf16 v[54:57], v[144:147], v[184:187], v[54:57]
	v_mfma_f32_16x16x32_bf16 v[46:49], v[152:155], v[184:187], v[46:49]
	v_mfma_f32_16x16x32_bf16 v[38:41], v[144:147], v[192:195], v[38:41]
	v_mfma_f32_16x16x32_bf16 v[30:33], v[152:155], v[192:195], v[30:33]
	v_mfma_f32_16x16x32_bf16 v[22:25], v[144:147], v[208:211], v[22:25]
	v_mfma_f32_16x16x32_bf16 v[14:17], v[152:155], v[208:211], v[14:17]
	v_mfma_f32_16x16x32_bf16 v[62:65], v[148:151], v[180:183], v[62:65]
	v_mfma_f32_16x16x32_bf16 v[58:61], v[156:159], v[180:183], v[58:61]
	v_mfma_f32_16x16x32_bf16 v[54:57], v[148:151], v[188:191], v[54:57]
	v_mfma_f32_16x16x32_bf16 v[46:49], v[156:159], v[188:191], v[46:49]
	v_mfma_f32_16x16x32_bf16 v[38:41], v[148:151], v[196:199], v[38:41]
	v_mfma_f32_16x16x32_bf16 v[30:33], v[156:159], v[196:199], v[30:33]
	v_mfma_f32_16x16x32_bf16 v[22:25], v[148:151], v[212:215], v[22:25]
	v_mfma_f32_16x16x32_bf16 v[14:17], v[156:159], v[212:215], v[14:17]
	s_setprio 0
	s_setprio 1
	v_mfma_f32_16x16x32_bf16 v[50:53], v[160:163], v[176:179], v[50:53]
	v_mfma_f32_16x16x32_bf16 v[42:45], v[168:171], v[176:179], v[42:45]
	v_mfma_f32_16x16x32_bf16 v[34:37], v[160:163], v[184:187], v[34:37]
	v_mfma_f32_16x16x32_bf16 v[26:29], v[168:171], v[184:187], v[26:29]
	v_mfma_f32_16x16x32_bf16 v[18:21], v[160:163], v[192:195], v[18:21]
	v_mfma_f32_16x16x32_bf16 v[10:13], v[168:171], v[192:195], v[10:13]
	v_mfma_f32_16x16x32_bf16 v[6:9], v[160:163], v[208:211], v[6:9]
	v_mfma_f32_16x16x32_bf16 v[2:5], v[168:171], v[208:211], v[2:5]
	v_mfma_f32_16x16x32_bf16 v[50:53], v[164:167], v[180:183], v[50:53]
	v_mfma_f32_16x16x32_bf16 v[42:45], v[172:175], v[180:183], v[42:45]
	v_mfma_f32_16x16x32_bf16 v[34:37], v[164:167], v[188:191], v[34:37]
	v_mfma_f32_16x16x32_bf16 v[26:29], v[172:175], v[188:191], v[26:29]
	v_mfma_f32_16x16x32_bf16 v[18:21], v[164:167], v[196:199], v[18:21]
	v_mfma_f32_16x16x32_bf16 v[10:13], v[172:175], v[196:199], v[10:13]
	v_mfma_f32_16x16x32_bf16 v[6:9], v[164:167], v[212:215], v[6:9]
	v_mfma_f32_16x16x32_bf16 v[2:5], v[172:175], v[212:215], v[2:5]
	s_barrier
	s_setprio 0
	s_andn2_b64 vcc, exec, s[22:23]
	s_mov_b64 s[2:3], -1
	s_mov_b64 s[22:23], 0
	s_mov_b64 s[4:5], 0x100
	s_cbranch_vccz .LBB0_1242
	s_and_b64 vcc, exec, s[10:11]
	s_cbranch_vccz .LBB0_1245
	s_barrier

.LBB0_1363:
	s_add_u32 s0, s20, 0xfffe0080
	s_addc_u32 s1, s21, -1
	s_add_i32 s33, 0, 0x10000
	s_cmp_eq_u32 s59, 4
	s_cselect_b32 s5, s38, s1
	s_cselect_b32 s4, s39, s0
	v_add_u32_e32 v147, s33, v143
	s_cselect_b32 s3, s40, s58
	s_cselect_b32 s2, s41, s49
	s_add_i32 s55, 0, 0x14000
	ds_read_b128 v[148:151], v147
	ds_read_b128 v[152:155], v147 offset:1024
	ds_read_b128 v[156:159], v147 offset:2048
	ds_read_b128 v[160:163], v147 offset:3072
	v_add_u32_e32 v147, s55, v143
	ds_read_b128 v[164:167], v147
	ds_read_b128 v[168:171], v147 offset:1024
	ds_read_b128 v[172:175], v147 offset:2048
	ds_read_b128 v[176:179], v147 offset:3072
	s_add_i32 m0, s25, 0xc000
	ds_read_b128 v[180:183], v146
	ds_read_b128 v[184:187], v146 offset:1024
	ds_read_b128 v[188:191], v146 offset:2048
	ds_read_b128 v[192:195], v146 offset:3072
	ds_read_b128 v[196:199], v146 offset:4096
	ds_read_b128 v[208:211], v146 offset:5120
	ds_read_b128 v[212:215], v146 offset:6144
	ds_read_b128 v[216:219], v146 offset:7168
	global_load_lds_dwordx4 v138, s[20:21]
	s_add_i32 m0, s25, 0xe000
	s_nop 0
	global_load_lds_dwordx4 v140, s[20:21]
	s_waitcnt vmcnt(8)
	s_waitcnt lgkmcnt(0)
	s_setprio 1
	s_barrier
	v_mfma_f32_16x16x32_bf16 v[126:129], v[148:151], v[180:183], v[126:129]
	v_mfma_f32_16x16x32_bf16 v[122:125], v[156:159], v[180:183], v[122:125]
	v_mfma_f32_16x16x32_bf16 v[110:113], v[148:151], v[188:191], v[110:113]
	v_mfma_f32_16x16x32_bf16 v[106:109], v[156:159], v[188:191], v[106:109]
	v_mfma_f32_16x16x32_bf16 v[94:97], v[148:151], v[196:199], v[94:97]
	v_mfma_f32_16x16x32_bf16 v[90:93], v[156:159], v[196:199], v[90:93]
	v_mfma_f32_16x16x32_bf16 v[78:81], v[148:151], v[212:215], v[78:81]
	v_mfma_f32_16x16x32_bf16 v[74:77], v[156:159], v[212:215], v[74:77]
	v_mfma_f32_16x16x32_bf16 v[126:129], v[152:155], v[184:187], v[126:129]
	v_mfma_f32_16x16x32_bf16 v[122:125], v[160:163], v[184:187], v[122:125]
	v_mfma_f32_16x16x32_bf16 v[110:113], v[152:155], v[192:195], v[110:113]
	v_mfma_f32_16x16x32_bf16 v[106:109], v[160:163], v[192:195], v[106:109]
	v_mfma_f32_16x16x32_bf16 v[94:97], v[152:155], v[208:211], v[94:97]
	v_mfma_f32_16x16x32_bf16 v[90:93], v[160:163], v[208:211], v[90:93]
	v_mfma_f32_16x16x32_bf16 v[78:81], v[152:155], v[216:219], v[78:81]
	v_mfma_f32_16x16x32_bf16 v[74:77], v[160:163], v[216:219], v[74:77]
	s_setprio 0
	s_setprio 1
	v_mfma_f32_16x16x32_bf16 v[118:121], v[164:167], v[180:183], v[118:121]
	v_mfma_f32_16x16x32_bf16 v[114:117], v[172:175], v[180:183], v[114:117]
	v_mfma_f32_16x16x32_bf16 v[102:105], v[164:167], v[188:191], v[102:105]
	v_mfma_f32_16x16x32_bf16 v[98:101], v[172:175], v[188:191], v[98:101]
	v_mfma_f32_16x16x32_bf16 v[86:89], v[164:167], v[196:199], v[86:89]
	v_mfma_f32_16x16x32_bf16 v[82:85], v[172:175], v[196:199], v[82:85]
	v_mfma_f32_16x16x32_bf16 v[70:73], v[164:167], v[212:215], v[70:73]
	v_mfma_f32_16x16x32_bf16 v[66:69], v[172:175], v[212:215], v[66:69]
	v_mfma_f32_16x16x32_bf16 v[118:121], v[168:171], v[184:187], v[118:121]
	v_mfma_f32_16x16x32_bf16 v[114:117], v[176:179], v[184:187], v[114:117]
	v_mfma_f32_16x16x32_bf16 v[102:105], v[168:171], v[192:195], v[102:105]
	v_mfma_f32_16x16x32_bf16 v[98:101], v[176:179], v[192:195], v[98:101]
	v_mfma_f32_16x16x32_bf16 v[86:89], v[168:171], v[208:211], v[86:89]
	v_mfma_f32_16x16x32_bf16 v[82:85], v[176:179], v[208:211], v[82:85]
	v_mfma_f32_16x16x32_bf16 v[70:73], v[168:171], v[216:219], v[70:73]
	v_mfma_f32_16x16x32_bf16 v[66:69], v[176:179], v[216:219], v[66:69]
	s_barrier
	s_setprio 0
	s_add_i32 s0, s33, s24
	v_lshl_add_u64 v[200:201], s[2:3], 0, v[134:135]
	s_mov_b32 m0, s0
	ds_read_b128 v[180:183], v146 offset:16384
	ds_read_b128 v[184:187], v146 offset:17408
	ds_read_b128 v[188:191], v146 offset:18432
	ds_read_b128 v[192:195], v146 offset:19456
	ds_read_b128 v[196:199], v146 offset:20480
	ds_read_b128 v[208:211], v146 offset:21504
	ds_read_b128 v[212:215], v146 offset:22528
	ds_read_b128 v[216:219], v146 offset:23552
	global_load_lds_dwordx4 v[200:201], off
	s_add_i32 m0, s0, 0x2000
	s_add_u32 s0, s2, 0x20000
	v_lshl_add_u64 v[204:205], s[2:3], 0, v[130:131]
	s_addc_u32 s1, s3, 0
	s_add_i32 s33, s55, s24
	global_load_lds_dwordx4 v[204:205], off
	s_mov_b32 m0, s33
	v_lshl_add_u64 v[220:221], s[4:5], 0, v[132:133]
	global_load_lds_dwordx4 v134, s[0:1]
	s_add_i32 m0, s33, 0x2000
	s_nop 0
	global_load_lds_dwordx4 v130, s[0:1]
	v_lshl_add_u64 v[206:207], s[4:5], 0, v[136:137]
	s_mov_b32 m0, s25
	s_nop 0
	global_load_lds_dwordx4 v[206:207], off
	s_mov_b32 m0, s26
	s_nop 0
	global_load_lds_dwordx4 v[220:221], off
	s_waitcnt vmcnt(8)
	s_waitcnt lgkmcnt(0)
	s_setprio 1
	s_barrier
	v_mfma_f32_16x16x32_bf16 v[62:65], v[148:151], v[180:183], v[62:65]
	v_mfma_f32_16x16x32_bf16 v[58:61], v[156:159], v[180:183], v[58:61]
	v_mfma_f32_16x16x32_bf16 v[46:49], v[148:151], v[188:191], v[46:49]
	v_mfma_f32_16x16x32_bf16 v[42:45], v[156:159], v[188:191], v[42:45]
	v_mfma_f32_16x16x32_bf16 v[30:33], v[148:151], v[196:199], v[30:33]
	v_mfma_f32_16x16x32_bf16 v[26:29], v[156:159], v[196:199], v[26:29]
	v_mfma_f32_16x16x32_bf16 v[14:17], v[148:151], v[212:215], v[14:17]
	v_mfma_f32_16x16x32_bf16 v[10:13], v[156:159], v[212:215], v[10:13]
	v_mfma_f32_16x16x32_bf16 v[62:65], v[152:155], v[184:187], v[62:65]
	v_mfma_f32_16x16x32_bf16 v[58:61], v[160:163], v[184:187], v[58:61]
	v_mfma_f32_16x16x32_bf16 v[46:49], v[152:155], v[192:195], v[46:49]
	v_mfma_f32_16x16x32_bf16 v[42:45], v[160:163], v[192:195], v[42:45]
	v_mfma_f32_16x16x32_bf16 v[30:33], v[152:155], v[208:211], v[30:33]
	v_mfma_f32_16x16x32_bf16 v[26:29], v[160:163], v[208:211], v[26:29]
	v_mfma_f32_16x16x32_bf16 v[14:17], v[152:155], v[216:219], v[14:17]
	v_mfma_f32_16x16x32_bf16 v[10:13], v[160:163], v[216:219], v[10:13]
	s_setprio 0
	s_setprio 1
	v_mfma_f32_16x16x32_bf16 v[54:57], v[164:167], v[180:183], v[54:57]
	v_mfma_f32_16x16x32_bf16 v[50:53], v[172:175], v[180:183], v[50:53]
	v_mfma_f32_16x16x32_bf16 v[38:41], v[164:167], v[188:191], v[38:41]
	v_mfma_f32_16x16x32_bf16 v[34:37], v[172:175], v[188:191], v[34:37]
	v_mfma_f32_16x16x32_bf16 v[22:25], v[164:167], v[196:199], v[22:25]
	v_mfma_f32_16x16x32_bf16 v[18:21], v[172:175], v[196:199], v[18:21]
	v_mfma_f32_16x16x32_bf16 v[6:9], v[164:167], v[212:215], v[6:9]
	v_mfma_f32_16x16x32_bf16 v[2:5], v[172:175], v[212:215], v[2:5]
	v_mfma_f32_16x16x32_bf16 v[54:57], v[168:171], v[184:187], v[54:57]
	v_mfma_f32_16x16x32_bf16 v[50:53], v[176:179], v[184:187], v[50:53]
	v_mfma_f32_16x16x32_bf16 v[38:41], v[168:171], v[192:195], v[38:41]
	v_mfma_f32_16x16x32_bf16 v[34:37], v[176:179], v[192:195], v[34:37]
	v_mfma_f32_16x16x32_bf16 v[22:25], v[168:171], v[208:211], v[22:25]
	v_mfma_f32_16x16x32_bf16 v[18:21], v[176:179], v[208:211], v[18:21]
	v_mfma_f32_16x16x32_bf16 v[6:9], v[168:171], v[216:219], v[6:9]
	v_mfma_f32_16x16x32_bf16 v[2:5], v[176:179], v[216:219], v[2:5]
	s_barrier
	s_setprio 0
	s_add_i32 s33, 0, 0x18000
	v_add_u32_e32 v147, s33, v143
	s_add_i32 s55, 0, 0x1c000
	ds_read_b128 v[148:151], v147
	ds_read_b128 v[152:155], v147 offset:1024
	ds_read_b128 v[156:159], v147 offset:2048
	ds_read_b128 v[160:163], v147 offset:3072
	v_add_u32_e32 v147, s55, v143
	ds_read_b128 v[164:167], v147
	ds_read_b128 v[168:171], v147 offset:1024
	ds_read_b128 v[172:175], v147 offset:2048
	ds_read_b128 v[176:179], v147 offset:3072
	s_add_u32 s0, s4, 0x20000
	s_addc_u32 s1, s5, 0
	s_mov_b32 m0, s27
	ds_read_b128 v[180:183], v146 offset:32768
	ds_read_b128 v[184:187], v146 offset:33792
	ds_read_b128 v[188:191], v146 offset:34816
	ds_read_b128 v[192:195], v146 offset:35840
	ds_read_b128 v[196:199], v146 offset:36864
	ds_read_b128 v[208:211], v146 offset:37888
	ds_read_b128 v[212:215], v146 offset:38912
	ds_read_b128 v[216:219], v146 offset:39936
	global_load_lds_dwordx4 v136, s[0:1]
	s_mov_b32 m0, s28
	s_nop 0
	global_load_lds_dwordx4 v132, s[0:1]
	s_waitcnt vmcnt(8)
	s_waitcnt lgkmcnt(0)
	s_setprio 1
	s_barrier
	v_mfma_f32_16x16x32_bf16 v[126:129], v[148:151], v[180:183], v[126:129]
	v_mfma_f32_16x16x32_bf16 v[122:125], v[156:159], v[180:183], v[122:125]
	v_mfma_f32_16x16x32_bf16 v[110:113], v[148:151], v[188:191], v[110:113]
	v_mfma_f32_16x16x32_bf16 v[106:109], v[156:159], v[188:191], v[106:109]
	v_mfma_f32_16x16x32_bf16 v[94:97], v[148:151], v[196:199], v[94:97]
	v_mfma_f32_16x16x32_bf16 v[90:93], v[156:159], v[196:199], v[90:93]
	v_mfma_f32_16x16x32_bf16 v[78:81], v[148:151], v[212:215], v[78:81]
	v_mfma_f32_16x16x32_bf16 v[74:77], v[156:159], v[212:215], v[74:77]
	v_mfma_f32_16x16x32_bf16 v[126:129], v[152:155], v[184:187], v[126:129]
	v_mfma_f32_16x16x32_bf16 v[122:125], v[160:163], v[184:187], v[122:125]
	v_mfma_f32_16x16x32_bf16 v[110:113], v[152:155], v[192:195], v[110:113]
	v_mfma_f32_16x16x32_bf16 v[106:109], v[160:163], v[192:195], v[106:109]
	v_mfma_f32_16x16x32_bf16 v[94:97], v[152:155], v[208:211], v[94:97]
	v_mfma_f32_16x16x32_bf16 v[90:93], v[160:163], v[208:211], v[90:93]
	v_mfma_f32_16x16x32_bf16 v[78:81], v[152:155], v[216:219], v[78:81]
	v_mfma_f32_16x16x32_bf16 v[74:77], v[160:163], v[216:219], v[74:77]
	s_setprio 0
	s_setprio 1
	v_mfma_f32_16x16x32_bf16 v[118:121], v[164:167], v[180:183], v[118:121]
	v_mfma_f32_16x16x32_bf16 v[114:117], v[172:175], v[180:183], v[114:117]
	v_mfma_f32_16x16x32_bf16 v[102:105], v[164:167], v[188:191], v[102:105]
	v_mfma_f32_16x16x32_bf16 v[98:101], v[172:175], v[188:191], v[98:101]
	v_mfma_f32_16x16x32_bf16 v[86:89], v[164:167], v[196:199], v[86:89]
	v_mfma_f32_16x16x32_bf16 v[82:85], v[172:175], v[196:199], v[82:85]
	v_mfma_f32_16x16x32_bf16 v[70:73], v[164:167], v[212:215], v[70:73]
	v_mfma_f32_16x16x32_bf16 v[66:69], v[172:175], v[212:215], v[66:69]
	v_mfma_f32_16x16x32_bf16 v[118:121], v[168:171], v[184:187], v[118:121]
	v_mfma_f32_16x16x32_bf16 v[114:117], v[176:179], v[184:187], v[114:117]
	v_mfma_f32_16x16x32_bf16 v[102:105], v[168:171], v[192:195], v[102:105]
	v_mfma_f32_16x16x32_bf16 v[98:101], v[176:179], v[192:195], v[98:101]
	v_mfma_f32_16x16x32_bf16 v[86:89], v[168:171], v[208:211], v[86:89]
	v_mfma_f32_16x16x32_bf16 v[82:85], v[176:179], v[208:211], v[82:85]
	v_mfma_f32_16x16x32_bf16 v[70:73], v[168:171], v[216:219], v[70:73]
	v_mfma_f32_16x16x32_bf16 v[66:69], v[176:179], v[216:219], v[66:69]
	s_barrier
	s_setprio 0
	s_add_i32 s0, s33, s24
	v_lshl_add_u64 v[200:201], v[200:201], 0, s[80:81]
	s_mov_b32 m0, s0
	ds_read_b128 v[180:183], v146 offset:49152
	ds_read_b128 v[184:187], v146 offset:50176
	ds_read_b128 v[188:191], v146 offset:51200
	ds_read_b128 v[192:195], v146 offset:52224
	ds_read_b128 v[196:199], v146 offset:53248
	ds_read_b128 v[208:211], v146 offset:54272
	ds_read_b128 v[212:215], v146 offset:55296
	ds_read_b128 v[216:219], v146 offset:56320
	global_load_lds_dwordx4 v[200:201], off
	s_add_i32 m0, s0, 0x2000
	s_add_u32 s0, s2, 0x20080
	v_lshl_add_u64 v[200:201], v[204:205], 0, s[80:81]
	s_addc_u32 s1, s3, 0
	s_add_i32 s2, s55, s24
	global_load_lds_dwordx4 v[200:201], off
	s_mov_b32 m0, s2
	s_nop 0
	global_load_lds_dwordx4 v134, s[0:1]
	s_add_i32 m0, s2, 0x2000
	s_nop 0
	global_load_lds_dwordx4 v130, s[0:1]
	v_lshl_add_u64 v[200:201], v[206:207], 0, s[80:81]
	s_mov_b32 m0, s29
	s_nop 0
	global_load_lds_dwordx4 v[200:201], off
	v_lshl_add_u64 v[200:201], v[220:221], 0, s[80:81]
	s_mov_b32 m0, s30
	s_nop 0
	global_load_lds_dwordx4 v[200:201], off
	s_waitcnt vmcnt(8)
	s_waitcnt lgkmcnt(0)
	s_setprio 1
	s_barrier
	v_mfma_f32_16x16x32_bf16 v[62:65], v[148:151], v[180:183], v[62:65]
	v_mfma_f32_16x16x32_bf16 v[58:61], v[156:159], v[180:183], v[58:61]
	v_mfma_f32_16x16x32_bf16 v[46:49], v[148:151], v[188:191], v[46:49]
	v_mfma_f32_16x16x32_bf16 v[42:45], v[156:159], v[188:191], v[42:45]
	v_mfma_f32_16x16x32_bf16 v[30:33], v[148:151], v[196:199], v[30:33]
	v_mfma_f32_16x16x32_bf16 v[26:29], v[156:159], v[196:199], v[26:29]
	v_mfma_f32_16x16x32_bf16 v[14:17], v[148:151], v[212:215], v[14:17]
	v_mfma_f32_16x16x32_bf16 v[10:13], v[156:159], v[212:215], v[10:13]
	v_mfma_f32_16x16x32_bf16 v[62:65], v[152:155], v[184:187], v[62:65]
	v_mfma_f32_16x16x32_bf16 v[58:61], v[160:163], v[184:187], v[58:61]
	v_mfma_f32_16x16x32_bf16 v[46:49], v[152:155], v[192:195], v[46:49]
	v_mfma_f32_16x16x32_bf16 v[42:45], v[160:163], v[192:195], v[42:45]
	v_mfma_f32_16x16x32_bf16 v[30:33], v[152:155], v[208:211], v[30:33]
	v_mfma_f32_16x16x32_bf16 v[26:29], v[160:163], v[208:211], v[26:29]
	v_mfma_f32_16x16x32_bf16 v[14:17], v[152:155], v[216:219], v[14:17]
	v_mfma_f32_16x16x32_bf16 v[10:13], v[160:163], v[216:219], v[10:13]
	s_setprio 0
	s_setprio 1
	v_mfma_f32_16x16x32_bf16 v[54:57], v[164:167], v[180:183], v[54:57]
	v_mfma_f32_16x16x32_bf16 v[50:53], v[172:175], v[180:183], v[50:53]
	v_mfma_f32_16x16x32_bf16 v[38:41], v[164:167], v[188:191], v[38:41]
	v_mfma_f32_16x16x32_bf16 v[34:37], v[172:175], v[188:191], v[34:37]
	v_mfma_f32_16x16x32_bf16 v[22:25], v[164:167], v[196:199], v[22:25]
	v_mfma_f32_16x16x32_bf16 v[18:21], v[172:175], v[196:199], v[18:21]
	v_mfma_f32_16x16x32_bf16 v[6:9], v[164:167], v[212:215], v[6:9]
	v_mfma_f32_16x16x32_bf16 v[2:5], v[172:175], v[212:215], v[2:5]
	v_mfma_f32_16x16x32_bf16 v[54:57], v[168:171], v[184:187], v[54:57]
	v_mfma_f32_16x16x32_bf16 v[50:53], v[176:179], v[184:187], v[50:53]
	v_mfma_f32_16x16x32_bf16 v[38:41], v[168:171], v[192:195], v[38:41]
	v_mfma_f32_16x16x32_bf16 v[34:37], v[176:179], v[192:195], v[34:37]
	v_mfma_f32_16x16x32_bf16 v[22:25], v[168:171], v[208:211], v[22:25]
	v_mfma_f32_16x16x32_bf16 v[18:21], v[176:179], v[208:211], v[18:21]
	v_mfma_f32_16x16x32_bf16 v[6:9], v[168:171], v[216:219], v[6:9]
	v_mfma_f32_16x16x32_bf16 v[2:5], v[176:179], v[216:219], v[2:5]
	s_barrier
	s_setprio 0
	s_add_i32 s59, s59, 2
	s_add_u32 s20, s20, 0x100
	s_addc_u32 s21, s21, 0
	s_add_u32 s49, s49, 0x100
	s_addc_u32 s58, s58, 0
	s_cmp_gt_u32 s59, 5
	s_cbranch_scc0 .LBB0_1363
	s_and_b64 vcc, exec, s[14:15]
	s_cbranch_vccz .LBB0_1366
	s_barrier

.LBB0_1428:
	s_add_u32 s0, s26, 0xfff80080
	s_addc_u32 s1, s27, -1
	s_add_i32 s33, 0, 0x10000
	s_cmp_eq_u32 s61, 28
	s_cselect_b32 s5, s17, s1
	s_cselect_b32 s4, s49, s0
	s_cselect_b32 s3, s15, s60
	s_cselect_b32 s2, s58, s59
	s_add_i32 s55, 0, 0x14000
	v_add_u32_e32 v142, s33, v187
	v_add_u32_e32 v158, s55, v187
	ds_read_b128 v[126:129], v142
	ds_read_b128 v[134:137], v142 offset:1024
	ds_read_b128 v[138:141], v142 offset:2048
	ds_read_b128 v[142:145], v142 offset:3072
	ds_read_b128 v[146:149], v158
	ds_read_b128 v[150:153], v158 offset:1024
	ds_read_b128 v[154:157], v158 offset:2048
	ds_read_b128 v[158:161], v158 offset:3072
	s_add_i32 m0, s23, 0xc000
	ds_read_b128 v[172:175], v189
	ds_read_b128 v[176:179], v189 offset:1024
	ds_read_b128 v[180:183], v189 offset:2048
	ds_read_b128 v[190:193], v189 offset:3072
	ds_read_b128 v[194:197], v189 offset:4096
	ds_read_b128 v[198:201], v189 offset:5120
	ds_read_b128 v[208:211], v189 offset:6144
	ds_read_b128 v[212:215], v189 offset:7168
	global_load_lds_dwordx4 v168, s[26:27]
	s_add_i32 m0, s23, 0xe000
	s_nop 0
	global_load_lds_dwordx4 v170, s[26:27]
	s_waitcnt vmcnt(8)
	s_waitcnt lgkmcnt(0)
	s_setprio 1
	s_barrier
	v_mfma_f32_16x16x32_bf16 v[130:133], v[126:129], v[172:175], v[130:133]
	v_mfma_f32_16x16x32_bf16 v[118:121], v[138:141], v[172:175], v[118:121]
	v_mfma_f32_16x16x32_bf16 v[110:113], v[126:129], v[180:183], v[110:113]
	v_mfma_f32_16x16x32_bf16 v[102:105], v[138:141], v[180:183], v[102:105]
	v_mfma_f32_16x16x32_bf16 v[94:97], v[126:129], v[194:197], v[94:97]
	v_mfma_f32_16x16x32_bf16 v[86:89], v[138:141], v[194:197], v[86:89]
	v_mfma_f32_16x16x32_bf16 v[78:81], v[126:129], v[208:211], v[78:81]
	v_mfma_f32_16x16x32_bf16 v[70:73], v[138:141], v[208:211], v[70:73]
	v_mfma_f32_16x16x32_bf16 v[130:133], v[134:137], v[176:179], v[130:133]
	v_mfma_f32_16x16x32_bf16 v[118:121], v[142:145], v[176:179], v[118:121]
	v_mfma_f32_16x16x32_bf16 v[110:113], v[134:137], v[190:193], v[110:113]
	v_mfma_f32_16x16x32_bf16 v[102:105], v[142:145], v[190:193], v[102:105]
	v_mfma_f32_16x16x32_bf16 v[94:97], v[134:137], v[198:201], v[94:97]
	v_mfma_f32_16x16x32_bf16 v[86:89], v[142:145], v[198:201], v[86:89]
	v_mfma_f32_16x16x32_bf16 v[78:81], v[134:137], v[212:215], v[78:81]
	v_mfma_f32_16x16x32_bf16 v[70:73], v[142:145], v[212:215], v[70:73]
	s_setprio 0
	s_setprio 1
	v_mfma_f32_16x16x32_bf16 v[122:125], v[146:149], v[172:175], v[122:125]
	v_mfma_f32_16x16x32_bf16 v[114:117], v[154:157], v[172:175], v[114:117]
	v_mfma_f32_16x16x32_bf16 v[106:109], v[146:149], v[180:183], v[106:109]
	v_mfma_f32_16x16x32_bf16 v[98:101], v[154:157], v[180:183], v[98:101]
	v_mfma_f32_16x16x32_bf16 v[90:93], v[146:149], v[194:197], v[90:93]
	v_mfma_f32_16x16x32_bf16 v[82:85], v[154:157], v[194:197], v[82:85]
	v_mfma_f32_16x16x32_bf16 v[74:77], v[146:149], v[208:211], v[74:77]
	v_mfma_f32_16x16x32_bf16 v[66:69], v[154:157], v[208:211], v[66:69]
	v_mfma_f32_16x16x32_bf16 v[122:125], v[150:153], v[176:179], v[122:125]
	v_mfma_f32_16x16x32_bf16 v[114:117], v[158:161], v[176:179], v[114:117]
	v_mfma_f32_16x16x32_bf16 v[106:109], v[150:153], v[190:193], v[106:109]
	v_mfma_f32_16x16x32_bf16 v[98:101], v[158:161], v[190:193], v[98:101]
	v_mfma_f32_16x16x32_bf16 v[90:93], v[150:153], v[198:201], v[90:93]
	v_mfma_f32_16x16x32_bf16 v[82:85], v[158:161], v[198:201], v[82:85]
	v_mfma_f32_16x16x32_bf16 v[74:77], v[150:153], v[212:215], v[74:77]
	v_mfma_f32_16x16x32_bf16 v[66:69], v[158:161], v[212:215], v[66:69]
	s_barrier
	s_setprio 0
	s_add_i32 s0, s33, s34
	v_lshl_add_u64 v[184:185], s[2:3], 0, v[202:203]
	s_mov_b32 m0, s0
	ds_read_b128 v[172:175], v189 offset:16384
	ds_read_b128 v[176:179], v189 offset:17408
	ds_read_b128 v[180:183], v189 offset:18432
	ds_read_b128 v[190:193], v189 offset:19456
	ds_read_b128 v[194:197], v189 offset:20480
	ds_read_b128 v[198:201], v189 offset:21504
	ds_read_b128 v[208:211], v189 offset:22528
	ds_read_b128 v[212:215], v189 offset:23552
	global_load_lds_dwordx4 v[184:185], off
	s_add_i32 m0, s0, 0x2000
	s_add_u32 s0, s2, 0x80000
	v_lshl_add_u64 v[204:205], s[2:3], 0, v[162:163]
	s_addc_u32 s1, s3, 0
	s_add_i32 s33, s55, s34
	global_load_lds_dwordx4 v[204:205], off
	s_mov_b32 m0, s33
	v_lshl_add_u64 v[216:217], s[4:5], 0, v[164:165]
	global_load_lds_dwordx4 v202, s[0:1]
	s_add_i32 m0, s33, 0x2000
	s_nop 0
	global_load_lds_dwordx4 v162, s[0:1]
	v_lshl_add_u64 v[206:207], s[4:5], 0, v[166:167]
	s_mov_b32 m0, s23
	s_nop 0
	global_load_lds_dwordx4 v[206:207], off
	s_mov_b32 m0, s25
	s_nop 0
	global_load_lds_dwordx4 v[216:217], off
	s_waitcnt vmcnt(8)
	s_waitcnt lgkmcnt(0)
	s_setprio 1
	s_barrier
	v_mfma_f32_16x16x32_bf16 v[62:65], v[126:129], v[172:175], v[62:65]
	v_mfma_f32_16x16x32_bf16 v[54:57], v[138:141], v[172:175], v[54:57]
	v_mfma_f32_16x16x32_bf16 v[46:49], v[126:129], v[180:183], v[46:49]
	v_mfma_f32_16x16x32_bf16 v[38:41], v[138:141], v[180:183], v[38:41]
	v_mfma_f32_16x16x32_bf16 v[30:33], v[126:129], v[194:197], v[30:33]
	v_mfma_f32_16x16x32_bf16 v[22:25], v[138:141], v[194:197], v[22:25]
	v_mfma_f32_16x16x32_bf16 v[14:17], v[126:129], v[208:211], v[14:17]
	v_mfma_f32_16x16x32_bf16 v[6:9], v[138:141], v[208:211], v[6:9]
	v_mfma_f32_16x16x32_bf16 v[62:65], v[134:137], v[176:179], v[62:65]
	v_mfma_f32_16x16x32_bf16 v[54:57], v[142:145], v[176:179], v[54:57]
	v_mfma_f32_16x16x32_bf16 v[46:49], v[134:137], v[190:193], v[46:49]
	v_mfma_f32_16x16x32_bf16 v[38:41], v[142:145], v[190:193], v[38:41]
	v_mfma_f32_16x16x32_bf16 v[30:33], v[134:137], v[198:201], v[30:33]
	v_mfma_f32_16x16x32_bf16 v[22:25], v[142:145], v[198:201], v[22:25]
	v_mfma_f32_16x16x32_bf16 v[14:17], v[134:137], v[212:215], v[14:17]
	v_mfma_f32_16x16x32_bf16 v[6:9], v[142:145], v[212:215], v[6:9]
	s_setprio 0
	s_setprio 1
	v_mfma_f32_16x16x32_bf16 v[58:61], v[146:149], v[172:175], v[58:61]
	v_mfma_f32_16x16x32_bf16 v[50:53], v[154:157], v[172:175], v[50:53]
	v_mfma_f32_16x16x32_bf16 v[42:45], v[146:149], v[180:183], v[42:45]
	v_mfma_f32_16x16x32_bf16 v[34:37], v[154:157], v[180:183], v[34:37]
	v_mfma_f32_16x16x32_bf16 v[26:29], v[146:149], v[194:197], v[26:29]
	v_mfma_f32_16x16x32_bf16 v[18:21], v[154:157], v[194:197], v[18:21]
	v_mfma_f32_16x16x32_bf16 v[10:13], v[146:149], v[208:211], v[10:13]
	v_mfma_f32_16x16x32_bf16 v[2:5], v[154:157], v[208:211], v[2:5]
	v_mfma_f32_16x16x32_bf16 v[58:61], v[150:153], v[176:179], v[58:61]
	v_mfma_f32_16x16x32_bf16 v[50:53], v[158:161], v[176:179], v[50:53]
	v_mfma_f32_16x16x32_bf16 v[42:45], v[150:153], v[190:193], v[42:45]
	v_mfma_f32_16x16x32_bf16 v[34:37], v[158:161], v[190:193], v[34:37]
	v_mfma_f32_16x16x32_bf16 v[26:29], v[150:153], v[198:201], v[26:29]
	v_mfma_f32_16x16x32_bf16 v[18:21], v[158:161], v[198:201], v[18:21]
	v_mfma_f32_16x16x32_bf16 v[10:13], v[150:153], v[212:215], v[10:13]
	v_mfma_f32_16x16x32_bf16 v[2:5], v[158:161], v[212:215], v[2:5]
	s_barrier
	s_setprio 0
	s_add_i32 s33, 0, 0x18000
	s_add_i32 s55, 0, 0x1c000
	v_add_u32_e32 v142, s33, v187
	v_add_u32_e32 v158, s55, v187
	ds_read_b128 v[126:129], v142
	ds_read_b128 v[134:137], v142 offset:1024
	ds_read_b128 v[138:141], v142 offset:2048
	ds_read_b128 v[142:145], v142 offset:3072
	ds_read_b128 v[146:149], v158
	ds_read_b128 v[150:153], v158 offset:1024
	ds_read_b128 v[154:157], v158 offset:2048
	ds_read_b128 v[158:161], v158 offset:3072
	s_add_u32 s0, s4, 0x80000
	s_addc_u32 s1, s5, 0
	s_mov_b32 m0, s35
	ds_read_b128 v[172:175], v189 offset:32768
	ds_read_b128 v[176:179], v189 offset:33792
	ds_read_b128 v[180:183], v189 offset:34816
	ds_read_b128 v[190:193], v189 offset:35840
	ds_read_b128 v[194:197], v189 offset:36864
	ds_read_b128 v[198:201], v189 offset:37888
	ds_read_b128 v[208:211], v189 offset:38912
	ds_read_b128 v[212:215], v189 offset:39936
	global_load_lds_dwordx4 v166, s[0:1]
	s_mov_b32 m0, s36
	s_nop 0
	global_load_lds_dwordx4 v164, s[0:1]
	s_waitcnt vmcnt(8)
	s_waitcnt lgkmcnt(0)
	s_setprio 1
	s_barrier
	v_mfma_f32_16x16x32_bf16 v[130:133], v[126:129], v[172:175], v[130:133]
	v_mfma_f32_16x16x32_bf16 v[118:121], v[138:141], v[172:175], v[118:121]
	v_mfma_f32_16x16x32_bf16 v[110:113], v[126:129], v[180:183], v[110:113]
	v_mfma_f32_16x16x32_bf16 v[102:105], v[138:141], v[180:183], v[102:105]
	v_mfma_f32_16x16x32_bf16 v[94:97], v[126:129], v[194:197], v[94:97]
	v_mfma_f32_16x16x32_bf16 v[86:89], v[138:141], v[194:197], v[86:89]
	v_mfma_f32_16x16x32_bf16 v[78:81], v[126:129], v[208:211], v[78:81]
	v_mfma_f32_16x16x32_bf16 v[70:73], v[138:141], v[208:211], v[70:73]
	v_mfma_f32_16x16x32_bf16 v[130:133], v[134:137], v[176:179], v[130:133]
	v_mfma_f32_16x16x32_bf16 v[118:121], v[142:145], v[176:179], v[118:121]
	v_mfma_f32_16x16x32_bf16 v[110:113], v[134:137], v[190:193], v[110:113]
	v_mfma_f32_16x16x32_bf16 v[102:105], v[142:145], v[190:193], v[102:105]
	v_mfma_f32_16x16x32_bf16 v[94:97], v[134:137], v[198:201], v[94:97]
	v_mfma_f32_16x16x32_bf16 v[86:89], v[142:145], v[198:201], v[86:89]
	v_mfma_f32_16x16x32_bf16 v[78:81], v[134:137], v[212:215], v[78:81]
	v_mfma_f32_16x16x32_bf16 v[70:73], v[142:145], v[212:215], v[70:73]
	s_setprio 0
	s_setprio 1
	v_mfma_f32_16x16x32_bf16 v[122:125], v[146:149], v[172:175], v[122:125]
	v_mfma_f32_16x16x32_bf16 v[114:117], v[154:157], v[172:175], v[114:117]
	v_mfma_f32_16x16x32_bf16 v[106:109], v[146:149], v[180:183], v[106:109]
	v_mfma_f32_16x16x32_bf16 v[98:101], v[154:157], v[180:183], v[98:101]
	v_mfma_f32_16x16x32_bf16 v[90:93], v[146:149], v[194:197], v[90:93]
	v_mfma_f32_16x16x32_bf16 v[82:85], v[154:157], v[194:197], v[82:85]
	v_mfma_f32_16x16x32_bf16 v[74:77], v[146:149], v[208:211], v[74:77]
	v_mfma_f32_16x16x32_bf16 v[66:69], v[154:157], v[208:211], v[66:69]
	v_mfma_f32_16x16x32_bf16 v[122:125], v[150:153], v[176:179], v[122:125]
	v_mfma_f32_16x16x32_bf16 v[114:117], v[158:161], v[176:179], v[114:117]
	v_mfma_f32_16x16x32_bf16 v[106:109], v[150:153], v[190:193], v[106:109]
	v_mfma_f32_16x16x32_bf16 v[98:101], v[158:161], v[190:193], v[98:101]
	v_mfma_f32_16x16x32_bf16 v[90:93], v[150:153], v[198:201], v[90:93]
	v_mfma_f32_16x16x32_bf16 v[82:85], v[158:161], v[198:201], v[82:85]
	v_mfma_f32_16x16x32_bf16 v[74:77], v[150:153], v[212:215], v[74:77]
	v_mfma_f32_16x16x32_bf16 v[66:69], v[158:161], v[212:215], v[66:69]
	s_barrier
	s_setprio 0
	s_add_i32 s0, s33, s34
	v_lshl_add_u64 v[184:185], v[184:185], 0, s[80:81]
	s_mov_b32 m0, s0
	ds_read_b128 v[172:175], v189 offset:49152
	ds_read_b128 v[176:179], v189 offset:50176
	ds_read_b128 v[180:183], v189 offset:51200
	ds_read_b128 v[190:193], v189 offset:52224
	ds_read_b128 v[194:197], v189 offset:53248
	ds_read_b128 v[198:201], v189 offset:54272
	ds_read_b128 v[208:211], v189 offset:55296
	ds_read_b128 v[212:215], v189 offset:56320
	global_load_lds_dwordx4 v[184:185], off
	s_add_i32 m0, s0, 0x2000
	s_add_u32 s0, s2, 0x80080
	v_lshl_add_u64 v[184:185], v[204:205], 0, s[80:81]
	s_addc_u32 s1, s3, 0
	s_add_i32 s2, s55, s34
	global_load_lds_dwordx4 v[184:185], off
	s_mov_b32 m0, s2
	s_nop 0
	global_load_lds_dwordx4 v202, s[0:1]
	s_add_i32 m0, s2, 0x2000
	s_nop 0
	global_load_lds_dwordx4 v162, s[0:1]
	v_lshl_add_u64 v[184:185], v[206:207], 0, s[80:81]
	s_mov_b32 m0, s39
	s_nop 0
	global_load_lds_dwordx4 v[184:185], off
	v_lshl_add_u64 v[184:185], v[216:217], 0, s[80:81]
	s_mov_b32 m0, s40
	s_nop 0
	global_load_lds_dwordx4 v[184:185], off
	s_waitcnt vmcnt(8)
	s_waitcnt lgkmcnt(0)
	s_setprio 1
	s_barrier
	v_mfma_f32_16x16x32_bf16 v[62:65], v[126:129], v[172:175], v[62:65]
	v_mfma_f32_16x16x32_bf16 v[54:57], v[138:141], v[172:175], v[54:57]
	v_mfma_f32_16x16x32_bf16 v[46:49], v[126:129], v[180:183], v[46:49]
	v_mfma_f32_16x16x32_bf16 v[38:41], v[138:141], v[180:183], v[38:41]
	v_mfma_f32_16x16x32_bf16 v[30:33], v[126:129], v[194:197], v[30:33]
	v_mfma_f32_16x16x32_bf16 v[22:25], v[138:141], v[194:197], v[22:25]
	v_mfma_f32_16x16x32_bf16 v[14:17], v[126:129], v[208:211], v[14:17]
	v_mfma_f32_16x16x32_bf16 v[6:9], v[138:141], v[208:211], v[6:9]
	v_mfma_f32_16x16x32_bf16 v[62:65], v[134:137], v[176:179], v[62:65]
	v_mfma_f32_16x16x32_bf16 v[54:57], v[142:145], v[176:179], v[54:57]
	v_mfma_f32_16x16x32_bf16 v[46:49], v[134:137], v[190:193], v[46:49]
	v_mfma_f32_16x16x32_bf16 v[38:41], v[142:145], v[190:193], v[38:41]
	v_mfma_f32_16x16x32_bf16 v[30:33], v[134:137], v[198:201], v[30:33]
	v_mfma_f32_16x16x32_bf16 v[22:25], v[142:145], v[198:201], v[22:25]
	v_mfma_f32_16x16x32_bf16 v[14:17], v[134:137], v[212:215], v[14:17]
	v_mfma_f32_16x16x32_bf16 v[6:9], v[142:145], v[212:215], v[6:9]
	s_setprio 0
	s_setprio 1
	v_mfma_f32_16x16x32_bf16 v[58:61], v[146:149], v[172:175], v[58:61]
	v_mfma_f32_16x16x32_bf16 v[50:53], v[154:157], v[172:175], v[50:53]
	v_mfma_f32_16x16x32_bf16 v[42:45], v[146:149], v[180:183], v[42:45]
	v_mfma_f32_16x16x32_bf16 v[34:37], v[154:157], v[180:183], v[34:37]
	v_mfma_f32_16x16x32_bf16 v[26:29], v[146:149], v[194:197], v[26:29]
	v_mfma_f32_16x16x32_bf16 v[18:21], v[154:157], v[194:197], v[18:21]
	v_mfma_f32_16x16x32_bf16 v[10:13], v[146:149], v[208:211], v[10:13]
	v_mfma_f32_16x16x32_bf16 v[2:5], v[154:157], v[208:211], v[2:5]
	v_mfma_f32_16x16x32_bf16 v[58:61], v[150:153], v[176:179], v[58:61]
	v_mfma_f32_16x16x32_bf16 v[50:53], v[158:161], v[176:179], v[50:53]
	v_mfma_f32_16x16x32_bf16 v[42:45], v[150:153], v[190:193], v[42:45]
	v_mfma_f32_16x16x32_bf16 v[34:37], v[158:161], v[190:193], v[34:37]
	v_mfma_f32_16x16x32_bf16 v[26:29], v[150:153], v[198:201], v[26:29]
	v_mfma_f32_16x16x32_bf16 v[18:21], v[158:161], v[198:201], v[18:21]
	v_mfma_f32_16x16x32_bf16 v[10:13], v[150:153], v[212:215], v[10:13]
	v_mfma_f32_16x16x32_bf16 v[2:5], v[158:161], v[212:215], v[2:5]
	s_barrier
	s_setprio 0
	s_add_i32 s61, s61, 2
	s_add_u32 s26, s26, 0x100
	s_addc_u32 s27, s27, 0
	s_add_u32 s59, s59, 0x100
	s_addc_u32 s60, s60, 0
	s_cmp_gt_u32 s61, 29
	s_cbranch_scc0 .LBB0_1428
	s_and_b64 vcc, exec, s[10:11]
	s_cbranch_vccz .LBB0_1431
	s_barrier

.LBB0_1594:
	s_add_u32 s0, s28, 0xfff80080
	s_addc_u32 s1, s29, -1
	s_add_i32 s33, 0, 0x10000
	s_cmp_eq_u32 s61, 28
	s_cselect_b32 s5, s19, s1
	s_cselect_b32 s4, s49, s0
	v_add_u32_e32 v140, s33, v143
	s_cselect_b32 s3, s17, s60
	s_cselect_b32 s2, s58, s59
	s_add_i32 s55, 0, 0x14000
	ds_read_b128 v[146:149], v140
	ds_read_b128 v[150:153], v140 offset:1024
	ds_read_b128 v[154:157], v140 offset:2048
	ds_read_b128 v[158:161], v140 offset:3072
	v_add_u32_e32 v140, s55, v143
	ds_read_b128 v[162:165], v140
	ds_read_b128 v[166:169], v140 offset:1024
	ds_read_b128 v[170:173], v140 offset:2048
	ds_read_b128 v[174:177], v140 offset:3072
	s_add_i32 m0, s25, 0xc000
	ds_read_b128 v[178:181], v145
	ds_read_b128 v[182:185], v145 offset:1024
	ds_read_b128 v[186:189], v145 offset:2048
	ds_read_b128 v[190:193], v145 offset:3072
	ds_read_b128 v[194:197], v145 offset:4096
	ds_read_b128 v[198:201], v145 offset:5120
	ds_read_b128 v[208:211], v145 offset:6144
	ds_read_b128 v[212:215], v145 offset:7168
	global_load_lds_dwordx4 v136, s[28:29]
	s_add_i32 m0, s25, 0xe000
	s_nop 0
	global_load_lds_dwordx4 v138, s[28:29]
	s_waitcnt vmcnt(8)
	s_waitcnt lgkmcnt(0)
	s_setprio 1
	s_barrier
	v_mfma_f32_16x16x32_bf16 v[126:129], v[146:149], v[178:181], v[126:129]
	v_mfma_f32_16x16x32_bf16 v[118:121], v[154:157], v[178:181], v[118:121]
	v_mfma_f32_16x16x32_bf16 v[110:113], v[146:149], v[186:189], v[110:113]
	v_mfma_f32_16x16x32_bf16 v[102:105], v[154:157], v[186:189], v[102:105]
	v_mfma_f32_16x16x32_bf16 v[94:97], v[146:149], v[194:197], v[94:97]
	v_mfma_f32_16x16x32_bf16 v[86:89], v[154:157], v[194:197], v[86:89]
	v_mfma_f32_16x16x32_bf16 v[78:81], v[146:149], v[208:211], v[78:81]
	v_mfma_f32_16x16x32_bf16 v[70:73], v[154:157], v[208:211], v[70:73]
	v_mfma_f32_16x16x32_bf16 v[126:129], v[150:153], v[182:185], v[126:129]
	v_mfma_f32_16x16x32_bf16 v[118:121], v[158:161], v[182:185], v[118:121]
	v_mfma_f32_16x16x32_bf16 v[110:113], v[150:153], v[190:193], v[110:113]
	v_mfma_f32_16x16x32_bf16 v[102:105], v[158:161], v[190:193], v[102:105]
	v_mfma_f32_16x16x32_bf16 v[94:97], v[150:153], v[198:201], v[94:97]
	v_mfma_f32_16x16x32_bf16 v[86:89], v[158:161], v[198:201], v[86:89]
	v_mfma_f32_16x16x32_bf16 v[78:81], v[150:153], v[212:215], v[78:81]
	v_mfma_f32_16x16x32_bf16 v[70:73], v[158:161], v[212:215], v[70:73]
	s_setprio 0
	s_setprio 1
	v_mfma_f32_16x16x32_bf16 v[122:125], v[162:165], v[178:181], v[122:125]
	v_mfma_f32_16x16x32_bf16 v[114:117], v[170:173], v[178:181], v[114:117]
	v_mfma_f32_16x16x32_bf16 v[106:109], v[162:165], v[186:189], v[106:109]
	v_mfma_f32_16x16x32_bf16 v[98:101], v[170:173], v[186:189], v[98:101]
	v_mfma_f32_16x16x32_bf16 v[90:93], v[162:165], v[194:197], v[90:93]
	v_mfma_f32_16x16x32_bf16 v[82:85], v[170:173], v[194:197], v[82:85]
	v_mfma_f32_16x16x32_bf16 v[74:77], v[162:165], v[208:211], v[74:77]
	v_mfma_f32_16x16x32_bf16 v[66:69], v[170:173], v[208:211], v[66:69]
	v_mfma_f32_16x16x32_bf16 v[122:125], v[166:169], v[182:185], v[122:125]
	v_mfma_f32_16x16x32_bf16 v[114:117], v[174:177], v[182:185], v[114:117]
	v_mfma_f32_16x16x32_bf16 v[106:109], v[166:169], v[190:193], v[106:109]
	v_mfma_f32_16x16x32_bf16 v[98:101], v[174:177], v[190:193], v[98:101]
	v_mfma_f32_16x16x32_bf16 v[90:93], v[166:169], v[198:201], v[90:93]
	v_mfma_f32_16x16x32_bf16 v[82:85], v[174:177], v[198:201], v[82:85]
	v_mfma_f32_16x16x32_bf16 v[74:77], v[166:169], v[212:215], v[74:77]
	v_mfma_f32_16x16x32_bf16 v[66:69], v[174:177], v[212:215], v[66:69]
	s_barrier
	s_setprio 0
	s_add_i32 s0, s33, s36
	v_lshl_add_u64 v[140:141], s[2:3], 0, v[202:203]
	s_mov_b32 m0, s0
	ds_read_b128 v[178:181], v145 offset:16384
	ds_read_b128 v[182:185], v145 offset:17408
	ds_read_b128 v[186:189], v145 offset:18432
	ds_read_b128 v[190:193], v145 offset:19456
	ds_read_b128 v[194:197], v145 offset:20480
	ds_read_b128 v[198:201], v145 offset:21504
	ds_read_b128 v[208:211], v145 offset:22528
	ds_read_b128 v[212:215], v145 offset:23552
	global_load_lds_dwordx4 v[140:141], off
	s_add_i32 m0, s0, 0x2000
	s_add_u32 s0, s2, 0x80000
	v_lshl_add_u64 v[204:205], s[2:3], 0, v[130:131]
	s_addc_u32 s1, s3, 0
	s_add_i32 s33, s55, s36
	global_load_lds_dwordx4 v[204:205], off
	s_mov_b32 m0, s33
	v_lshl_add_u64 v[216:217], s[4:5], 0, v[132:133]
	global_load_lds_dwordx4 v202, s[0:1]
	s_add_i32 m0, s33, 0x2000
	s_nop 0
	global_load_lds_dwordx4 v130, s[0:1]
	v_lshl_add_u64 v[206:207], s[4:5], 0, v[134:135]
	s_mov_b32 m0, s25
	s_nop 0
	global_load_lds_dwordx4 v[206:207], off
	s_mov_b32 m0, s27
	s_nop 0
	global_load_lds_dwordx4 v[216:217], off
	s_waitcnt vmcnt(8)
	s_waitcnt lgkmcnt(0)
	s_setprio 1
	s_barrier
	v_mfma_f32_16x16x32_bf16 v[62:65], v[146:149], v[178:181], v[62:65]
	v_mfma_f32_16x16x32_bf16 v[54:57], v[154:157], v[178:181], v[54:57]
	v_mfma_f32_16x16x32_bf16 v[46:49], v[146:149], v[186:189], v[46:49]
	v_mfma_f32_16x16x32_bf16 v[38:41], v[154:157], v[186:189], v[38:41]
	v_mfma_f32_16x16x32_bf16 v[30:33], v[146:149], v[194:197], v[30:33]
	v_mfma_f32_16x16x32_bf16 v[22:25], v[154:157], v[194:197], v[22:25]
	v_mfma_f32_16x16x32_bf16 v[14:17], v[146:149], v[208:211], v[14:17]
	v_mfma_f32_16x16x32_bf16 v[6:9], v[154:157], v[208:211], v[6:9]
	v_mfma_f32_16x16x32_bf16 v[62:65], v[150:153], v[182:185], v[62:65]
	v_mfma_f32_16x16x32_bf16 v[54:57], v[158:161], v[182:185], v[54:57]
	v_mfma_f32_16x16x32_bf16 v[46:49], v[150:153], v[190:193], v[46:49]
	v_mfma_f32_16x16x32_bf16 v[38:41], v[158:161], v[190:193], v[38:41]
	v_mfma_f32_16x16x32_bf16 v[30:33], v[150:153], v[198:201], v[30:33]
	v_mfma_f32_16x16x32_bf16 v[22:25], v[158:161], v[198:201], v[22:25]
	v_mfma_f32_16x16x32_bf16 v[14:17], v[150:153], v[212:215], v[14:17]
	v_mfma_f32_16x16x32_bf16 v[6:9], v[158:161], v[212:215], v[6:9]
	s_setprio 0
	s_setprio 1
	v_mfma_f32_16x16x32_bf16 v[58:61], v[162:165], v[178:181], v[58:61]
	v_mfma_f32_16x16x32_bf16 v[50:53], v[170:173], v[178:181], v[50:53]
	v_mfma_f32_16x16x32_bf16 v[42:45], v[162:165], v[186:189], v[42:45]
	v_mfma_f32_16x16x32_bf16 v[34:37], v[170:173], v[186:189], v[34:37]
	v_mfma_f32_16x16x32_bf16 v[26:29], v[162:165], v[194:197], v[26:29]
	v_mfma_f32_16x16x32_bf16 v[18:21], v[170:173], v[194:197], v[18:21]
	v_mfma_f32_16x16x32_bf16 v[10:13], v[162:165], v[208:211], v[10:13]
	v_mfma_f32_16x16x32_bf16 v[2:5], v[170:173], v[208:211], v[2:5]
	v_mfma_f32_16x16x32_bf16 v[58:61], v[166:169], v[182:185], v[58:61]
	v_mfma_f32_16x16x32_bf16 v[50:53], v[174:177], v[182:185], v[50:53]
	v_mfma_f32_16x16x32_bf16 v[42:45], v[166:169], v[190:193], v[42:45]
	v_mfma_f32_16x16x32_bf16 v[34:37], v[174:177], v[190:193], v[34:37]
	v_mfma_f32_16x16x32_bf16 v[26:29], v[166:169], v[198:201], v[26:29]
	v_mfma_f32_16x16x32_bf16 v[18:21], v[174:177], v[198:201], v[18:21]
	v_mfma_f32_16x16x32_bf16 v[10:13], v[166:169], v[212:215], v[10:13]
	v_mfma_f32_16x16x32_bf16 v[2:5], v[174:177], v[212:215], v[2:5]
	s_barrier
	s_setprio 0
	s_add_i32 s33, 0, 0x18000
	s_add_i32 s55, 0, 0x1c000
	v_add_u32_e32 v158, s33, v143
	v_add_u32_e32 v174, s55, v143
	ds_read_b128 v[146:149], v158
	ds_read_b128 v[150:153], v158 offset:1024
	ds_read_b128 v[154:157], v158 offset:2048
	ds_read_b128 v[158:161], v158 offset:3072
	ds_read_b128 v[162:165], v174
	ds_read_b128 v[166:169], v174 offset:1024
	ds_read_b128 v[170:173], v174 offset:2048
	ds_read_b128 v[174:177], v174 offset:3072
	s_add_u32 s0, s4, 0x80000
	s_addc_u32 s1, s5, 0
	s_mov_b32 m0, s37
	ds_read_b128 v[178:181], v145 offset:32768
	ds_read_b128 v[182:185], v145 offset:33792
	ds_read_b128 v[186:189], v145 offset:34816
	ds_read_b128 v[190:193], v145 offset:35840
	ds_read_b128 v[194:197], v145 offset:36864
	ds_read_b128 v[198:201], v145 offset:37888
	ds_read_b128 v[208:211], v145 offset:38912
	ds_read_b128 v[212:215], v145 offset:39936
	global_load_lds_dwordx4 v134, s[0:1]
	s_mov_b32 m0, s38
	s_nop 0
	global_load_lds_dwordx4 v132, s[0:1]
	s_waitcnt vmcnt(8)
	s_waitcnt lgkmcnt(0)
	s_setprio 1
	s_barrier
	v_mfma_f32_16x16x32_bf16 v[126:129], v[146:149], v[178:181], v[126:129]
	v_mfma_f32_16x16x32_bf16 v[118:121], v[154:157], v[178:181], v[118:121]
	v_mfma_f32_16x16x32_bf16 v[110:113], v[146:149], v[186:189], v[110:113]
	v_mfma_f32_16x16x32_bf16 v[102:105], v[154:157], v[186:189], v[102:105]
	v_mfma_f32_16x16x32_bf16 v[94:97], v[146:149], v[194:197], v[94:97]
	v_mfma_f32_16x16x32_bf16 v[86:89], v[154:157], v[194:197], v[86:89]
	v_mfma_f32_16x16x32_bf16 v[78:81], v[146:149], v[208:211], v[78:81]
	v_mfma_f32_16x16x32_bf16 v[70:73], v[154:157], v[208:211], v[70:73]
	v_mfma_f32_16x16x32_bf16 v[126:129], v[150:153], v[182:185], v[126:129]
	v_mfma_f32_16x16x32_bf16 v[118:121], v[158:161], v[182:185], v[118:121]
	v_mfma_f32_16x16x32_bf16 v[110:113], v[150:153], v[190:193], v[110:113]
	v_mfma_f32_16x16x32_bf16 v[102:105], v[158:161], v[190:193], v[102:105]
	v_mfma_f32_16x16x32_bf16 v[94:97], v[150:153], v[198:201], v[94:97]
	v_mfma_f32_16x16x32_bf16 v[86:89], v[158:161], v[198:201], v[86:89]
	v_mfma_f32_16x16x32_bf16 v[78:81], v[150:153], v[212:215], v[78:81]
	v_mfma_f32_16x16x32_bf16 v[70:73], v[158:161], v[212:215], v[70:73]
	s_setprio 0
	s_setprio 1
	v_mfma_f32_16x16x32_bf16 v[122:125], v[162:165], v[178:181], v[122:125]
	v_mfma_f32_16x16x32_bf16 v[114:117], v[170:173], v[178:181], v[114:117]
	v_mfma_f32_16x16x32_bf16 v[106:109], v[162:165], v[186:189], v[106:109]
	v_mfma_f32_16x16x32_bf16 v[98:101], v[170:173], v[186:189], v[98:101]
	v_mfma_f32_16x16x32_bf16 v[90:93], v[162:165], v[194:197], v[90:93]
	v_mfma_f32_16x16x32_bf16 v[82:85], v[170:173], v[194:197], v[82:85]
	v_mfma_f32_16x16x32_bf16 v[74:77], v[162:165], v[208:211], v[74:77]
	v_mfma_f32_16x16x32_bf16 v[66:69], v[170:173], v[208:211], v[66:69]
	v_mfma_f32_16x16x32_bf16 v[122:125], v[166:169], v[182:185], v[122:125]
	v_mfma_f32_16x16x32_bf16 v[114:117], v[174:177], v[182:185], v[114:117]
	v_mfma_f32_16x16x32_bf16 v[106:109], v[166:169], v[190:193], v[106:109]
	v_mfma_f32_16x16x32_bf16 v[98:101], v[174:177], v[190:193], v[98:101]
	v_mfma_f32_16x16x32_bf16 v[90:93], v[166:169], v[198:201], v[90:93]
	v_mfma_f32_16x16x32_bf16 v[82:85], v[174:177], v[198:201], v[82:85]
	v_mfma_f32_16x16x32_bf16 v[74:77], v[166:169], v[212:215], v[74:77]
	v_mfma_f32_16x16x32_bf16 v[66:69], v[174:177], v[212:215], v[66:69]
	s_barrier
	s_setprio 0
	s_add_i32 s0, s33, s36
	v_lshl_add_u64 v[140:141], v[140:141], 0, s[80:81]
	s_mov_b32 m0, s0
	ds_read_b128 v[178:181], v145 offset:49152
	ds_read_b128 v[182:185], v145 offset:50176
	ds_read_b128 v[186:189], v145 offset:51200
	ds_read_b128 v[190:193], v145 offset:52224
	ds_read_b128 v[194:197], v145 offset:53248
	ds_read_b128 v[198:201], v145 offset:54272
	ds_read_b128 v[208:211], v145 offset:55296
	ds_read_b128 v[212:215], v145 offset:56320
	global_load_lds_dwordx4 v[140:141], off
	s_add_i32 m0, s0, 0x2000
	s_add_u32 s0, s2, 0x80080
	v_lshl_add_u64 v[140:141], v[204:205], 0, s[80:81]
	s_addc_u32 s1, s3, 0
	s_add_i32 s2, s55, s36
	global_load_lds_dwordx4 v[140:141], off
	s_mov_b32 m0, s2
	s_nop 0
	global_load_lds_dwordx4 v202, s[0:1]
	s_add_i32 m0, s2, 0x2000
	s_nop 0
	global_load_lds_dwordx4 v130, s[0:1]
	v_lshl_add_u64 v[140:141], v[206:207], 0, s[80:81]
	s_mov_b32 m0, s39
	s_nop 0
	global_load_lds_dwordx4 v[140:141], off
	v_lshl_add_u64 v[140:141], v[216:217], 0, s[80:81]
	s_mov_b32 m0, s40
	s_nop 0
	global_load_lds_dwordx4 v[140:141], off
	s_waitcnt vmcnt(8)
	s_waitcnt lgkmcnt(0)
	s_setprio 1
	s_barrier
	v_mfma_f32_16x16x32_bf16 v[62:65], v[146:149], v[178:181], v[62:65]
	v_mfma_f32_16x16x32_bf16 v[54:57], v[154:157], v[178:181], v[54:57]
	v_mfma_f32_16x16x32_bf16 v[46:49], v[146:149], v[186:189], v[46:49]
	v_mfma_f32_16x16x32_bf16 v[38:41], v[154:157], v[186:189], v[38:41]
	v_mfma_f32_16x16x32_bf16 v[30:33], v[146:149], v[194:197], v[30:33]
	v_mfma_f32_16x16x32_bf16 v[22:25], v[154:157], v[194:197], v[22:25]
	v_mfma_f32_16x16x32_bf16 v[14:17], v[146:149], v[208:211], v[14:17]
	v_mfma_f32_16x16x32_bf16 v[6:9], v[154:157], v[208:211], v[6:9]
	v_mfma_f32_16x16x32_bf16 v[62:65], v[150:153], v[182:185], v[62:65]
	v_mfma_f32_16x16x32_bf16 v[54:57], v[158:161], v[182:185], v[54:57]
	v_mfma_f32_16x16x32_bf16 v[46:49], v[150:153], v[190:193], v[46:49]
	v_mfma_f32_16x16x32_bf16 v[38:41], v[158:161], v[190:193], v[38:41]
	v_mfma_f32_16x16x32_bf16 v[30:33], v[150:153], v[198:201], v[30:33]
	v_mfma_f32_16x16x32_bf16 v[22:25], v[158:161], v[198:201], v[22:25]
	v_mfma_f32_16x16x32_bf16 v[14:17], v[150:153], v[212:215], v[14:17]
	v_mfma_f32_16x16x32_bf16 v[6:9], v[158:161], v[212:215], v[6:9]
	s_setprio 0
	s_setprio 1
	v_mfma_f32_16x16x32_bf16 v[58:61], v[162:165], v[178:181], v[58:61]
	v_mfma_f32_16x16x32_bf16 v[50:53], v[170:173], v[178:181], v[50:53]
	v_mfma_f32_16x16x32_bf16 v[42:45], v[162:165], v[186:189], v[42:45]
	v_mfma_f32_16x16x32_bf16 v[34:37], v[170:173], v[186:189], v[34:37]
	v_mfma_f32_16x16x32_bf16 v[26:29], v[162:165], v[194:197], v[26:29]
	v_mfma_f32_16x16x32_bf16 v[18:21], v[170:173], v[194:197], v[18:21]
	v_mfma_f32_16x16x32_bf16 v[10:13], v[162:165], v[208:211], v[10:13]
	v_mfma_f32_16x16x32_bf16 v[2:5], v[170:173], v[208:211], v[2:5]
	v_mfma_f32_16x16x32_bf16 v[58:61], v[166:169], v[182:185], v[58:61]
	v_mfma_f32_16x16x32_bf16 v[50:53], v[174:177], v[182:185], v[50:53]
	v_mfma_f32_16x16x32_bf16 v[42:45], v[166:169], v[190:193], v[42:45]
	v_mfma_f32_16x16x32_bf16 v[34:37], v[174:177], v[190:193], v[34:37]
	v_mfma_f32_16x16x32_bf16 v[26:29], v[166:169], v[198:201], v[26:29]
	v_mfma_f32_16x16x32_bf16 v[18:21], v[174:177], v[198:201], v[18:21]
	v_mfma_f32_16x16x32_bf16 v[10:13], v[166:169], v[212:215], v[10:13]
	v_mfma_f32_16x16x32_bf16 v[2:5], v[174:177], v[212:215], v[2:5]
	s_barrier
	s_setprio 0
	s_add_i32 s61, s61, 2
	s_add_u32 s28, s28, 0x100
	s_addc_u32 s29, s29, 0
	s_add_u32 s59, s59, 0x100
	s_addc_u32 s60, s60, 0
	s_cmp_gt_u32 s61, 29
	s_cbranch_scc0 .LBB0_1594
	s_and_b64 vcc, exec, s[14:15]
	s_cbranch_vccz .LBB0_1597
	s_barrier

.LBB0_1718:
	s_add_u32 s18, s4, 0x100
	s_addc_u32 s19, s5, 0
	s_add_i32 s0, 0, 0x10000
	s_cmpk_eq_i32 s59, 0x54
	s_cselect_b32 s23, s9, s19
	s_cselect_b32 s22, s8, s18
	s_cselect_b32 s21, s17, s58
	s_cselect_b32 s20, s16, s49
	s_add_i32 s33, 0, 0x14000
	v_add_u32_e32 v98, s0, v205
	v_add_u32_e32 v134, s33, v205
	ds_read_b128 v[78:81], v98
	ds_read_b128 v[82:85], v98 offset:1024
	ds_read_b128 v[94:97], v98 offset:2048
	ds_read_b128 v[98:101], v98 offset:3072
	ds_read_b128 v[106:109], v134
	ds_read_b128 v[110:113], v134 offset:1024
	ds_read_b128 v[126:129], v134 offset:2048
	ds_read_b128 v[134:137], v134 offset:3072
	s_add_i32 m0, s27, 0xc000
	ds_read_b128 v[146:149], v239
	ds_read_b128 v[158:161], v239 offset:1024
	ds_read_b128 v[166:169], v239 offset:2048
	ds_read_b128 v[174:177], v239 offset:3072
	ds_read_b128 v[178:181], v239 offset:4096
	ds_read_b128 v[182:185], v239 offset:5120
	ds_read_b128 v[186:189], v239 offset:6144
	ds_read_b128 v[190:193], v239 offset:7168
	global_load_lds_dwordx4 v214, s[4:5]
	s_add_i32 m0, s27, 0xe000
	s_nop 0
	global_load_lds_dwordx4 v216, s[4:5]
	s_waitcnt vmcnt(8)
	s_waitcnt lgkmcnt(0)
	s_setprio 1
	s_barrier
	v_mfma_f32_16x16x32_bf16 v[170:173], v[78:81], v[146:149], v[170:173]
	v_mfma_f32_16x16x32_bf16 v[162:165], v[94:97], v[146:149], v[162:165]
	v_mfma_f32_16x16x32_bf16 v[142:145], v[78:81], v[166:169], v[142:145]
	v_mfma_f32_16x16x32_bf16 v[138:141], v[94:97], v[166:169], v[138:141]
	v_mfma_f32_16x16x32_bf16 v[118:121], v[78:81], v[178:181], v[118:121]
	v_mfma_f32_16x16x32_bf16 v[114:117], v[94:97], v[178:181], v[114:117]
	v_mfma_f32_16x16x32_bf16 v[86:89], v[78:81], v[186:189], v[86:89]
	v_mfma_f32_16x16x32_bf16 v[74:77], v[94:97], v[186:189], v[74:77]
	v_mfma_f32_16x16x32_bf16 v[170:173], v[82:85], v[158:161], v[170:173]
	v_mfma_f32_16x16x32_bf16 v[162:165], v[98:101], v[158:161], v[162:165]
	v_mfma_f32_16x16x32_bf16 v[142:145], v[82:85], v[174:177], v[142:145]
	v_mfma_f32_16x16x32_bf16 v[138:141], v[98:101], v[174:177], v[138:141]
	v_mfma_f32_16x16x32_bf16 v[118:121], v[82:85], v[182:185], v[118:121]
	v_mfma_f32_16x16x32_bf16 v[114:117], v[98:101], v[182:185], v[114:117]
	v_mfma_f32_16x16x32_bf16 v[86:89], v[82:85], v[190:193], v[86:89]
	v_mfma_f32_16x16x32_bf16 v[74:77], v[98:101], v[190:193], v[74:77]
	s_setprio 0
	s_setprio 1
	v_mfma_f32_16x16x32_bf16 v[154:157], v[106:109], v[146:149], v[154:157]
	v_mfma_f32_16x16x32_bf16 v[130:133], v[106:109], v[166:169], v[130:133]
	v_mfma_f32_16x16x32_bf16 v[122:125], v[126:129], v[166:169], v[122:125]
	v_mfma_f32_16x16x32_bf16 v[102:105], v[106:109], v[178:181], v[102:105]
	v_mfma_f32_16x16x32_bf16 v[90:93], v[126:129], v[178:181], v[90:93]
	v_mfma_f32_16x16x32_bf16 v[70:73], v[106:109], v[186:189], v[70:73]
	v_mfma_f32_16x16x32_bf16 v[66:69], v[126:129], v[186:189], v[66:69]
	v_mfma_f32_16x16x32_bf16 v[154:157], v[110:113], v[158:161], v[154:157]
	v_mfma_f32_16x16x32_bf16 v[146:149], v[126:129], v[146:149], v[150:153]
	v_mfma_f32_16x16x32_bf16 v[130:133], v[110:113], v[174:177], v[130:133]
	v_mfma_f32_16x16x32_bf16 v[122:125], v[134:137], v[174:177], v[122:125]
	v_mfma_f32_16x16x32_bf16 v[102:105], v[110:113], v[182:185], v[102:105]
	v_mfma_f32_16x16x32_bf16 v[90:93], v[134:137], v[182:185], v[90:93]
	v_mfma_f32_16x16x32_bf16 v[70:73], v[110:113], v[190:193], v[70:73]
	v_mfma_f32_16x16x32_bf16 v[66:69], v[134:137], v[190:193], v[66:69]
	v_mfma_f32_16x16x32_bf16 v[146:149], v[134:137], v[158:161], v[146:149]
	s_barrier
	s_setprio 0
	s_add_i32 s0, s0, s26
	v_lshl_add_u64 v[194:195], s[20:21], 0, v[202:203]
	s_mov_b32 m0, s0
	ds_read_b128 v[150:153], v239 offset:16384
	ds_read_b128 v[158:161], v239 offset:17408
	ds_read_b128 v[166:169], v239 offset:18432
	ds_read_b128 v[174:177], v239 offset:19456
	ds_read_b128 v[178:181], v239 offset:20480
	ds_read_b128 v[182:185], v239 offset:21504
	ds_read_b128 v[186:189], v239 offset:22528
	ds_read_b128 v[190:193], v239 offset:23552
	global_load_lds_dwordx4 v[194:195], off
	s_add_i32 m0, s0, 0x2000
	s_add_u32 s0, s20, 0x160000
	v_lshl_add_u64 v[196:197], s[20:21], 0, v[208:209]
	s_addc_u32 s1, s21, 0
	s_add_i32 s4, s33, s26
	global_load_lds_dwordx4 v[196:197], off
	s_mov_b32 m0, s4
	v_lshl_add_u64 v[200:201], s[22:23], 0, v[210:211]
	global_load_lds_dwordx4 v202, s[0:1]
	s_add_i32 m0, s4, 0x2000
	s_nop 0
	global_load_lds_dwordx4 v208, s[0:1]
	v_lshl_add_u64 v[198:199], s[22:23], 0, v[212:213]
	s_mov_b32 m0, s27
	s_nop 0
	global_load_lds_dwordx4 v[198:199], off
	s_mov_b32 m0, s28
	s_nop 0
	global_load_lds_dwordx4 v[200:201], off
	s_waitcnt vmcnt(8)
	s_waitcnt lgkmcnt(0)
	s_setprio 1
	s_barrier
	v_mfma_f32_16x16x32_bf16 v[62:65], v[78:81], v[150:153], v[62:65]
	v_mfma_f32_16x16x32_bf16 v[58:61], v[94:97], v[150:153], v[58:61]
	v_mfma_f32_16x16x32_bf16 v[46:49], v[78:81], v[166:169], v[46:49]
	v_mfma_f32_16x16x32_bf16 v[42:45], v[94:97], v[166:169], v[42:45]
	v_mfma_f32_16x16x32_bf16 v[30:33], v[78:81], v[178:181], v[30:33]
	v_mfma_f32_16x16x32_bf16 v[26:29], v[94:97], v[178:181], v[26:29]
	v_mfma_f32_16x16x32_bf16 v[14:17], v[78:81], v[186:189], v[14:17]
	v_mfma_f32_16x16x32_bf16 v[10:13], v[94:97], v[186:189], v[10:13]
	v_mfma_f32_16x16x32_bf16 v[62:65], v[82:85], v[158:161], v[62:65]
	v_mfma_f32_16x16x32_bf16 v[58:61], v[98:101], v[158:161], v[58:61]
	v_mfma_f32_16x16x32_bf16 v[46:49], v[82:85], v[174:177], v[46:49]
	v_mfma_f32_16x16x32_bf16 v[42:45], v[98:101], v[174:177], v[42:45]
	v_mfma_f32_16x16x32_bf16 v[30:33], v[82:85], v[182:185], v[30:33]
	v_mfma_f32_16x16x32_bf16 v[26:29], v[98:101], v[182:185], v[26:29]
	v_mfma_f32_16x16x32_bf16 v[14:17], v[82:85], v[190:193], v[14:17]
	v_mfma_f32_16x16x32_bf16 v[10:13], v[98:101], v[190:193], v[10:13]
	s_setprio 0
	s_setprio 1
	v_mfma_f32_16x16x32_bf16 v[54:57], v[106:109], v[150:153], v[54:57]
	v_mfma_f32_16x16x32_bf16 v[50:53], v[126:129], v[150:153], v[50:53]
	v_mfma_f32_16x16x32_bf16 v[38:41], v[106:109], v[166:169], v[38:41]
	v_mfma_f32_16x16x32_bf16 v[34:37], v[126:129], v[166:169], v[34:37]
	v_mfma_f32_16x16x32_bf16 v[22:25], v[106:109], v[178:181], v[22:25]
	v_mfma_f32_16x16x32_bf16 v[18:21], v[126:129], v[178:181], v[18:21]
	v_mfma_f32_16x16x32_bf16 v[6:9], v[106:109], v[186:189], v[6:9]
	v_mfma_f32_16x16x32_bf16 v[2:5], v[126:129], v[186:189], v[2:5]
	v_mfma_f32_16x16x32_bf16 v[54:57], v[110:113], v[158:161], v[54:57]
	v_mfma_f32_16x16x32_bf16 v[50:53], v[134:137], v[158:161], v[50:53]
	v_mfma_f32_16x16x32_bf16 v[38:41], v[110:113], v[174:177], v[38:41]
	v_mfma_f32_16x16x32_bf16 v[34:37], v[134:137], v[174:177], v[34:37]
	v_mfma_f32_16x16x32_bf16 v[22:25], v[110:113], v[182:185], v[22:25]
	v_mfma_f32_16x16x32_bf16 v[18:21], v[134:137], v[182:185], v[18:21]
	v_mfma_f32_16x16x32_bf16 v[6:9], v[110:113], v[190:193], v[6:9]
	v_mfma_f32_16x16x32_bf16 v[2:5], v[134:137], v[190:193], v[2:5]
	s_barrier
	s_setprio 0
	s_add_i32 s4, 0, 0x18000
	s_add_i32 s5, 0, 0x1c000
	v_add_u32_e32 v98, s4, v205
	v_add_u32_e32 v134, s5, v205
	ds_read_b128 v[78:81], v98
	ds_read_b128 v[82:85], v98 offset:1024
	ds_read_b128 v[94:97], v98 offset:2048
	ds_read_b128 v[98:101], v98 offset:3072
	ds_read_b128 v[106:109], v134
	ds_read_b128 v[110:113], v134 offset:1024
	ds_read_b128 v[126:129], v134 offset:2048
	ds_read_b128 v[134:137], v134 offset:3072
	s_add_u32 s0, s22, 0x160000
	s_addc_u32 s1, s23, 0
	s_mov_b32 m0, s29
	ds_read_b128 v[150:153], v239 offset:32768
	ds_read_b128 v[158:161], v239 offset:33792
	ds_read_b128 v[166:169], v239 offset:34816
	ds_read_b128 v[174:177], v239 offset:35840
	ds_read_b128 v[178:181], v239 offset:36864
	ds_read_b128 v[182:185], v239 offset:37888
	ds_read_b128 v[186:189], v239 offset:38912
	ds_read_b128 v[190:193], v239 offset:39936
	global_load_lds_dwordx4 v212, s[0:1]
	s_mov_b32 m0, s30
	s_nop 0
	global_load_lds_dwordx4 v210, s[0:1]
	s_waitcnt vmcnt(8)
	s_waitcnt lgkmcnt(0)
	s_setprio 1
	s_barrier
	v_mfma_f32_16x16x32_bf16 v[170:173], v[78:81], v[150:153], v[170:173]
	v_mfma_f32_16x16x32_bf16 v[162:165], v[94:97], v[150:153], v[162:165]
	v_mfma_f32_16x16x32_bf16 v[142:145], v[78:81], v[166:169], v[142:145]
	v_mfma_f32_16x16x32_bf16 v[138:141], v[94:97], v[166:169], v[138:141]
	v_mfma_f32_16x16x32_bf16 v[118:121], v[78:81], v[178:181], v[118:121]
	v_mfma_f32_16x16x32_bf16 v[114:117], v[94:97], v[178:181], v[114:117]
	v_mfma_f32_16x16x32_bf16 v[86:89], v[78:81], v[186:189], v[86:89]
	v_mfma_f32_16x16x32_bf16 v[74:77], v[94:97], v[186:189], v[74:77]
	v_mfma_f32_16x16x32_bf16 v[170:173], v[82:85], v[158:161], v[170:173]
	v_mfma_f32_16x16x32_bf16 v[162:165], v[98:101], v[158:161], v[162:165]
	v_mfma_f32_16x16x32_bf16 v[142:145], v[82:85], v[174:177], v[142:145]
	v_mfma_f32_16x16x32_bf16 v[138:141], v[98:101], v[174:177], v[138:141]
	v_mfma_f32_16x16x32_bf16 v[118:121], v[82:85], v[182:185], v[118:121]
	v_mfma_f32_16x16x32_bf16 v[114:117], v[98:101], v[182:185], v[114:117]
	v_mfma_f32_16x16x32_bf16 v[86:89], v[82:85], v[190:193], v[86:89]
	v_mfma_f32_16x16x32_bf16 v[74:77], v[98:101], v[190:193], v[74:77]
	s_setprio 0
	s_setprio 1
	v_mfma_f32_16x16x32_bf16 v[154:157], v[106:109], v[150:153], v[154:157]
	v_mfma_f32_16x16x32_bf16 v[146:149], v[126:129], v[150:153], v[146:149]
	v_mfma_f32_16x16x32_bf16 v[130:133], v[106:109], v[166:169], v[130:133]
	v_mfma_f32_16x16x32_bf16 v[122:125], v[126:129], v[166:169], v[122:125]
	v_mfma_f32_16x16x32_bf16 v[102:105], v[106:109], v[178:181], v[102:105]
	v_mfma_f32_16x16x32_bf16 v[90:93], v[126:129], v[178:181], v[90:93]
	v_mfma_f32_16x16x32_bf16 v[70:73], v[106:109], v[186:189], v[70:73]
	v_mfma_f32_16x16x32_bf16 v[66:69], v[126:129], v[186:189], v[66:69]
	v_mfma_f32_16x16x32_bf16 v[154:157], v[110:113], v[158:161], v[154:157]
	v_mfma_f32_16x16x32_bf16 v[150:153], v[134:137], v[158:161], v[146:149]
	v_mfma_f32_16x16x32_bf16 v[130:133], v[110:113], v[174:177], v[130:133]
	v_mfma_f32_16x16x32_bf16 v[122:125], v[134:137], v[174:177], v[122:125]
	v_mfma_f32_16x16x32_bf16 v[102:105], v[110:113], v[182:185], v[102:105]
	v_mfma_f32_16x16x32_bf16 v[90:93], v[134:137], v[182:185], v[90:93]
	v_mfma_f32_16x16x32_bf16 v[70:73], v[110:113], v[190:193], v[70:73]
	v_mfma_f32_16x16x32_bf16 v[66:69], v[134:137], v[190:193], v[66:69]
	s_barrier
	s_setprio 0
	s_add_i32 s0, s4, s26
	v_lshl_add_u64 v[194:195], v[194:195], 0, s[80:81]
	s_mov_b32 m0, s0
	ds_read_b128 v[146:149], v239 offset:49152
	ds_read_b128 v[158:161], v239 offset:50176
	ds_read_b128 v[166:169], v239 offset:51200
	ds_read_b128 v[174:177], v239 offset:52224
	ds_read_b128 v[178:181], v239 offset:53248
	ds_read_b128 v[182:185], v239 offset:54272
	ds_read_b128 v[186:189], v239 offset:55296
	ds_read_b128 v[190:193], v239 offset:56320
	global_load_lds_dwordx4 v[194:195], off
	s_add_i32 m0, s0, 0x2000
	s_add_u32 s0, s20, 0x160080
	v_lshl_add_u64 v[194:195], v[196:197], 0, s[80:81]
	s_addc_u32 s1, s21, 0
	s_add_i32 s4, s5, s26
	global_load_lds_dwordx4 v[194:195], off
	s_mov_b32 m0, s4
	s_nop 0
	global_load_lds_dwordx4 v202, s[0:1]
	s_add_i32 m0, s4, 0x2000
	s_nop 0
	global_load_lds_dwordx4 v208, s[0:1]
	v_lshl_add_u64 v[194:195], v[198:199], 0, s[80:81]
	s_mov_b32 m0, s35
	s_nop 0
	global_load_lds_dwordx4 v[194:195], off
	v_lshl_add_u64 v[194:195], v[200:201], 0, s[80:81]
	s_mov_b32 m0, s36
	s_nop 0
	global_load_lds_dwordx4 v[194:195], off
	s_waitcnt vmcnt(8)
	s_waitcnt lgkmcnt(0)
	s_setprio 1
	s_barrier
	v_mfma_f32_16x16x32_bf16 v[62:65], v[78:81], v[146:149], v[62:65]
	v_mfma_f32_16x16x32_bf16 v[58:61], v[94:97], v[146:149], v[58:61]
	v_mfma_f32_16x16x32_bf16 v[46:49], v[78:81], v[166:169], v[46:49]
	v_mfma_f32_16x16x32_bf16 v[42:45], v[94:97], v[166:169], v[42:45]
	v_mfma_f32_16x16x32_bf16 v[30:33], v[78:81], v[178:181], v[30:33]
	v_mfma_f32_16x16x32_bf16 v[26:29], v[94:97], v[178:181], v[26:29]
	v_mfma_f32_16x16x32_bf16 v[14:17], v[78:81], v[186:189], v[14:17]
	v_mfma_f32_16x16x32_bf16 v[10:13], v[94:97], v[186:189], v[10:13]
	v_mfma_f32_16x16x32_bf16 v[62:65], v[82:85], v[158:161], v[62:65]
	v_mfma_f32_16x16x32_bf16 v[58:61], v[98:101], v[158:161], v[58:61]
	v_mfma_f32_16x16x32_bf16 v[46:49], v[82:85], v[174:177], v[46:49]
	v_mfma_f32_16x16x32_bf16 v[42:45], v[98:101], v[174:177], v[42:45]
	v_mfma_f32_16x16x32_bf16 v[30:33], v[82:85], v[182:185], v[30:33]
	v_mfma_f32_16x16x32_bf16 v[26:29], v[98:101], v[182:185], v[26:29]
	v_mfma_f32_16x16x32_bf16 v[14:17], v[82:85], v[190:193], v[14:17]
	v_mfma_f32_16x16x32_bf16 v[10:13], v[98:101], v[190:193], v[10:13]
	s_setprio 0
	s_setprio 1
	v_mfma_f32_16x16x32_bf16 v[54:57], v[106:109], v[146:149], v[54:57]
	v_mfma_f32_16x16x32_bf16 v[50:53], v[126:129], v[146:149], v[50:53]
	v_mfma_f32_16x16x32_bf16 v[38:41], v[106:109], v[166:169], v[38:41]
	v_mfma_f32_16x16x32_bf16 v[34:37], v[126:129], v[166:169], v[34:37]
	v_mfma_f32_16x16x32_bf16 v[22:25], v[106:109], v[178:181], v[22:25]
	v_mfma_f32_16x16x32_bf16 v[18:21], v[126:129], v[178:181], v[18:21]
	v_mfma_f32_16x16x32_bf16 v[6:9], v[106:109], v[186:189], v[6:9]
	v_mfma_f32_16x16x32_bf16 v[2:5], v[126:129], v[186:189], v[2:5]
	v_mfma_f32_16x16x32_bf16 v[54:57], v[110:113], v[158:161], v[54:57]
	v_mfma_f32_16x16x32_bf16 v[50:53], v[134:137], v[158:161], v[50:53]
	v_mfma_f32_16x16x32_bf16 v[38:41], v[110:113], v[174:177], v[38:41]
	v_mfma_f32_16x16x32_bf16 v[34:37], v[134:137], v[174:177], v[34:37]
	v_mfma_f32_16x16x32_bf16 v[22:25], v[110:113], v[182:185], v[22:25]
	v_mfma_f32_16x16x32_bf16 v[18:21], v[134:137], v[182:185], v[18:21]
	v_mfma_f32_16x16x32_bf16 v[6:9], v[110:113], v[190:193], v[6:9]
	v_mfma_f32_16x16x32_bf16 v[2:5], v[134:137], v[190:193], v[2:5]
	s_barrier
	s_setprio 0
	s_add_i32 s59, s59, 2
	s_add_u32 s49, s49, 0x100
	s_addc_u32 s58, s58, 0
	s_cmpk_gt_u32 s59, 0x55
	s_mov_b64 s[4:5], s[18:19]
	s_cbranch_scc0 .LBB0_1718
	s_and_b64 vcc, exec, s[14:15]
	s_cbranch_vccz .LBB0_1721
	s_barrier

.LBB0_1739:
	s_add_u32 s16, s14, 0x100
	s_addc_u32 s17, s15, 0
	s_add_i32 s0, 0, 0x10000
	s_cmp_eq_u32 s49, 4
	s_cselect_b32 s21, s9, s17
	s_cselect_b32 s20, s8, s16
	s_cselect_b32 s19, s11, s41
	s_cselect_b32 s18, s10, s40
	s_add_i32 s33, 0, 0x14000
	v_add_u32_e32 v152, s0, v136
	v_add_u32_e32 v168, s33, v136
	ds_read_b128 v[140:143], v152
	ds_read_b128 v[144:147], v152 offset:1024
	ds_read_b128 v[148:151], v152 offset:2048
	ds_read_b128 v[152:155], v152 offset:3072
	ds_read_b128 v[156:159], v168
	ds_read_b128 v[160:163], v168 offset:1024
	ds_read_b128 v[164:167], v168 offset:2048
	ds_read_b128 v[168:171], v168 offset:3072
	s_add_i32 m0, s23, 0xc000
	ds_read_b128 v[172:175], v139
	ds_read_b128 v[176:179], v139 offset:1024
	ds_read_b128 v[180:183], v139 offset:2048
	ds_read_b128 v[184:187], v139 offset:3072
	ds_read_b128 v[188:191], v139 offset:4096
	ds_read_b128 v[192:195], v139 offset:5120
	ds_read_b128 v[196:199], v139 offset:6144
	ds_read_b128 v[208:211], v139 offset:7168
	global_load_lds_dwordx4 v132, s[14:15]
	s_add_i32 m0, s23, 0xe000
	s_nop 0
	global_load_lds_dwordx4 v134, s[14:15]
	s_waitcnt vmcnt(8)
	s_waitcnt lgkmcnt(0)
	s_setprio 1
	s_barrier
	v_mfma_f32_16x16x32_bf16 v[126:129], v[140:143], v[172:175], v[126:129]
	v_mfma_f32_16x16x32_bf16 v[122:125], v[148:151], v[172:175], v[122:125]
	v_mfma_f32_16x16x32_bf16 v[118:121], v[140:143], v[180:183], v[118:121]
	v_mfma_f32_16x16x32_bf16 v[114:117], v[148:151], v[180:183], v[114:117]
	v_mfma_f32_16x16x32_bf16 v[106:109], v[140:143], v[188:191], v[106:109]
	v_mfma_f32_16x16x32_bf16 v[98:101], v[148:151], v[188:191], v[98:101]
	v_mfma_f32_16x16x32_bf16 v[90:93], v[140:143], v[196:199], v[90:93]
	v_mfma_f32_16x16x32_bf16 v[82:85], v[148:151], v[196:199], v[82:85]
	v_mfma_f32_16x16x32_bf16 v[126:129], v[144:147], v[176:179], v[126:129]
	v_mfma_f32_16x16x32_bf16 v[122:125], v[152:155], v[176:179], v[122:125]
	v_mfma_f32_16x16x32_bf16 v[118:121], v[144:147], v[184:187], v[118:121]
	v_mfma_f32_16x16x32_bf16 v[114:117], v[152:155], v[184:187], v[114:117]
	v_mfma_f32_16x16x32_bf16 v[106:109], v[144:147], v[192:195], v[106:109]
	v_mfma_f32_16x16x32_bf16 v[98:101], v[152:155], v[192:195], v[98:101]
	v_mfma_f32_16x16x32_bf16 v[90:93], v[144:147], v[208:211], v[90:93]
	v_mfma_f32_16x16x32_bf16 v[82:85], v[152:155], v[208:211], v[82:85]
	s_setprio 0
	s_setprio 1
	v_mfma_f32_16x16x32_bf16 v[110:113], v[156:159], v[172:175], v[110:113]
	v_mfma_f32_16x16x32_bf16 v[102:105], v[164:167], v[172:175], v[102:105]
	v_mfma_f32_16x16x32_bf16 v[94:97], v[156:159], v[180:183], v[94:97]
	v_mfma_f32_16x16x32_bf16 v[86:89], v[164:167], v[180:183], v[86:89]
	v_mfma_f32_16x16x32_bf16 v[78:81], v[156:159], v[188:191], v[78:81]
	v_mfma_f32_16x16x32_bf16 v[74:77], v[164:167], v[188:191], v[74:77]
	v_mfma_f32_16x16x32_bf16 v[70:73], v[156:159], v[196:199], v[70:73]
	v_mfma_f32_16x16x32_bf16 v[66:69], v[164:167], v[196:199], v[66:69]
	v_mfma_f32_16x16x32_bf16 v[110:113], v[160:163], v[176:179], v[110:113]
	v_mfma_f32_16x16x32_bf16 v[102:105], v[168:171], v[176:179], v[102:105]
	v_mfma_f32_16x16x32_bf16 v[94:97], v[160:163], v[184:187], v[94:97]
	v_mfma_f32_16x16x32_bf16 v[86:89], v[168:171], v[184:187], v[86:89]
	v_mfma_f32_16x16x32_bf16 v[78:81], v[160:163], v[192:195], v[78:81]
	v_mfma_f32_16x16x32_bf16 v[74:77], v[168:171], v[192:195], v[74:77]
	v_mfma_f32_16x16x32_bf16 v[70:73], v[160:163], v[208:211], v[70:73]
	v_mfma_f32_16x16x32_bf16 v[66:69], v[168:171], v[208:211], v[66:69]
	s_barrier
	s_setprio 0
	s_add_i32 s0, s0, s22
	v_lshl_add_u64 v[200:201], s[18:19], 0, v[202:203]
	s_mov_b32 m0, s0
	ds_read_b128 v[172:175], v139 offset:16384
	ds_read_b128 v[176:179], v139 offset:17408
	ds_read_b128 v[180:183], v139 offset:18432
	ds_read_b128 v[184:187], v139 offset:19456
	ds_read_b128 v[188:191], v139 offset:20480
	ds_read_b128 v[192:195], v139 offset:21504
	ds_read_b128 v[196:199], v139 offset:22528
	ds_read_b128 v[208:211], v139 offset:23552
	global_load_lds_dwordx4 v[200:201], off
	s_add_i32 m0, s0, 0x2000
	s_add_u32 s0, s18, 0x160000
	v_lshl_add_u64 v[204:205], s[18:19], 0, v[130:131]
	s_addc_u32 s1, s19, 0
	s_add_i32 s14, s33, s22
	global_load_lds_dwordx4 v[204:205], off
	s_mov_b32 m0, s14
	v_lshl_add_u64 v[212:213], s[20:21], 0, v[130:131]
	global_load_lds_dwordx4 v202, s[0:1]
	s_add_i32 m0, s14, 0x2000
	s_nop 0
	global_load_lds_dwordx4 v130, s[0:1]
	v_lshl_add_u64 v[206:207], s[20:21], 0, v[202:203]
	s_mov_b32 m0, s23
	s_nop 0
	global_load_lds_dwordx4 v[206:207], off
	s_mov_b32 m0, s26
	s_nop 0
	global_load_lds_dwordx4 v[212:213], off
	s_waitcnt vmcnt(8)
	s_waitcnt lgkmcnt(0)
	s_setprio 1
	s_barrier
	v_mfma_f32_16x16x32_bf16 v[62:65], v[140:143], v[172:175], v[62:65]
	v_mfma_f32_16x16x32_bf16 v[58:61], v[148:151], v[172:175], v[58:61]
	v_mfma_f32_16x16x32_bf16 v[54:57], v[140:143], v[180:183], v[54:57]
	v_mfma_f32_16x16x32_bf16 v[50:53], v[148:151], v[180:183], v[50:53]
	v_mfma_f32_16x16x32_bf16 v[38:41], v[140:143], v[188:191], v[38:41]
	v_mfma_f32_16x16x32_bf16 v[34:37], v[148:151], v[188:191], v[34:37]
	v_mfma_f32_16x16x32_bf16 v[22:25], v[140:143], v[196:199], v[22:25]
	v_mfma_f32_16x16x32_bf16 v[18:21], v[148:151], v[196:199], v[18:21]
	v_mfma_f32_16x16x32_bf16 v[62:65], v[144:147], v[176:179], v[62:65]
	v_mfma_f32_16x16x32_bf16 v[58:61], v[152:155], v[176:179], v[58:61]
	v_mfma_f32_16x16x32_bf16 v[54:57], v[144:147], v[184:187], v[54:57]
	v_mfma_f32_16x16x32_bf16 v[50:53], v[152:155], v[184:187], v[50:53]
	v_mfma_f32_16x16x32_bf16 v[38:41], v[144:147], v[192:195], v[38:41]
	v_mfma_f32_16x16x32_bf16 v[34:37], v[152:155], v[192:195], v[34:37]
	v_mfma_f32_16x16x32_bf16 v[22:25], v[144:147], v[208:211], v[22:25]
	v_mfma_f32_16x16x32_bf16 v[18:21], v[152:155], v[208:211], v[18:21]
	s_setprio 0
	s_setprio 1
	v_mfma_f32_16x16x32_bf16 v[46:49], v[156:159], v[172:175], v[46:49]
	v_mfma_f32_16x16x32_bf16 v[42:45], v[164:167], v[172:175], v[42:45]
	v_mfma_f32_16x16x32_bf16 v[30:33], v[156:159], v[180:183], v[30:33]
	v_mfma_f32_16x16x32_bf16 v[26:29], v[164:167], v[180:183], v[26:29]
	v_mfma_f32_16x16x32_bf16 v[14:17], v[156:159], v[188:191], v[14:17]
	v_mfma_f32_16x16x32_bf16 v[10:13], v[164:167], v[188:191], v[10:13]
	v_mfma_f32_16x16x32_bf16 v[6:9], v[156:159], v[196:199], v[6:9]
	v_mfma_f32_16x16x32_bf16 v[2:5], v[164:167], v[196:199], v[2:5]
	v_mfma_f32_16x16x32_bf16 v[46:49], v[160:163], v[176:179], v[46:49]
	v_mfma_f32_16x16x32_bf16 v[42:45], v[168:171], v[176:179], v[42:45]
	v_mfma_f32_16x16x32_bf16 v[30:33], v[160:163], v[184:187], v[30:33]
	v_mfma_f32_16x16x32_bf16 v[26:29], v[168:171], v[184:187], v[26:29]
	v_mfma_f32_16x16x32_bf16 v[14:17], v[160:163], v[192:195], v[14:17]
	v_mfma_f32_16x16x32_bf16 v[10:13], v[168:171], v[192:195], v[10:13]
	v_mfma_f32_16x16x32_bf16 v[6:9], v[160:163], v[208:211], v[6:9]
	v_mfma_f32_16x16x32_bf16 v[2:5], v[168:171], v[208:211], v[2:5]
	s_barrier
	s_setprio 0
	s_add_i32 s14, 0, 0x18000
	s_add_i32 s15, 0, 0x1c000
	v_add_u32_e32 v152, s14, v136
	v_add_u32_e32 v168, s15, v136
	ds_read_b128 v[140:143], v152
	ds_read_b128 v[144:147], v152 offset:1024
	ds_read_b128 v[148:151], v152 offset:2048
	ds_read_b128 v[152:155], v152 offset:3072
	ds_read_b128 v[156:159], v168
	ds_read_b128 v[160:163], v168 offset:1024
	ds_read_b128 v[164:167], v168 offset:2048
	ds_read_b128 v[168:171], v168 offset:3072
	s_add_u32 s0, s20, 0x160000
	s_addc_u32 s1, s21, 0
	s_mov_b32 m0, s27
	ds_read_b128 v[172:175], v139 offset:32768
	ds_read_b128 v[176:179], v139 offset:33792
	ds_read_b128 v[180:183], v139 offset:34816
	ds_read_b128 v[184:187], v139 offset:35840
	ds_read_b128 v[188:191], v139 offset:36864
	ds_read_b128 v[192:195], v139 offset:37888
	ds_read_b128 v[196:199], v139 offset:38912
	ds_read_b128 v[208:211], v139 offset:39936
	global_load_lds_dwordx4 v202, s[0:1]
	s_mov_b32 m0, s28
	s_nop 0
	global_load_lds_dwordx4 v130, s[0:1]
	s_waitcnt vmcnt(8)
	s_waitcnt lgkmcnt(0)
	s_setprio 1
	s_barrier
	v_mfma_f32_16x16x32_bf16 v[126:129], v[140:143], v[172:175], v[126:129]
	v_mfma_f32_16x16x32_bf16 v[122:125], v[148:151], v[172:175], v[122:125]
	v_mfma_f32_16x16x32_bf16 v[118:121], v[140:143], v[180:183], v[118:121]
	v_mfma_f32_16x16x32_bf16 v[114:117], v[148:151], v[180:183], v[114:117]
	v_mfma_f32_16x16x32_bf16 v[106:109], v[140:143], v[188:191], v[106:109]
	v_mfma_f32_16x16x32_bf16 v[98:101], v[148:151], v[188:191], v[98:101]
	v_mfma_f32_16x16x32_bf16 v[90:93], v[140:143], v[196:199], v[90:93]
	v_mfma_f32_16x16x32_bf16 v[82:85], v[148:151], v[196:199], v[82:85]
	v_mfma_f32_16x16x32_bf16 v[126:129], v[144:147], v[176:179], v[126:129]
	v_mfma_f32_16x16x32_bf16 v[122:125], v[152:155], v[176:179], v[122:125]
	v_mfma_f32_16x16x32_bf16 v[118:121], v[144:147], v[184:187], v[118:121]
	v_mfma_f32_16x16x32_bf16 v[114:117], v[152:155], v[184:187], v[114:117]
	v_mfma_f32_16x16x32_bf16 v[106:109], v[144:147], v[192:195], v[106:109]
	v_mfma_f32_16x16x32_bf16 v[98:101], v[152:155], v[192:195], v[98:101]
	v_mfma_f32_16x16x32_bf16 v[90:93], v[144:147], v[208:211], v[90:93]
	v_mfma_f32_16x16x32_bf16 v[82:85], v[152:155], v[208:211], v[82:85]
	s_setprio 0
	s_setprio 1
	v_mfma_f32_16x16x32_bf16 v[110:113], v[156:159], v[172:175], v[110:113]
	v_mfma_f32_16x16x32_bf16 v[102:105], v[164:167], v[172:175], v[102:105]
	v_mfma_f32_16x16x32_bf16 v[94:97], v[156:159], v[180:183], v[94:97]
	v_mfma_f32_16x16x32_bf16 v[86:89], v[164:167], v[180:183], v[86:89]
	v_mfma_f32_16x16x32_bf16 v[78:81], v[156:159], v[188:191], v[78:81]
	v_mfma_f32_16x16x32_bf16 v[74:77], v[164:167], v[188:191], v[74:77]
	v_mfma_f32_16x16x32_bf16 v[70:73], v[156:159], v[196:199], v[70:73]
	v_mfma_f32_16x16x32_bf16 v[66:69], v[164:167], v[196:199], v[66:69]
	v_mfma_f32_16x16x32_bf16 v[110:113], v[160:163], v[176:179], v[110:113]
	v_mfma_f32_16x16x32_bf16 v[102:105], v[168:171], v[176:179], v[102:105]
	v_mfma_f32_16x16x32_bf16 v[94:97], v[160:163], v[184:187], v[94:97]
	v_mfma_f32_16x16x32_bf16 v[86:89], v[168:171], v[184:187], v[86:89]
	v_mfma_f32_16x16x32_bf16 v[78:81], v[160:163], v[192:195], v[78:81]
	v_mfma_f32_16x16x32_bf16 v[74:77], v[168:171], v[192:195], v[74:77]
	v_mfma_f32_16x16x32_bf16 v[70:73], v[160:163], v[208:211], v[70:73]
	v_mfma_f32_16x16x32_bf16 v[66:69], v[168:171], v[208:211], v[66:69]
	s_barrier
	s_setprio 0
	s_add_i32 s0, s14, s22
	v_lshl_add_u64 v[200:201], v[200:201], 0, s[80:81]
	s_mov_b32 m0, s0
	ds_read_b128 v[172:175], v139 offset:49152
	ds_read_b128 v[176:179], v139 offset:50176
	ds_read_b128 v[180:183], v139 offset:51200
	ds_read_b128 v[184:187], v139 offset:52224
	ds_read_b128 v[188:191], v139 offset:53248
	ds_read_b128 v[192:195], v139 offset:54272
	ds_read_b128 v[196:199], v139 offset:55296
	ds_read_b128 v[208:211], v139 offset:56320
	global_load_lds_dwordx4 v[200:201], off
	s_add_i32 m0, s0, 0x2000
	s_add_u32 s0, s18, 0x160080
	v_lshl_add_u64 v[200:201], v[204:205], 0, s[80:81]
	s_addc_u32 s1, s19, 0
	s_add_i32 s14, s15, s22
	global_load_lds_dwordx4 v[200:201], off
	s_mov_b32 m0, s14
	s_nop 0
	global_load_lds_dwordx4 v202, s[0:1]
	s_add_i32 m0, s14, 0x2000
	s_nop 0
	global_load_lds_dwordx4 v130, s[0:1]
	v_lshl_add_u64 v[200:201], v[206:207], 0, s[80:81]
	s_mov_b32 m0, s29
	s_nop 0
	global_load_lds_dwordx4 v[200:201], off
	v_lshl_add_u64 v[200:201], v[212:213], 0, s[80:81]
	s_mov_b32 m0, s30
	s_nop 0
	global_load_lds_dwordx4 v[200:201], off
	s_waitcnt vmcnt(8)
	s_waitcnt lgkmcnt(0)
	s_setprio 1
	s_barrier
	v_mfma_f32_16x16x32_bf16 v[62:65], v[140:143], v[172:175], v[62:65]
	v_mfma_f32_16x16x32_bf16 v[58:61], v[148:151], v[172:175], v[58:61]
	v_mfma_f32_16x16x32_bf16 v[54:57], v[140:143], v[180:183], v[54:57]
	v_mfma_f32_16x16x32_bf16 v[50:53], v[148:151], v[180:183], v[50:53]
	v_mfma_f32_16x16x32_bf16 v[38:41], v[140:143], v[188:191], v[38:41]
	v_mfma_f32_16x16x32_bf16 v[34:37], v[148:151], v[188:191], v[34:37]
	v_mfma_f32_16x16x32_bf16 v[22:25], v[140:143], v[196:199], v[22:25]
	v_mfma_f32_16x16x32_bf16 v[18:21], v[148:151], v[196:199], v[18:21]
	v_mfma_f32_16x16x32_bf16 v[62:65], v[144:147], v[176:179], v[62:65]
	v_mfma_f32_16x16x32_bf16 v[58:61], v[152:155], v[176:179], v[58:61]
	v_mfma_f32_16x16x32_bf16 v[54:57], v[144:147], v[184:187], v[54:57]
	v_mfma_f32_16x16x32_bf16 v[50:53], v[152:155], v[184:187], v[50:53]
	v_mfma_f32_16x16x32_bf16 v[38:41], v[144:147], v[192:195], v[38:41]
	v_mfma_f32_16x16x32_bf16 v[34:37], v[152:155], v[192:195], v[34:37]
	v_mfma_f32_16x16x32_bf16 v[22:25], v[144:147], v[208:211], v[22:25]
	v_mfma_f32_16x16x32_bf16 v[18:21], v[152:155], v[208:211], v[18:21]
	s_setprio 0
	s_setprio 1
	v_mfma_f32_16x16x32_bf16 v[46:49], v[156:159], v[172:175], v[46:49]
	v_mfma_f32_16x16x32_bf16 v[42:45], v[164:167], v[172:175], v[42:45]
	v_mfma_f32_16x16x32_bf16 v[30:33], v[156:159], v[180:183], v[30:33]
	v_mfma_f32_16x16x32_bf16 v[26:29], v[164:167], v[180:183], v[26:29]
	v_mfma_f32_16x16x32_bf16 v[14:17], v[156:159], v[188:191], v[14:17]
	v_mfma_f32_16x16x32_bf16 v[10:13], v[164:167], v[188:191], v[10:13]
	v_mfma_f32_16x16x32_bf16 v[6:9], v[156:159], v[196:199], v[6:9]
	v_mfma_f32_16x16x32_bf16 v[2:5], v[164:167], v[196:199], v[2:5]
	v_mfma_f32_16x16x32_bf16 v[46:49], v[160:163], v[176:179], v[46:49]
	v_mfma_f32_16x16x32_bf16 v[42:45], v[168:171], v[176:179], v[42:45]
	v_mfma_f32_16x16x32_bf16 v[30:33], v[160:163], v[184:187], v[30:33]
	v_mfma_f32_16x16x32_bf16 v[26:29], v[168:171], v[184:187], v[26:29]
	v_mfma_f32_16x16x32_bf16 v[14:17], v[160:163], v[192:195], v[14:17]
	v_mfma_f32_16x16x32_bf16 v[10:13], v[168:171], v[192:195], v[10:13]
	v_mfma_f32_16x16x32_bf16 v[6:9], v[160:163], v[208:211], v[6:9]
	v_mfma_f32_16x16x32_bf16 v[2:5], v[168:171], v[208:211], v[2:5]
	s_barrier
	s_setprio 0
	s_add_i32 s49, s49, 2
	s_add_u32 s40, s40, 0x100
	s_addc_u32 s41, s41, 0
	s_cmp_gt_u32 s49, 5
	s_mov_b64 s[14:15], s[16:17]
	s_cbranch_scc0 .LBB0_1739
	s_and_b64 vcc, exec, s[6:7]
	s_cbranch_vccz .LBB0_1742
	s_barrier
